# v20 + non-temporal hint on single-use streaming loads (P0: x rows and f32 weights; P4: branch outputs and LSE)
# speedup vs baseline: 1.0313x; 1.0313x over previous
; DI void transpose_item(const float* W, int ldn, int sc, const float* gain, bf16* WT, int K, int drow, int k0, LAS float* scr, int lane) {
;     ...
; #pragma unroll
;     for (int i = 0; i < 32; ++i) { const int kk = 2 * i + (lane >> 5); tv[i] = 0.f;
;         if (sc >= 0) { tv[i] = W[(size_t)(k0 + kk) * ldn + sc + (lane & 31)]; if (gain) tv[i] *= gain[k0 + kk]; } }
; __global__ void __launch_bounds__(512, 2) fwd_megakernel(Params P) {
;     ...
;             if (r < I0) { const int g = r % 72, kb = r / 72; int sc;
;                 if (g < 64) sc = 32 * g; else if (g == 64) sc = 2048; else if (g == 65) sc = 2080; else if (g == 66) sc = 2176; else if (g == 67) sc = -1;
;                 else if (g == 68) sc = 2112; else if (g == 69) sc = 2144; else if (g == 70) sc = 2208; else sc = -1;
;                 transpose_item(P.w_in, 2240, sc, nullptr, Wt_in, 1024, 32 * g, 64 * kb, scr, lane); continue; } r -= I0;
;             if (r < I1) { const int g = r % 32, kb = r / 32; transpose_item(P.w_mkv, 1024, 32 * g, nullptr, Wt_mkv, 1024, 32 * g, 64 * kb, scr, lane); continue; } r -= I1;
;             if (r < I2) { const int g = r % 24, kb = r / 24; transpose_item(P.w_q_up, 768, 32 * g, P.q_norm, Wt_q, 384, 32 * g, 64 * kb, scr, lane); continue; } r -= I2;
;             if (r < I3) { const int g = r % 32, kb = r / 32; transpose_item(P.w_kv_up, 1024, 32 * g, P.kv_norm, Wt_kv, 256, 32 * g, 64 * kb, scr, lane); continue; } r -= I3;
;             if (r < I4) { const int g = r % 32, kb = r / 32; transpose_item(P.w_out, 1024, 32 * g, nullptr, Wt_out, 1024, 32 * g, 64 * kb, scr, lane); continue; } r -= I4;
;             if (r < I5) { const int g = r % 16, kb = r / 16; transpose_item(P.w_mq, 512, 32 * g, P.norm_mem_q, Wt_mq, 1024, 32 * g, 64 * kb, scr, lane); continue; } r -= I5;
;             if (r < I6) { const int g = r % 32, kb = r / 32; transpose_item(P.w_mo, 1024, 32 * g, nullptr, Wt_mo, 512, 32 * g, 64 * kb, scr, lane); continue; } r -= I6;
;             if (r < I7) { const int g = r % 176, kb = r / 176; const int pn = g >> 3, bj = (g >> 2) & 1, q = g & 3;
;                 transpose_item(bj ? P.w_up : P.w_gate, DFF, 128 * pn + 32 * q, P.norm_ffn, Wt_gu, 1024, 32 * g, 64 * kb, scr, lane); continue; } r -= I7;
;             { const int g = r % 32, kb = r / 32; transpose_item(P.w_down, 1024, 32 * g, nullptr, Wt_dn, DFF, 32 * g, 64 * kb, scr, lane); }
.LBB0_23:
	s_cmpk_gt_i32 s64, 0x47f
	s_mov_b64 s[2:3], -1
	s_cbranch_scc0 .LBB0_309
	s_cmpk_gt_u32 s64, 0x67f
	s_cbranch_scc0 .LBB0_306
	s_cmpk_gt_u32 s64, 0x70f
	s_cbranch_scc0 .LBB0_239
	s_cmpk_gt_u32 s64, 0x78f
	s_cbranch_scc0 .LBB0_172
	s_cmpk_gt_u32 s64, 0x98f
	s_cbranch_scc0 .LBB0_169
	s_cmpk_gt_u32 s64, 0xa8f
	s_cbranch_scc0 .LBB0_102
	s_cmpk_gt_u32 s64, 0xb8f
	s_cbranch_scc0 .LBB0_99
	s_cmpk_gt_u32 s64, 0x168f
	s_cbranch_scc0 .LBB0_32
	s_add_i32 s1, s45, 0xffffd2e0
	s_add_i32 s0, s5, 0xfffd2e00
	s_and_b32 s1, s1, 0x7fffffc0
	s_and_b32 s0, s0, 0x3e0
	v_or_b32_e32 v0, s1, v46
	s_lshl_b32 s76, s0, 2
	v_or_b32_e32 v60, 2, v0
	v_mov_b32_e32 v61, v1
	v_or_b32_e32 v62, 4, v0
	v_mov_b32_e32 v63, v1
	v_or_b32_e32 v64, 6, v0
	v_mov_b32_e32 v65, v1
	v_or_b32_e32 v66, 8, v0
	v_mov_b32_e32 v67, v1
	v_or_b32_e32 v68, 10, v0
	v_mov_b32_e32 v69, v1
	v_or_b32_e32 v70, 12, v0
	v_mov_b32_e32 v71, v1
	v_lshl_add_u64 v[42:43], v[2:3], 0, s[76:77]
	v_lshlrev_b64 v[44:45], 12, v[0:1]
	v_lshlrev_b64 v[60:61], 12, v[60:61]
	v_lshlrev_b64 v[62:63], 12, v[62:63]
	v_lshlrev_b64 v[64:65], 12, v[64:65]
	v_lshlrev_b64 v[66:67], 12, v[66:67]
	v_lshlrev_b64 v[68:69], 12, v[68:69]
	v_lshlrev_b64 v[70:71], 12, v[70:71]
	v_or_b32_e32 v72, 14, v0
	v_mov_b32_e32 v73, v1
	v_lshl_add_u64 v[44:45], v[42:43], 0, v[44:45]
	v_lshl_add_u64 v[60:61], v[42:43], 0, v[60:61]
	v_lshl_add_u64 v[62:63], v[42:43], 0, v[62:63]
	v_lshl_add_u64 v[64:65], v[42:43], 0, v[64:65]
	v_lshl_add_u64 v[66:67], v[42:43], 0, v[66:67]
	v_lshl_add_u64 v[68:69], v[42:43], 0, v[68:69]
	v_lshl_add_u64 v[70:71], v[42:43], 0, v[70:71]
	v_lshlrev_b64 v[72:73], 12, v[72:73]
	v_lshl_add_u64 v[72:73], v[42:43], 0, v[72:73]
	global_load_dword v41, v[44:45], off nt
	global_load_dword v74, v[60:61], off nt
	global_load_dword v75, v[62:63], off nt
	global_load_dword v76, v[64:65], off nt
	global_load_dword v77, v[66:67], off nt
	global_load_dword v78, v[68:69], off nt
	global_load_dword v79, v[70:71], off nt
	global_load_dword v80, v[72:73], off nt
	v_or_b32_e32 v44, 16, v0
	v_mov_b32_e32 v45, v1
	v_or_b32_e32 v60, 18, v0
	v_mov_b32_e32 v61, v1
	v_or_b32_e32 v62, 20, v0
	v_mov_b32_e32 v63, v1
	v_or_b32_e32 v64, 22, v0
	v_mov_b32_e32 v65, v1
	v_or_b32_e32 v66, 24, v0
	v_mov_b32_e32 v67, v1
	v_or_b32_e32 v68, 26, v0
	v_mov_b32_e32 v69, v1
	v_or_b32_e32 v70, 28, v0
	v_mov_b32_e32 v71, v1
	v_lshlrev_b64 v[44:45], 12, v[44:45]
	v_lshlrev_b64 v[60:61], 12, v[60:61]
	v_lshlrev_b64 v[62:63], 12, v[62:63]
	v_lshlrev_b64 v[64:65], 12, v[64:65]
	v_lshlrev_b64 v[66:67], 12, v[66:67]
	v_lshlrev_b64 v[68:69], 12, v[68:69]
	v_lshlrev_b64 v[70:71], 12, v[70:71]
	v_or_b32_e32 v72, 30, v0
	v_mov_b32_e32 v73, v1
	v_lshl_add_u64 v[44:45], v[42:43], 0, v[44:45]
	v_lshl_add_u64 v[60:61], v[42:43], 0, v[60:61]
	v_lshl_add_u64 v[62:63], v[42:43], 0, v[62:63]
	v_lshl_add_u64 v[64:65], v[42:43], 0, v[64:65]
	v_lshl_add_u64 v[66:67], v[42:43], 0, v[66:67]
	v_lshl_add_u64 v[68:69], v[42:43], 0, v[68:69]
	v_lshl_add_u64 v[70:71], v[42:43], 0, v[70:71]
	v_lshlrev_b64 v[72:73], 12, v[72:73]
	v_lshl_add_u64 v[72:73], v[42:43], 0, v[72:73]
	global_load_dword v81, v[44:45], off nt
	global_load_dword v82, v[60:61], off nt
	global_load_dword v83, v[62:63], off nt
	global_load_dword v84, v[64:65], off nt
	global_load_dword v85, v[66:67], off nt
	global_load_dword v86, v[68:69], off nt
	global_load_dword v87, v[70:71], off nt
	global_load_dword v88, v[72:73], off nt
	v_or_b32_e32 v44, 32, v0
	v_mov_b32_e32 v45, v1
	v_or_b32_e32 v60, 34, v0
	v_mov_b32_e32 v61, v1
	v_or_b32_e32 v62, 36, v0
	v_mov_b32_e32 v63, v1
	v_or_b32_e32 v64, 38, v0
	v_mov_b32_e32 v65, v1
	v_or_b32_e32 v66, 40, v0
	v_mov_b32_e32 v67, v1
	v_or_b32_e32 v68, 42, v0
	v_mov_b32_e32 v69, v1
	v_or_b32_e32 v70, 44, v0
	v_mov_b32_e32 v71, v1
	v_lshlrev_b64 v[44:45], 12, v[44:45]
	v_lshlrev_b64 v[60:61], 12, v[60:61]
	v_lshlrev_b64 v[62:63], 12, v[62:63]
	v_lshlrev_b64 v[64:65], 12, v[64:65]
	v_lshlrev_b64 v[66:67], 12, v[66:67]
	v_lshlrev_b64 v[68:69], 12, v[68:69]
	v_lshlrev_b64 v[70:71], 12, v[70:71]
	v_or_b32_e32 v72, 46, v0
	v_mov_b32_e32 v73, v1
	v_lshl_add_u64 v[44:45], v[42:43], 0, v[44:45]
	v_lshl_add_u64 v[60:61], v[42:43], 0, v[60:61]
	v_lshl_add_u64 v[62:63], v[42:43], 0, v[62:63]
	v_lshl_add_u64 v[64:65], v[42:43], 0, v[64:65]
	v_lshl_add_u64 v[66:67], v[42:43], 0, v[66:67]
	v_lshl_add_u64 v[68:69], v[42:43], 0, v[68:69]
	v_lshl_add_u64 v[70:71], v[42:43], 0, v[70:71]
	v_lshlrev_b64 v[72:73], 12, v[72:73]
	v_lshl_add_u64 v[72:73], v[42:43], 0, v[72:73]
	global_load_dword v89, v[44:45], off nt
	global_load_dword v90, v[60:61], off nt
	global_load_dword v91, v[62:63], off nt
	global_load_dword v92, v[64:65], off nt
	global_load_dword v93, v[66:67], off nt
	global_load_dword v94, v[68:69], off nt
	global_load_dword v95, v[70:71], off nt
	global_load_dword v96, v[72:73], off nt
	v_or_b32_e32 v44, 48, v0
	v_mov_b32_e32 v45, v1
	v_or_b32_e32 v60, 50, v0
	v_mov_b32_e32 v61, v1
	v_or_b32_e32 v62, 52, v0
	v_mov_b32_e32 v63, v1
	v_or_b32_e32 v64, 54, v0
	v_mov_b32_e32 v65, v1
	v_or_b32_e32 v66, 56, v0
	v_mov_b32_e32 v67, v1
	v_or_b32_e32 v68, 58, v0
	v_mov_b32_e32 v69, v1
	v_or_b32_e32 v70, 60, v0
	v_mov_b32_e32 v71, v1
	v_or_b32_e32 v0, 62, v0
	v_lshlrev_b64 v[44:45], 12, v[44:45]
	v_lshlrev_b64 v[60:61], 12, v[60:61]
	v_lshlrev_b64 v[62:63], 12, v[62:63]
	v_lshlrev_b64 v[64:65], 12, v[64:65]
	v_lshlrev_b64 v[66:67], 12, v[66:67]
	v_lshlrev_b64 v[68:69], 12, v[68:69]
	v_lshlrev_b64 v[70:71], 12, v[70:71]
	v_lshlrev_b64 v[72:73], 12, v[0:1]
	v_lshl_add_u64 v[44:45], v[42:43], 0, v[44:45]
	v_lshl_add_u64 v[60:61], v[42:43], 0, v[60:61]
	v_lshl_add_u64 v[62:63], v[42:43], 0, v[62:63]
	v_lshl_add_u64 v[64:65], v[42:43], 0, v[64:65]
	v_lshl_add_u64 v[66:67], v[42:43], 0, v[66:67]
	v_lshl_add_u64 v[68:69], v[42:43], 0, v[68:69]
	v_lshl_add_u64 v[70:71], v[42:43], 0, v[70:71]
	v_lshl_add_u64 v[42:43], v[42:43], 0, v[72:73]
	global_load_dword v0, v[44:45], off nt
	s_nop 0
	global_load_dword v44, v[60:61], off nt
	global_load_dword v45, v[62:63], off nt
	s_nop 0
	global_load_dword v60, v[64:65], off nt
	global_load_dword v61, v[66:67], off nt
	global_load_dword v62, v[68:69], off nt
	global_load_dword v63, v[70:71], off nt
	s_nop 0
	global_load_dword v42, v[42:43], off nt
	s_waitcnt vmcnt(30)
; #define LAS __attribute__((address_space(3)))
; DI unsigned pk2(float lo, float hi) { return pg8::cvt_pk_bf16(lo, hi); }
; DI void transpose_item(const float* W, int ldn, int sc, const float* gain, bf16* WT, int K, int drow, int k0, LAS float* scr, int lane) {
;     ...
;     for (int i = 0; i < 32; ++i) { const int kk = 2 * i + (lane >> 5); tv[i] = 0.f;
;         if (sc >= 0) { tv[i] = W[(size_t)(k0 + kk) * ldn + sc + (lane & 31)]; if (gain) tv[i] *= gain[k0 + kk]; } }
; #pragma unroll
;     for (int i = 0; i < 32; ++i) scr[(2 * i + (lane >> 5)) * 33 + (lane & 31)] = tv[i];
;     asm volatile("s_waitcnt lgkmcnt(0)" ::: "memory");
;     const int c = lane & 7;
; #pragma unroll
;     for (int j = 0; j < 4; ++j) { const int n = (lane >> 3) + 8 * j; const LAS float* s = scr + (8 * c) * 33 + n;
;         u32x4 o; o.x = pk2(s[0 * 33], s[1 * 33]); o.y = pk2(s[2 * 33], s[3 * 33]); o.z = pk2(s[4 * 33], s[5 * 33]); o.w = pk2(s[6 * 33], s[7 * 33]);
;         *(u32x4*)(WT + (size_t)(drow + n) * K + k0 + 8 * c) = o; }
; __global__ void __launch_bounds__(512, 2) fwd_megakernel(Params P) {
;     ...
;             if (r < I7) { const int g = r % 176, kb = r / 176; const int pn = g >> 3, bj = (g >> 2) & 1, q = g & 3;
;                 transpose_item(bj ? P.w_up : P.w_gate, DFF, 128 * pn + 32 * q, P.norm_ffn, Wt_gu, 1024, 32 * g, 64 * kb, scr, lane); continue; } r -= I7;
	ds_write2_b32 v47, v41, v74 offset1:66
	s_waitcnt vmcnt(28)
	ds_write2_b32 v47, v75, v76 offset0:132 offset1:198
	s_waitcnt vmcnt(26)
	ds_write2_b32 v53, v77, v78 offset0:8 offset1:74
	s_waitcnt vmcnt(24)
	ds_write2_b32 v53, v79, v80 offset0:140 offset1:206
	s_waitcnt vmcnt(22)
	ds_write2_b32 v54, v81, v82 offset0:16 offset1:82
	s_waitcnt vmcnt(20)
	ds_write2_b32 v54, v83, v84 offset0:148 offset1:214
	s_waitcnt vmcnt(18)
	ds_write2_b32 v55, v85, v86 offset0:24 offset1:90
	s_waitcnt vmcnt(16)
	ds_write2_b32 v55, v87, v88 offset0:156 offset1:222
	s_waitcnt vmcnt(14)
	ds_write2_b32 v56, v89, v90 offset0:32 offset1:98
	s_waitcnt vmcnt(12)
	ds_write2_b32 v56, v91, v92 offset0:164 offset1:230
	s_waitcnt vmcnt(10)
	ds_write2_b32 v57, v93, v94 offset0:40 offset1:106
	s_waitcnt vmcnt(8)
	ds_write2_b32 v57, v95, v96 offset0:172 offset1:238
	s_waitcnt vmcnt(6)
	ds_write2_b32 v58, v0, v44 offset0:48 offset1:114
	s_waitcnt vmcnt(4)
	ds_write2_b32 v58, v45, v60 offset0:180 offset1:246
	s_waitcnt vmcnt(2)
	ds_write2_b32 v59, v61, v62 offset0:56 offset1:122
	s_waitcnt vmcnt(0)
	ds_write2_b32 v59, v63, v42 offset0:188 offset1:254
	s_waitcnt lgkmcnt(0)
	v_or_b32_e32 v0, s0, v48
	s_lshl_b32 s76, s1, 1
	ds_read2_b32 v[60:61], v49 offset0:33 offset1:41
	ds_read2_b32 v[62:63], v49 offset1:8
	ds_read2_b32 v[64:65], v49 offset0:66 offset1:74
	ds_read2_b32 v[66:67], v49 offset0:99 offset1:107
	ds_read2_b32 v[68:69], v49 offset0:132 offset1:140
	ds_read2_b32 v[70:71], v49 offset0:165 offset1:173
	ds_read2_b32 v[72:73], v49 offset0:198 offset1:206
	ds_read2_b32 v[74:75], v49 offset0:231 offset1:239
	v_mul_u32_u24_e32 v0, 0xb00, v0
	v_lshl_add_u64 v[76:77], v[6:7], 0, s[76:77]
	v_lshlrev_b32_e32 v0, 1, v0
	v_lshl_add_u64 v[78:79], v[76:77], 0, v[0:1]
	v_or_b32_e32 v0, s0, v50
	v_mul_u32_u24_e32 v0, 0xb00, v0
	s_waitcnt lgkmcnt(6)
	v_cvt_pk_bf16_f32 v42, v62, v60
	v_lshlrev_b32_e32 v0, 1, v0
	s_waitcnt lgkmcnt(4)
	v_cvt_pk_bf16_f32 v43, v64, v66
	s_waitcnt lgkmcnt(2)
	v_cvt_pk_bf16_f32 v44, v68, v70
	s_waitcnt lgkmcnt(0)
	v_cvt_pk_bf16_f32 v45, v72, v74
	global_store_dwordx4 v[78:79], v[42:45], off
	s_mov_b64 s[2:3], 0
	s_nop 0
	v_cvt_pk_bf16_f32 v42, v63, v61
	v_lshl_add_u64 v[60:61], v[76:77], 0, v[0:1]
	v_or_b32_e32 v0, s0, v51
	v_cvt_pk_bf16_f32 v43, v65, v67
	v_cvt_pk_bf16_f32 v44, v69, v71
	v_cvt_pk_bf16_f32 v45, v73, v75
	ds_read2_b32 v[62:63], v49 offset0:16 offset1:24
	ds_read2_b32 v[64:65], v49 offset0:49 offset1:57
	ds_read2_b32 v[66:67], v49 offset0:82 offset1:90
	ds_read2_b32 v[68:69], v49 offset0:115 offset1:123
	ds_read2_b32 v[70:71], v49 offset0:148 offset1:156
	ds_read2_b32 v[72:73], v49 offset0:181 offset1:189
	ds_read2_b32 v[74:75], v49 offset0:214 offset1:222
	ds_read2_b32 v[78:79], v49 offset0:247 offset1:255
	v_mul_u32_u24_e32 v0, 0xb00, v0
	v_lshlrev_b32_e32 v0, 1, v0
	global_store_dwordx4 v[60:61], v[42:45], off
	v_lshl_add_u64 v[60:61], v[76:77], 0, v[0:1]
	v_or_b32_e32 v0, s0, v52
	v_mul_u32_u24_e32 v0, 0xb00, v0
	v_lshlrev_b32_e32 v0, 1, v0
	s_waitcnt lgkmcnt(6)
	v_cvt_pk_bf16_f32 v42, v62, v64
	s_waitcnt lgkmcnt(4)
	v_cvt_pk_bf16_f32 v43, v66, v68
	s_waitcnt lgkmcnt(2)
	v_cvt_pk_bf16_f32 v44, v70, v72
	s_waitcnt lgkmcnt(0)
	v_cvt_pk_bf16_f32 v45, v74, v78
	global_store_dwordx4 v[60:61], v[42:45], off
	v_lshl_add_u64 v[60:61], v[76:77], 0, v[0:1]
	s_nop 0
	v_cvt_pk_bf16_f32 v42, v63, v65
	v_cvt_pk_bf16_f32 v43, v67, v69
	v_cvt_pk_bf16_f32 v44, v71, v73
	v_cvt_pk_bf16_f32 v45, v75, v79
	global_store_dwordx4 v[60:61], v[42:45], off
	s_waitcnt lgkmcnt(0)
.LBB0_32:
	s_andn2_b64 vcc, exec, s[2:3]
	s_cbranch_vccnz .LBB0_98
	s_add_i32 s0, s64, 0xf470
	s_and_b32 s1, s0, 0xffff
	s_mul_i32 s1, s1, 0xba2f
	s_lshr_b32 s1, s1, 23
	s_mul_i32 s2, s1, 0xb0
	s_sub_i32 s0, s0, s2
	s_and_b32 s2, s0, 0xffff
	s_bitcmp0_b32 s0, 2
	s_cselect_b32 s3, s17, s19
	s_cselect_b32 s10, s16, s18
	s_lshl_b32 s0, s2, 4
	s_and_b32 s11, s0, 0xf80
	s_lshl_b32 s0, s2, 5
	s_and_b32 s2, s0, 0x60
	s_or_b32 s2, s11, s2
	s_lshl_b32 s1, s1, 6
	s_lshl_b32 s2, s2, 2
	s_add_u32 s2, s10, s2
	s_addc_u32 s3, s3, 0
	v_mov_b32_e32 v41, v1
	v_or_b32_e32 v44, s1, v46
	v_lshl_add_u64 v[42:43], s[2:3], 0, v[40:41]
	v_mad_u64_u32 v[60:61], s[2:3], v44, s53, v[42:43]
	global_load_dword v0, v[60:61], off nt
	v_cndmask_b32_e64 v41, 0, 1, s[6:7]
	v_cmp_ne_u32_e64 s[2:3], 1, v41
	s_andn2_b64 vcc, exec, s[6:7]
	v_lshlrev_b32_e32 v41, 2, v44
	s_cbranch_vccnz .LBB0_35
	global_load_dword v45, v41, s[14:15] nt
	s_waitcnt vmcnt(0)
	v_mul_f32_e32 v0, v0, v45
.LBB0_35:
	v_or_b32_e32 v45, 2, v44
	v_mad_u64_u32 v[60:61], s[10:11], v45, s53, v[42:43]
	global_load_dword v45, v[60:61], off nt
	s_and_b64 vcc, exec, s[2:3]
	s_cbranch_vccnz .LBB0_37
	global_load_dword v60, v41, s[14:15] offset:8 nt
	s_waitcnt vmcnt(0)
	v_mul_f32_e32 v45, v45, v60
.LBB0_37:
	v_or_b32_e32 v60, 4, v44
	v_mad_u64_u32 v[60:61], s[10:11], v60, s53, v[42:43]
	global_load_dword v60, v[60:61], off nt
	s_and_b64 vcc, exec, s[2:3]
	s_cbranch_vccnz .LBB0_39
	global_load_dword v61, v41, s[14:15] offset:16 nt
	s_waitcnt vmcnt(0)
	v_mul_f32_e32 v60, v60, v61
.LBB0_39:
	v_or_b32_e32 v61, 6, v44
	v_mad_u64_u32 v[62:63], s[10:11], v61, s53, v[42:43]
	global_load_dword v61, v[62:63], off nt
	s_and_b64 vcc, exec, s[2:3]
	s_cbranch_vccnz .LBB0_41
	global_load_dword v62, v41, s[14:15] offset:24 nt
	s_waitcnt vmcnt(0)
	v_mul_f32_e32 v61, v61, v62
.LBB0_41:
	v_or_b32_e32 v62, 8, v44
	v_mad_u64_u32 v[62:63], s[10:11], v62, s53, v[42:43]
	global_load_dword v62, v[62:63], off nt
	s_and_b64 vcc, exec, s[2:3]
	s_cbranch_vccnz .LBB0_43
	global_load_dword v63, v41, s[14:15] offset:32 nt
	s_waitcnt vmcnt(0)
	v_mul_f32_e32 v62, v62, v63
; DI void transpose_item(const float* W, int ldn, int sc, const float* gain, bf16* WT, int K, int drow, int k0, LAS float* scr, int lane) {
;     ...
;     for (int i = 0; i < 32; ++i) { const int kk = 2 * i + (lane >> 5); tv[i] = 0.f;
;         if (sc >= 0) { tv[i] = W[(size_t)(k0 + kk) * ldn + sc + (lane & 31)]; if (gain) tv[i] *= gain[k0 + kk]; } }
.LBB0_43:
	v_or_b32_e32 v63, 10, v44
	v_mad_u64_u32 v[64:65], s[10:11], v63, s53, v[42:43]
	global_load_dword v63, v[64:65], off nt
	s_and_b64 vcc, exec, s[2:3]
	s_cbranch_vccnz .LBB0_45
	global_load_dword v64, v41, s[14:15] offset:40 nt
	s_waitcnt vmcnt(0)
	v_mul_f32_e32 v63, v63, v64
.LBB0_45:
	v_or_b32_e32 v64, 12, v44
	v_mad_u64_u32 v[64:65], s[10:11], v64, s53, v[42:43]
	global_load_dword v64, v[64:65], off nt
	s_and_b64 vcc, exec, s[2:3]
	s_cbranch_vccnz .LBB0_47
	global_load_dword v65, v41, s[14:15] offset:48 nt
	s_waitcnt vmcnt(0)
	v_mul_f32_e32 v64, v64, v65
.LBB0_47:
	v_or_b32_e32 v65, 14, v44
	v_mad_u64_u32 v[66:67], s[10:11], v65, s53, v[42:43]
	global_load_dword v65, v[66:67], off nt
	s_and_b64 vcc, exec, s[2:3]
	s_cbranch_vccnz .LBB0_49
	global_load_dword v66, v41, s[14:15] offset:56 nt
	s_waitcnt vmcnt(0)
	v_mul_f32_e32 v65, v65, v66
.LBB0_49:
	v_or_b32_e32 v66, 16, v44
	v_mad_u64_u32 v[66:67], s[10:11], v66, s53, v[42:43]
	global_load_dword v66, v[66:67], off nt
	s_and_b64 vcc, exec, s[2:3]
	s_cbranch_vccnz .LBB0_51
	global_load_dword v67, v41, s[14:15] offset:64 nt
	s_waitcnt vmcnt(0)
	v_mul_f32_e32 v66, v66, v67
.LBB0_51:
	v_or_b32_e32 v67, 18, v44
	v_mad_u64_u32 v[68:69], s[10:11], v67, s53, v[42:43]
	global_load_dword v67, v[68:69], off nt
	s_and_b64 vcc, exec, s[2:3]
	s_cbranch_vccnz .LBB0_53
	global_load_dword v68, v41, s[14:15] offset:72 nt
	s_waitcnt vmcnt(0)
	v_mul_f32_e32 v67, v67, v68
.LBB0_53:
	v_or_b32_e32 v68, 20, v44
	v_mad_u64_u32 v[68:69], s[10:11], v68, s53, v[42:43]
	global_load_dword v68, v[68:69], off nt
	s_and_b64 vcc, exec, s[2:3]
	s_cbranch_vccnz .LBB0_55
	global_load_dword v69, v41, s[14:15] offset:80 nt
	s_waitcnt vmcnt(0)
	v_mul_f32_e32 v68, v68, v69
.LBB0_55:
	v_or_b32_e32 v69, 22, v44
	v_mad_u64_u32 v[70:71], s[10:11], v69, s53, v[42:43]
	global_load_dword v69, v[70:71], off nt
	s_and_b64 vcc, exec, s[2:3]
	s_cbranch_vccnz .LBB0_57
	global_load_dword v70, v41, s[14:15] offset:88 nt
	s_waitcnt vmcnt(0)
	v_mul_f32_e32 v69, v69, v70
.LBB0_57:
	v_or_b32_e32 v70, 24, v44
	v_mad_u64_u32 v[70:71], s[10:11], v70, s53, v[42:43]
	global_load_dword v70, v[70:71], off nt
	s_and_b64 vcc, exec, s[2:3]
	s_cbranch_vccnz .LBB0_59
	global_load_dword v71, v41, s[14:15] offset:96 nt
	s_waitcnt vmcnt(0)
	v_mul_f32_e32 v70, v70, v71
.LBB0_59:
	v_or_b32_e32 v71, 26, v44
	v_mad_u64_u32 v[72:73], s[10:11], v71, s53, v[42:43]
	global_load_dword v71, v[72:73], off nt
	s_and_b64 vcc, exec, s[2:3]
	s_cbranch_vccnz .LBB0_61
	global_load_dword v72, v41, s[14:15] offset:104 nt
	s_waitcnt vmcnt(0)
	v_mul_f32_e32 v71, v71, v72
.LBB0_61:
	v_or_b32_e32 v72, 28, v44
	v_mad_u64_u32 v[72:73], s[10:11], v72, s53, v[42:43]
	global_load_dword v72, v[72:73], off nt
	s_and_b64 vcc, exec, s[2:3]
	s_cbranch_vccnz .LBB0_63
	global_load_dword v73, v41, s[14:15] offset:112 nt
	s_waitcnt vmcnt(0)
	v_mul_f32_e32 v72, v72, v73
.LBB0_63:
	v_or_b32_e32 v73, 30, v44
	v_mad_u64_u32 v[74:75], s[10:11], v73, s53, v[42:43]
	global_load_dword v73, v[74:75], off nt
	s_and_b64 vcc, exec, s[2:3]
	s_cbranch_vccnz .LBB0_65
	global_load_dword v74, v41, s[14:15] offset:120 nt
	s_waitcnt vmcnt(0)
	v_mul_f32_e32 v73, v73, v74
.LBB0_65:
	v_or_b32_e32 v74, 32, v44
	v_mad_u64_u32 v[74:75], s[10:11], v74, s53, v[42:43]
	global_load_dword v74, v[74:75], off nt
	s_and_b64 vcc, exec, s[2:3]
	s_cbranch_vccnz .LBB0_67
	global_load_dword v75, v41, s[14:15] offset:128 nt
	s_waitcnt vmcnt(0)
	v_mul_f32_e32 v74, v74, v75
.LBB0_67:
	v_or_b32_e32 v75, 34, v44
	v_mad_u64_u32 v[76:77], s[10:11], v75, s53, v[42:43]
	global_load_dword v75, v[76:77], off nt
	s_and_b64 vcc, exec, s[2:3]
	s_cbranch_vccnz .LBB0_69
	global_load_dword v76, v41, s[14:15] offset:136 nt
	s_waitcnt vmcnt(0)
	v_mul_f32_e32 v75, v75, v76
.LBB0_69:
	v_or_b32_e32 v76, 36, v44
	v_mad_u64_u32 v[76:77], s[10:11], v76, s53, v[42:43]
	global_load_dword v76, v[76:77], off nt
	s_and_b64 vcc, exec, s[2:3]
	s_cbranch_vccnz .LBB0_71
	global_load_dword v77, v41, s[14:15] offset:144 nt
	s_waitcnt vmcnt(0)
	v_mul_f32_e32 v76, v76, v77
; DI void transpose_item(const float* W, int ldn, int sc, const float* gain, bf16* WT, int K, int drow, int k0, LAS float* scr, int lane) {
;     ...
;     for (int i = 0; i < 32; ++i) { const int kk = 2 * i + (lane >> 5); tv[i] = 0.f;
;         if (sc >= 0) { tv[i] = W[(size_t)(k0 + kk) * ldn + sc + (lane & 31)]; if (gain) tv[i] *= gain[k0 + kk]; } }
.LBB0_71:
	v_or_b32_e32 v77, 38, v44
	v_mad_u64_u32 v[78:79], s[10:11], v77, s53, v[42:43]
	global_load_dword v77, v[78:79], off nt
	s_and_b64 vcc, exec, s[2:3]
	s_cbranch_vccnz .LBB0_73
	global_load_dword v78, v41, s[14:15] offset:152 nt
	s_waitcnt vmcnt(0)
	v_mul_f32_e32 v77, v77, v78
.LBB0_73:
	v_or_b32_e32 v78, 40, v44
	v_mad_u64_u32 v[78:79], s[10:11], v78, s53, v[42:43]
	global_load_dword v78, v[78:79], off nt
	s_and_b64 vcc, exec, s[2:3]
	s_cbranch_vccnz .LBB0_75
	global_load_dword v79, v41, s[14:15] offset:160 nt
	s_waitcnt vmcnt(0)
	v_mul_f32_e32 v78, v78, v79
.LBB0_75:
	v_or_b32_e32 v79, 42, v44
	v_mad_u64_u32 v[80:81], s[10:11], v79, s53, v[42:43]
	global_load_dword v79, v[80:81], off nt
	s_and_b64 vcc, exec, s[2:3]
	s_cbranch_vccnz .LBB0_77
	global_load_dword v80, v41, s[14:15] offset:168 nt
	s_waitcnt vmcnt(0)
	v_mul_f32_e32 v79, v79, v80
.LBB0_77:
	v_or_b32_e32 v80, 44, v44
	v_mad_u64_u32 v[80:81], s[10:11], v80, s53, v[42:43]
	global_load_dword v80, v[80:81], off nt
	s_and_b64 vcc, exec, s[2:3]
	s_cbranch_vccnz .LBB0_79
	global_load_dword v81, v41, s[14:15] offset:176 nt
	s_waitcnt vmcnt(0)
	v_mul_f32_e32 v80, v80, v81
.LBB0_79:
	v_or_b32_e32 v81, 46, v44
	v_mad_u64_u32 v[82:83], s[10:11], v81, s53, v[42:43]
	global_load_dword v81, v[82:83], off nt
	s_and_b64 vcc, exec, s[2:3]
	s_cbranch_vccnz .LBB0_81
	global_load_dword v82, v41, s[14:15] offset:184 nt
	s_waitcnt vmcnt(0)
	v_mul_f32_e32 v81, v81, v82
.LBB0_81:
	v_or_b32_e32 v82, 48, v44
	v_mad_u64_u32 v[82:83], s[10:11], v82, s53, v[42:43]
	global_load_dword v82, v[82:83], off nt
	s_and_b64 vcc, exec, s[2:3]
	s_cbranch_vccnz .LBB0_83
	global_load_dword v83, v41, s[14:15] offset:192 nt
	s_waitcnt vmcnt(0)
	v_mul_f32_e32 v82, v82, v83
.LBB0_83:
	v_or_b32_e32 v83, 50, v44
	v_mad_u64_u32 v[84:85], s[10:11], v83, s53, v[42:43]
	global_load_dword v83, v[84:85], off nt
	s_and_b64 vcc, exec, s[2:3]
	s_cbranch_vccnz .LBB0_85
	global_load_dword v84, v41, s[14:15] offset:200 nt
	s_waitcnt vmcnt(0)
	v_mul_f32_e32 v83, v83, v84
.LBB0_85:
	v_or_b32_e32 v84, 52, v44
	v_mad_u64_u32 v[84:85], s[10:11], v84, s53, v[42:43]
	global_load_dword v84, v[84:85], off nt
	s_and_b64 vcc, exec, s[2:3]
	s_cbranch_vccnz .LBB0_87
	global_load_dword v85, v41, s[14:15] offset:208 nt
	s_waitcnt vmcnt(0)
	v_mul_f32_e32 v84, v84, v85
.LBB0_87:
	v_or_b32_e32 v85, 54, v44
	v_mad_u64_u32 v[86:87], s[10:11], v85, s53, v[42:43]
	global_load_dword v85, v[86:87], off nt
	s_and_b64 vcc, exec, s[2:3]
	s_cbranch_vccnz .LBB0_89
	global_load_dword v86, v41, s[14:15] offset:216 nt
	s_waitcnt vmcnt(0)
	v_mul_f32_e32 v85, v85, v86
.LBB0_89:
	v_or_b32_e32 v86, 56, v44
	v_mad_u64_u32 v[86:87], s[10:11], v86, s53, v[42:43]
	global_load_dword v86, v[86:87], off nt
	s_and_b64 vcc, exec, s[2:3]
	s_cbranch_vccnz .LBB0_91
	global_load_dword v87, v41, s[14:15] offset:224 nt
	s_waitcnt vmcnt(0)
	v_mul_f32_e32 v86, v86, v87
.LBB0_91:
	v_or_b32_e32 v87, 58, v44
	v_mad_u64_u32 v[88:89], s[10:11], v87, s53, v[42:43]
	global_load_dword v87, v[88:89], off nt
	s_and_b64 vcc, exec, s[2:3]
	s_cbranch_vccnz .LBB0_93
	global_load_dword v88, v41, s[14:15] offset:232 nt
	s_waitcnt vmcnt(0)
	v_mul_f32_e32 v87, v87, v88
.LBB0_93:
	v_or_b32_e32 v88, 60, v44
	v_mad_u64_u32 v[88:89], s[10:11], v88, s53, v[42:43]
	global_load_dword v88, v[88:89], off nt
	s_and_b64 vcc, exec, s[2:3]
	s_cbranch_vccnz .LBB0_95
	global_load_dword v89, v41, s[14:15] offset:240 nt
	s_waitcnt vmcnt(0)
	v_mul_f32_e32 v88, v88, v89
.LBB0_95:
	v_or_b32_e32 v44, 62, v44
	v_mad_u64_u32 v[42:43], s[10:11], v44, s53, v[42:43]
	global_load_dword v42, v[42:43], off nt
	s_and_b64 vcc, exec, s[2:3]
	s_cbranch_vccnz .LBB0_97
	global_load_dword v41, v41, s[14:15] offset:248 nt
	s_waitcnt vmcnt(0)
	v_mul_f32_e32 v42, v42, v41

; DI void transpose_item(const float* W, int ldn, int sc, const float* gain, bf16* WT, int K, int drow, int k0, LAS float* scr, int lane) {
;     ...
; #pragma unroll
;     for (int i = 0; i < 32; ++i) { const int kk = 2 * i + (lane >> 5); tv[i] = 0.f;
;         if (sc >= 0) { tv[i] = W[(size_t)(k0 + kk) * ldn + sc + (lane & 31)]; if (gain) tv[i] *= gain[k0 + kk]; } }
; __global__ void __launch_bounds__(512, 2) fwd_megakernel(Params P) {
;     ...
;             if (r < I6) { const int g = r % 32, kb = r / 32; transpose_item(P.w_mo, 1024, 32 * g, nullptr, Wt_mo, 512, 32 * g, 64 * kb, scr, lane); continue; } r -= I6;
.LBB0_99:
	s_andn2_b64 vcc, exec, s[2:3]
	s_cbranch_vccnz .LBB0_101
	s_add_i32 s1, s45, 0xffffeae0
	s_add_i32 s0, s5, 0xfffeae00
	s_and_b32 s1, s1, 0x7fffffc0
	s_and_b32 s0, s0, 0x3e0
	v_or_b32_e32 v0, s1, v46
	s_lshl_b32 s76, s0, 2
	v_or_b32_e32 v60, 2, v0
	v_mov_b32_e32 v61, v1
	v_or_b32_e32 v62, 4, v0
	v_mov_b32_e32 v63, v1
	v_or_b32_e32 v64, 6, v0
	v_mov_b32_e32 v65, v1
	v_or_b32_e32 v66, 8, v0
	v_mov_b32_e32 v67, v1
	v_or_b32_e32 v68, 10, v0
	v_mov_b32_e32 v69, v1
	v_or_b32_e32 v70, 12, v0
	v_mov_b32_e32 v71, v1
	v_lshl_add_u64 v[42:43], v[14:15], 0, s[76:77]
	v_lshlrev_b64 v[44:45], 12, v[0:1]
	v_lshlrev_b64 v[60:61], 12, v[60:61]
	v_lshlrev_b64 v[62:63], 12, v[62:63]
	v_lshlrev_b64 v[64:65], 12, v[64:65]
	v_lshlrev_b64 v[66:67], 12, v[66:67]
	v_lshlrev_b64 v[68:69], 12, v[68:69]
	v_lshlrev_b64 v[70:71], 12, v[70:71]
	v_or_b32_e32 v72, 14, v0
	v_mov_b32_e32 v73, v1
	v_lshl_add_u64 v[44:45], v[42:43], 0, v[44:45]
	v_lshl_add_u64 v[60:61], v[42:43], 0, v[60:61]
	v_lshl_add_u64 v[62:63], v[42:43], 0, v[62:63]
	v_lshl_add_u64 v[64:65], v[42:43], 0, v[64:65]
	v_lshl_add_u64 v[66:67], v[42:43], 0, v[66:67]
	v_lshl_add_u64 v[68:69], v[42:43], 0, v[68:69]
	v_lshl_add_u64 v[70:71], v[42:43], 0, v[70:71]
	v_lshlrev_b64 v[72:73], 12, v[72:73]
	v_lshl_add_u64 v[72:73], v[42:43], 0, v[72:73]
	global_load_dword v41, v[44:45], off nt
	global_load_dword v74, v[60:61], off nt
	global_load_dword v75, v[62:63], off nt
	global_load_dword v76, v[64:65], off nt
	global_load_dword v77, v[66:67], off nt
	global_load_dword v78, v[68:69], off nt
	global_load_dword v79, v[70:71], off nt
	global_load_dword v80, v[72:73], off nt
	v_or_b32_e32 v44, 16, v0
	v_mov_b32_e32 v45, v1
	v_or_b32_e32 v60, 18, v0
	v_mov_b32_e32 v61, v1
	v_or_b32_e32 v62, 20, v0
	v_mov_b32_e32 v63, v1
	v_or_b32_e32 v64, 22, v0
	v_mov_b32_e32 v65, v1
	v_or_b32_e32 v66, 24, v0
	v_mov_b32_e32 v67, v1
	v_or_b32_e32 v68, 26, v0
	v_mov_b32_e32 v69, v1
	v_or_b32_e32 v70, 28, v0
	v_mov_b32_e32 v71, v1
	v_lshlrev_b64 v[44:45], 12, v[44:45]
	v_lshlrev_b64 v[60:61], 12, v[60:61]
	v_lshlrev_b64 v[62:63], 12, v[62:63]
	v_lshlrev_b64 v[64:65], 12, v[64:65]
	v_lshlrev_b64 v[66:67], 12, v[66:67]
	v_lshlrev_b64 v[68:69], 12, v[68:69]
	v_lshlrev_b64 v[70:71], 12, v[70:71]
	v_or_b32_e32 v72, 30, v0
	v_mov_b32_e32 v73, v1
	v_lshl_add_u64 v[44:45], v[42:43], 0, v[44:45]
	v_lshl_add_u64 v[60:61], v[42:43], 0, v[60:61]
	v_lshl_add_u64 v[62:63], v[42:43], 0, v[62:63]
	v_lshl_add_u64 v[64:65], v[42:43], 0, v[64:65]
	v_lshl_add_u64 v[66:67], v[42:43], 0, v[66:67]
	v_lshl_add_u64 v[68:69], v[42:43], 0, v[68:69]
	v_lshl_add_u64 v[70:71], v[42:43], 0, v[70:71]
	v_lshlrev_b64 v[72:73], 12, v[72:73]
	v_lshl_add_u64 v[72:73], v[42:43], 0, v[72:73]
	global_load_dword v81, v[44:45], off nt
	global_load_dword v82, v[60:61], off nt
	global_load_dword v83, v[62:63], off nt
	global_load_dword v84, v[64:65], off nt
	global_load_dword v85, v[66:67], off nt
	global_load_dword v86, v[68:69], off nt
	global_load_dword v87, v[70:71], off nt
	global_load_dword v88, v[72:73], off nt
	v_or_b32_e32 v44, 32, v0
	v_mov_b32_e32 v45, v1
	v_or_b32_e32 v60, 34, v0
	v_mov_b32_e32 v61, v1
	v_or_b32_e32 v62, 36, v0
	v_mov_b32_e32 v63, v1
	v_or_b32_e32 v64, 38, v0
	v_mov_b32_e32 v65, v1
	v_or_b32_e32 v66, 40, v0
	v_mov_b32_e32 v67, v1
	v_or_b32_e32 v68, 42, v0
	v_mov_b32_e32 v69, v1
	v_or_b32_e32 v70, 44, v0
	v_mov_b32_e32 v71, v1
	v_lshlrev_b64 v[44:45], 12, v[44:45]
	v_lshlrev_b64 v[60:61], 12, v[60:61]
	v_lshlrev_b64 v[62:63], 12, v[62:63]
	v_lshlrev_b64 v[64:65], 12, v[64:65]
	v_lshlrev_b64 v[66:67], 12, v[66:67]
	v_lshlrev_b64 v[68:69], 12, v[68:69]
	v_lshlrev_b64 v[70:71], 12, v[70:71]
	v_or_b32_e32 v72, 46, v0
	v_mov_b32_e32 v73, v1
	v_lshl_add_u64 v[44:45], v[42:43], 0, v[44:45]
	v_lshl_add_u64 v[60:61], v[42:43], 0, v[60:61]
	v_lshl_add_u64 v[62:63], v[42:43], 0, v[62:63]
	v_lshl_add_u64 v[64:65], v[42:43], 0, v[64:65]
	v_lshl_add_u64 v[66:67], v[42:43], 0, v[66:67]
	v_lshl_add_u64 v[68:69], v[42:43], 0, v[68:69]
	v_lshl_add_u64 v[70:71], v[42:43], 0, v[70:71]
	v_lshlrev_b64 v[72:73], 12, v[72:73]
	v_lshl_add_u64 v[72:73], v[42:43], 0, v[72:73]
	global_load_dword v89, v[44:45], off nt
	global_load_dword v90, v[60:61], off nt
	global_load_dword v91, v[62:63], off nt
	global_load_dword v92, v[64:65], off nt
	global_load_dword v93, v[66:67], off nt
	global_load_dword v94, v[68:69], off nt
	global_load_dword v95, v[70:71], off nt
	global_load_dword v96, v[72:73], off nt
	v_or_b32_e32 v44, 48, v0
	v_mov_b32_e32 v45, v1
	v_or_b32_e32 v60, 50, v0
	v_mov_b32_e32 v61, v1
	v_or_b32_e32 v62, 52, v0
	v_mov_b32_e32 v63, v1
	v_or_b32_e32 v64, 54, v0
	v_mov_b32_e32 v65, v1
	v_or_b32_e32 v66, 56, v0
	v_mov_b32_e32 v67, v1
	v_or_b32_e32 v68, 58, v0
	v_mov_b32_e32 v69, v1
	v_or_b32_e32 v70, 60, v0
	v_mov_b32_e32 v71, v1
	v_or_b32_e32 v0, 62, v0
	v_lshlrev_b64 v[44:45], 12, v[44:45]
	v_lshlrev_b64 v[60:61], 12, v[60:61]
	v_lshlrev_b64 v[62:63], 12, v[62:63]
	v_lshlrev_b64 v[64:65], 12, v[64:65]
	v_lshlrev_b64 v[66:67], 12, v[66:67]
	v_lshlrev_b64 v[68:69], 12, v[68:69]
	v_lshlrev_b64 v[70:71], 12, v[70:71]
	v_lshlrev_b64 v[72:73], 12, v[0:1]
	v_lshl_add_u64 v[44:45], v[42:43], 0, v[44:45]
	v_lshl_add_u64 v[60:61], v[42:43], 0, v[60:61]
	v_lshl_add_u64 v[62:63], v[42:43], 0, v[62:63]
	v_lshl_add_u64 v[64:65], v[42:43], 0, v[64:65]
	v_lshl_add_u64 v[66:67], v[42:43], 0, v[66:67]
	v_lshl_add_u64 v[68:69], v[42:43], 0, v[68:69]
	v_lshl_add_u64 v[70:71], v[42:43], 0, v[70:71]
	v_lshl_add_u64 v[42:43], v[42:43], 0, v[72:73]
	global_load_dword v0, v[44:45], off nt
	s_nop 0
	global_load_dword v44, v[60:61], off nt
	global_load_dword v45, v[62:63], off nt
	s_nop 0
	global_load_dword v60, v[64:65], off nt
	global_load_dword v61, v[66:67], off nt
	global_load_dword v62, v[68:69], off nt
	global_load_dword v63, v[70:71], off nt
	s_nop 0
	global_load_dword v42, v[42:43], off nt
	s_waitcnt vmcnt(30)
; #define LAS __attribute__((address_space(3)))
; DI unsigned pk2(float lo, float hi) { return pg8::cvt_pk_bf16(lo, hi); }
; DI void transpose_item(const float* W, int ldn, int sc, const float* gain, bf16* WT, int K, int drow, int k0, LAS float* scr, int lane) {
;     ...
;     for (int i = 0; i < 32; ++i) scr[(2 * i + (lane >> 5)) * 33 + (lane & 31)] = tv[i];
;     asm volatile("s_waitcnt lgkmcnt(0)" ::: "memory");
;     const int c = lane & 7;
; #pragma unroll
;     for (int j = 0; j < 4; ++j) { const int n = (lane >> 3) + 8 * j; const LAS float* s = scr + (8 * c) * 33 + n;
;         u32x4 o; o.x = pk2(s[0 * 33], s[1 * 33]); o.y = pk2(s[2 * 33], s[3 * 33]); o.z = pk2(s[4 * 33], s[5 * 33]); o.w = pk2(s[6 * 33], s[7 * 33]);
;         *(u32x4*)(WT + (size_t)(drow + n) * K + k0 + 8 * c) = o; }
	ds_write2_b32 v47, v41, v74 offset1:66
	s_waitcnt vmcnt(28)
	ds_write2_b32 v47, v75, v76 offset0:132 offset1:198
	s_waitcnt vmcnt(26)
	ds_write2_b32 v53, v77, v78 offset0:8 offset1:74
	s_waitcnt vmcnt(24)
	ds_write2_b32 v53, v79, v80 offset0:140 offset1:206
	s_waitcnt vmcnt(22)
	ds_write2_b32 v54, v81, v82 offset0:16 offset1:82
	s_waitcnt vmcnt(20)
	ds_write2_b32 v54, v83, v84 offset0:148 offset1:214
	s_waitcnt vmcnt(18)
	ds_write2_b32 v55, v85, v86 offset0:24 offset1:90
	s_waitcnt vmcnt(16)
	ds_write2_b32 v55, v87, v88 offset0:156 offset1:222
	s_waitcnt vmcnt(14)
	ds_write2_b32 v56, v89, v90 offset0:32 offset1:98
	s_waitcnt vmcnt(12)
	ds_write2_b32 v56, v91, v92 offset0:164 offset1:230
	s_waitcnt vmcnt(10)
	ds_write2_b32 v57, v93, v94 offset0:40 offset1:106
	s_waitcnt vmcnt(8)
	ds_write2_b32 v57, v95, v96 offset0:172 offset1:238
	s_waitcnt vmcnt(6)
	ds_write2_b32 v58, v0, v44 offset0:48 offset1:114
	s_waitcnt vmcnt(4)
	ds_write2_b32 v58, v45, v60 offset0:180 offset1:246
	s_waitcnt vmcnt(2)
	ds_write2_b32 v59, v61, v62 offset0:56 offset1:122
	s_waitcnt vmcnt(0)
	ds_write2_b32 v59, v63, v42 offset0:188 offset1:254
	s_waitcnt lgkmcnt(0)
	ds_read2_b32 v[60:61], v49 offset0:33 offset1:41
	ds_read2_b32 v[62:63], v49 offset1:8
	ds_read2_b32 v[64:65], v49 offset0:66 offset1:74
	ds_read2_b32 v[66:67], v49 offset0:99 offset1:107
	ds_read2_b32 v[68:69], v49 offset0:132 offset1:140
	ds_read2_b32 v[70:71], v49 offset0:165 offset1:173
	ds_read2_b32 v[72:73], v49 offset0:198 offset1:206
	ds_read2_b32 v[74:75], v49 offset0:231 offset1:239
	s_lshl_b32 s76, s1, 1
	v_or_b32_e32 v0, s0, v48
	v_lshl_add_u64 v[76:77], v[16:17], 0, s[76:77]
	v_lshlrev_b32_e32 v0, 10, v0
	v_lshl_add_u64 v[78:79], v[76:77], 0, v[0:1]
	s_waitcnt lgkmcnt(6)
	v_cvt_pk_bf16_f32 v42, v62, v60
	s_waitcnt lgkmcnt(4)
	v_cvt_pk_bf16_f32 v43, v64, v66
	s_waitcnt lgkmcnt(2)
	v_cvt_pk_bf16_f32 v44, v68, v70
	s_waitcnt lgkmcnt(0)
	v_cvt_pk_bf16_f32 v45, v72, v74
	global_store_dwordx4 v[78:79], v[42:45], off
	v_or_b32_e32 v0, s0, v50
	v_lshlrev_b32_e32 v0, 10, v0
	v_cvt_pk_bf16_f32 v42, v63, v61
	v_cvt_pk_bf16_f32 v43, v65, v67
	v_cvt_pk_bf16_f32 v44, v69, v71
	v_cvt_pk_bf16_f32 v45, v73, v75
	ds_read2_b32 v[62:63], v49 offset0:16 offset1:24
	ds_read2_b32 v[64:65], v49 offset0:49 offset1:57
	ds_read2_b32 v[66:67], v49 offset0:82 offset1:90
	ds_read2_b32 v[68:69], v49 offset0:115 offset1:123
	ds_read2_b32 v[70:71], v49 offset0:148 offset1:156
	ds_read2_b32 v[72:73], v49 offset0:181 offset1:189
	ds_read2_b32 v[74:75], v49 offset0:214 offset1:222
	ds_read2_b32 v[78:79], v49 offset0:247 offset1:255
	v_lshl_add_u64 v[60:61], v[76:77], 0, v[0:1]
	v_or_b32_e32 v0, s0, v51
	v_lshlrev_b32_e32 v0, 10, v0
	global_store_dwordx4 v[60:61], v[42:45], off
	v_lshl_add_u64 v[60:61], v[76:77], 0, v[0:1]
	v_or_b32_e32 v0, s0, v52
	v_lshlrev_b32_e32 v0, 10, v0
	s_waitcnt lgkmcnt(6)
	v_cvt_pk_bf16_f32 v42, v62, v64
	s_waitcnt lgkmcnt(4)
	v_cvt_pk_bf16_f32 v43, v66, v68
	s_waitcnt lgkmcnt(2)
	v_cvt_pk_bf16_f32 v44, v70, v72
	s_waitcnt lgkmcnt(0)
	v_cvt_pk_bf16_f32 v45, v74, v78
	global_store_dwordx4 v[60:61], v[42:45], off
	v_lshl_add_u64 v[60:61], v[76:77], 0, v[0:1]
	s_nop 0
	v_cvt_pk_bf16_f32 v42, v63, v65
	v_cvt_pk_bf16_f32 v43, v67, v69
	v_cvt_pk_bf16_f32 v44, v71, v73
	v_cvt_pk_bf16_f32 v45, v75, v79
	global_store_dwordx4 v[60:61], v[42:45], off
	s_waitcnt lgkmcnt(0)

; DI void transpose_item(const float* W, int ldn, int sc, const float* gain, bf16* WT, int K, int drow, int k0, LAS float* scr, int lane) {
;     ...
;     for (int i = 0; i < 32; ++i) { const int kk = 2 * i + (lane >> 5); tv[i] = 0.f;
;         if (sc >= 0) { tv[i] = W[(size_t)(k0 + kk) * ldn + sc + (lane & 31)]; if (gain) tv[i] *= gain[k0 + kk]; } }
; __global__ void __launch_bounds__(512, 2) fwd_megakernel(Params P) {
;     ...
;             if (r < I5) { const int g = r % 16, kb = r / 16; transpose_item(P.w_mq, 512, 32 * g, P.norm_mem_q, Wt_mq, 1024, 32 * g, 64 * kb, scr, lane); continue; } r -= I5;
.LBB0_102:
	s_andn2_b64 vcc, exec, s[2:3]
	s_cbranch_vccnz .LBB0_168
	s_and_b32 s1, s49, 0x3fc0
	s_and_b32 s0, s5, 0x1e0
	s_add_i32 s12, s1, 0xffffd9c0
	v_or_b32_e32 v0, s12, v46
	s_lshl_b32 s76, s0, 2
	v_lshl_add_u64 v[42:43], v[18:19], 0, s[76:77]
	v_lshlrev_b64 v[44:45], 11, v[0:1]
	v_lshl_add_u64 v[44:45], v[42:43], 0, v[44:45]
	global_load_dword v41, v[44:45], off nt
	v_readlane_b32 s80, v254, 0
	v_cndmask_b32_e64 v44, 0, 1, s[70:71]
	v_readlane_b32 s88, v254, 8
	v_readlane_b32 s89, v254, 9
	v_cmp_ne_u32_e64 s[2:3], 1, v44
	s_andn2_b64 vcc, exec, s[70:71]
	v_lshl_add_u64 v[44:45], v[0:1], 2, s[88:89]
	v_readlane_b32 s81, v254, 1
	v_readlane_b32 s82, v254, 2
	v_readlane_b32 s83, v254, 3
	v_readlane_b32 s84, v254, 4
	v_readlane_b32 s85, v254, 5
	v_readlane_b32 s86, v254, 6
	v_readlane_b32 s87, v254, 7
	v_readlane_b32 s90, v254, 10
	v_readlane_b32 s91, v254, 11
	v_readlane_b32 s92, v254, 12
	v_readlane_b32 s93, v254, 13
	v_readlane_b32 s94, v254, 14
	v_readlane_b32 s95, v254, 15
	s_cbranch_vccnz .LBB0_105
	global_load_dword v60, v[44:45], off nt
	s_waitcnt vmcnt(0)
	v_mul_f32_e32 v41, v41, v60
.LBB0_105:
	v_or_b32_e32 v60, 2, v0
	v_mov_b32_e32 v61, v1
	v_lshlrev_b64 v[60:61], 11, v[60:61]
	v_lshl_add_u64 v[60:61], v[42:43], 0, v[60:61]
	global_load_dword v60, v[60:61], off nt
	s_and_b64 vcc, exec, s[2:3]
	s_cbranch_vccnz .LBB0_107
	global_load_dword v61, v[44:45], off offset:8 nt
	s_waitcnt vmcnt(0)
	v_mul_f32_e32 v60, v60, v61
.LBB0_107:
	v_or_b32_e32 v62, 4, v0
	v_mov_b32_e32 v63, v1
	v_lshlrev_b64 v[62:63], 11, v[62:63]
	v_lshl_add_u64 v[62:63], v[42:43], 0, v[62:63]
	global_load_dword v61, v[62:63], off nt
	s_and_b64 vcc, exec, s[2:3]
	s_cbranch_vccnz .LBB0_109
	global_load_dword v62, v[44:45], off offset:16 nt
	s_waitcnt vmcnt(0)
	v_mul_f32_e32 v61, v61, v62
.LBB0_109:
	v_or_b32_e32 v62, 6, v0
	v_mov_b32_e32 v63, v1
	v_lshlrev_b64 v[62:63], 11, v[62:63]
	v_lshl_add_u64 v[62:63], v[42:43], 0, v[62:63]
	global_load_dword v62, v[62:63], off nt
	s_and_b64 vcc, exec, s[2:3]
	s_cbranch_vccnz .LBB0_111
	global_load_dword v63, v[44:45], off offset:24 nt
	s_waitcnt vmcnt(0)
	v_mul_f32_e32 v62, v62, v63
.LBB0_111:
	v_or_b32_e32 v64, 8, v0
	v_mov_b32_e32 v65, v1
	v_lshlrev_b64 v[64:65], 11, v[64:65]
	v_lshl_add_u64 v[64:65], v[42:43], 0, v[64:65]
	global_load_dword v63, v[64:65], off nt
	s_and_b64 vcc, exec, s[2:3]
	s_cbranch_vccnz .LBB0_113
	global_load_dword v64, v[44:45], off offset:32 nt
	s_waitcnt vmcnt(0)
	v_mul_f32_e32 v63, v63, v64
.LBB0_113:
	v_or_b32_e32 v64, 10, v0
	v_mov_b32_e32 v65, v1
	v_lshlrev_b64 v[64:65], 11, v[64:65]
	v_lshl_add_u64 v[64:65], v[42:43], 0, v[64:65]
	global_load_dword v64, v[64:65], off nt
	s_and_b64 vcc, exec, s[2:3]
	s_cbranch_vccnz .LBB0_115
	global_load_dword v65, v[44:45], off offset:40 nt
	s_waitcnt vmcnt(0)
	v_mul_f32_e32 v64, v64, v65
.LBB0_115:
	v_or_b32_e32 v66, 12, v0
	v_mov_b32_e32 v67, v1
	v_lshlrev_b64 v[66:67], 11, v[66:67]
	v_lshl_add_u64 v[66:67], v[42:43], 0, v[66:67]
	global_load_dword v65, v[66:67], off nt
	s_and_b64 vcc, exec, s[2:3]
	s_cbranch_vccnz .LBB0_117
	global_load_dword v66, v[44:45], off offset:48 nt
	s_waitcnt vmcnt(0)
	v_mul_f32_e32 v65, v65, v66
.LBB0_117:
	v_or_b32_e32 v66, 14, v0
	v_mov_b32_e32 v67, v1
	v_lshlrev_b64 v[66:67], 11, v[66:67]
	v_lshl_add_u64 v[66:67], v[42:43], 0, v[66:67]
	global_load_dword v66, v[66:67], off nt
	s_and_b64 vcc, exec, s[2:3]
	s_cbranch_vccnz .LBB0_119
	global_load_dword v67, v[44:45], off offset:56 nt
	s_waitcnt vmcnt(0)
	v_mul_f32_e32 v66, v66, v67
.LBB0_119:
	v_or_b32_e32 v68, 16, v0
	v_mov_b32_e32 v69, v1
	v_lshlrev_b64 v[68:69], 11, v[68:69]
	v_lshl_add_u64 v[68:69], v[42:43], 0, v[68:69]
	global_load_dword v67, v[68:69], off nt
	s_and_b64 vcc, exec, s[2:3]
	s_cbranch_vccnz .LBB0_121
	global_load_dword v68, v[44:45], off offset:64 nt
	s_waitcnt vmcnt(0)
	v_mul_f32_e32 v67, v67, v68
.LBB0_121:
	v_or_b32_e32 v68, 18, v0
	v_mov_b32_e32 v69, v1
	v_lshlrev_b64 v[68:69], 11, v[68:69]
	v_lshl_add_u64 v[68:69], v[42:43], 0, v[68:69]
	global_load_dword v68, v[68:69], off nt
	s_and_b64 vcc, exec, s[2:3]
	s_cbranch_vccnz .LBB0_123
	global_load_dword v69, v[44:45], off offset:72 nt
	s_waitcnt vmcnt(0)
	v_mul_f32_e32 v68, v68, v69
.LBB0_123:
	v_or_b32_e32 v70, 20, v0
	v_mov_b32_e32 v71, v1
	v_lshlrev_b64 v[70:71], 11, v[70:71]
	v_lshl_add_u64 v[70:71], v[42:43], 0, v[70:71]
	global_load_dword v69, v[70:71], off nt
	s_and_b64 vcc, exec, s[2:3]
	s_cbranch_vccnz .LBB0_125
	global_load_dword v70, v[44:45], off offset:80 nt
	s_waitcnt vmcnt(0)
	v_mul_f32_e32 v69, v69, v70
.LBB0_125:
	v_or_b32_e32 v70, 22, v0
	v_mov_b32_e32 v71, v1
	v_lshlrev_b64 v[70:71], 11, v[70:71]
	v_lshl_add_u64 v[70:71], v[42:43], 0, v[70:71]
	global_load_dword v70, v[70:71], off nt
	s_and_b64 vcc, exec, s[2:3]
	s_cbranch_vccnz .LBB0_127
	global_load_dword v71, v[44:45], off offset:88 nt
	s_waitcnt vmcnt(0)
	v_mul_f32_e32 v70, v70, v71
.LBB0_127:
	v_or_b32_e32 v72, 24, v0
	v_mov_b32_e32 v73, v1
	v_lshlrev_b64 v[72:73], 11, v[72:73]
	v_lshl_add_u64 v[72:73], v[42:43], 0, v[72:73]
	global_load_dword v71, v[72:73], off nt
	s_and_b64 vcc, exec, s[2:3]
	s_cbranch_vccnz .LBB0_129
	global_load_dword v72, v[44:45], off offset:96 nt
	s_waitcnt vmcnt(0)
	v_mul_f32_e32 v71, v71, v72
.LBB0_129:
	v_or_b32_e32 v72, 26, v0
	v_mov_b32_e32 v73, v1
	v_lshlrev_b64 v[72:73], 11, v[72:73]
	v_lshl_add_u64 v[72:73], v[42:43], 0, v[72:73]
	global_load_dword v72, v[72:73], off nt
	s_and_b64 vcc, exec, s[2:3]
	s_cbranch_vccnz .LBB0_131
	global_load_dword v73, v[44:45], off offset:104 nt
	s_waitcnt vmcnt(0)
	v_mul_f32_e32 v72, v72, v73
; DI void transpose_item(const float* W, int ldn, int sc, const float* gain, bf16* WT, int K, int drow, int k0, LAS float* scr, int lane) {
;     ...
;     for (int i = 0; i < 32; ++i) { const int kk = 2 * i + (lane >> 5); tv[i] = 0.f;
;         if (sc >= 0) { tv[i] = W[(size_t)(k0 + kk) * ldn + sc + (lane & 31)]; if (gain) tv[i] *= gain[k0 + kk]; } }
.LBB0_131:
	v_or_b32_e32 v74, 28, v0
	v_mov_b32_e32 v75, v1
	v_lshlrev_b64 v[74:75], 11, v[74:75]
	v_lshl_add_u64 v[74:75], v[42:43], 0, v[74:75]
	global_load_dword v73, v[74:75], off nt
	s_and_b64 vcc, exec, s[2:3]
	s_cbranch_vccnz .LBB0_133
	global_load_dword v74, v[44:45], off offset:112 nt
	s_waitcnt vmcnt(0)
	v_mul_f32_e32 v73, v73, v74
.LBB0_133:
	v_or_b32_e32 v74, 30, v0
	v_mov_b32_e32 v75, v1
	v_lshlrev_b64 v[74:75], 11, v[74:75]
	v_lshl_add_u64 v[74:75], v[42:43], 0, v[74:75]
	global_load_dword v74, v[74:75], off nt
	s_and_b64 vcc, exec, s[2:3]
	s_cbranch_vccnz .LBB0_135
	global_load_dword v75, v[44:45], off offset:120 nt
	s_waitcnt vmcnt(0)
	v_mul_f32_e32 v74, v74, v75
.LBB0_135:
	v_or_b32_e32 v76, 32, v0
	v_mov_b32_e32 v77, v1
	v_lshlrev_b64 v[76:77], 11, v[76:77]
	v_lshl_add_u64 v[76:77], v[42:43], 0, v[76:77]
	global_load_dword v75, v[76:77], off nt
	s_and_b64 vcc, exec, s[2:3]
	s_cbranch_vccnz .LBB0_137
	global_load_dword v76, v[44:45], off offset:128 nt
	s_waitcnt vmcnt(0)
	v_mul_f32_e32 v75, v75, v76
.LBB0_137:
	v_or_b32_e32 v76, 34, v0
	v_mov_b32_e32 v77, v1
	v_lshlrev_b64 v[76:77], 11, v[76:77]
	v_lshl_add_u64 v[76:77], v[42:43], 0, v[76:77]
	global_load_dword v76, v[76:77], off nt
	s_and_b64 vcc, exec, s[2:3]
	s_cbranch_vccnz .LBB0_139
	global_load_dword v77, v[44:45], off offset:136 nt
	s_waitcnt vmcnt(0)
	v_mul_f32_e32 v76, v76, v77
.LBB0_139:
	v_or_b32_e32 v78, 36, v0
	v_mov_b32_e32 v79, v1
	v_lshlrev_b64 v[78:79], 11, v[78:79]
	v_lshl_add_u64 v[78:79], v[42:43], 0, v[78:79]
	global_load_dword v77, v[78:79], off nt
	s_and_b64 vcc, exec, s[2:3]
	s_cbranch_vccnz .LBB0_141
	global_load_dword v78, v[44:45], off offset:144 nt
	s_waitcnt vmcnt(0)
	v_mul_f32_e32 v77, v77, v78
.LBB0_141:
	v_or_b32_e32 v78, 38, v0
	v_mov_b32_e32 v79, v1
	v_lshlrev_b64 v[78:79], 11, v[78:79]
	v_lshl_add_u64 v[78:79], v[42:43], 0, v[78:79]
	global_load_dword v78, v[78:79], off nt
	s_and_b64 vcc, exec, s[2:3]
	s_cbranch_vccnz .LBB0_143
	global_load_dword v79, v[44:45], off offset:152 nt
	s_waitcnt vmcnt(0)
	v_mul_f32_e32 v78, v78, v79
.LBB0_143:
	v_or_b32_e32 v80, 40, v0
	v_mov_b32_e32 v81, v1
	v_lshlrev_b64 v[80:81], 11, v[80:81]
	v_lshl_add_u64 v[80:81], v[42:43], 0, v[80:81]
	global_load_dword v79, v[80:81], off nt
	s_and_b64 vcc, exec, s[2:3]
	s_cbranch_vccnz .LBB0_145
	global_load_dword v80, v[44:45], off offset:160 nt
	s_waitcnt vmcnt(0)
	v_mul_f32_e32 v79, v79, v80
.LBB0_145:
	v_or_b32_e32 v80, 42, v0
	v_mov_b32_e32 v81, v1
	v_lshlrev_b64 v[80:81], 11, v[80:81]
	v_lshl_add_u64 v[80:81], v[42:43], 0, v[80:81]
	global_load_dword v80, v[80:81], off nt
	s_and_b64 vcc, exec, s[2:3]
	s_cbranch_vccnz .LBB0_147
	global_load_dword v81, v[44:45], off offset:168 nt
	s_waitcnt vmcnt(0)
	v_mul_f32_e32 v80, v80, v81
.LBB0_147:
	v_or_b32_e32 v82, 44, v0
	v_mov_b32_e32 v83, v1
	v_lshlrev_b64 v[82:83], 11, v[82:83]
	v_lshl_add_u64 v[82:83], v[42:43], 0, v[82:83]
	global_load_dword v81, v[82:83], off nt
	s_and_b64 vcc, exec, s[2:3]
	s_cbranch_vccnz .LBB0_149
	global_load_dword v82, v[44:45], off offset:176 nt
	s_waitcnt vmcnt(0)
	v_mul_f32_e32 v81, v81, v82
.LBB0_149:
	v_or_b32_e32 v82, 46, v0
	v_mov_b32_e32 v83, v1
	v_lshlrev_b64 v[82:83], 11, v[82:83]
	v_lshl_add_u64 v[82:83], v[42:43], 0, v[82:83]
	global_load_dword v82, v[82:83], off nt
	s_and_b64 vcc, exec, s[2:3]
	s_cbranch_vccnz .LBB0_151
	global_load_dword v83, v[44:45], off offset:184 nt
	s_waitcnt vmcnt(0)
	v_mul_f32_e32 v82, v82, v83
.LBB0_151:
	v_or_b32_e32 v84, 48, v0
	v_mov_b32_e32 v85, v1
	v_lshlrev_b64 v[84:85], 11, v[84:85]
	v_lshl_add_u64 v[84:85], v[42:43], 0, v[84:85]
	global_load_dword v83, v[84:85], off nt
	s_and_b64 vcc, exec, s[2:3]
	s_cbranch_vccnz .LBB0_153
	global_load_dword v84, v[44:45], off offset:192 nt
	s_waitcnt vmcnt(0)
	v_mul_f32_e32 v83, v83, v84
.LBB0_153:
	v_or_b32_e32 v84, 50, v0
	v_mov_b32_e32 v85, v1
	v_lshlrev_b64 v[84:85], 11, v[84:85]
	v_lshl_add_u64 v[84:85], v[42:43], 0, v[84:85]
	global_load_dword v84, v[84:85], off nt
	s_and_b64 vcc, exec, s[2:3]
	s_cbranch_vccnz .LBB0_155
	global_load_dword v85, v[44:45], off offset:200 nt
	s_waitcnt vmcnt(0)
	v_mul_f32_e32 v84, v84, v85
.LBB0_155:
	v_or_b32_e32 v86, 52, v0
	v_mov_b32_e32 v87, v1
	v_lshlrev_b64 v[86:87], 11, v[86:87]
	v_lshl_add_u64 v[86:87], v[42:43], 0, v[86:87]
	global_load_dword v85, v[86:87], off nt
	s_and_b64 vcc, exec, s[2:3]
	s_cbranch_vccnz .LBB0_157
	global_load_dword v86, v[44:45], off offset:208 nt
	s_waitcnt vmcnt(0)
	v_mul_f32_e32 v85, v85, v86
.LBB0_157:
	v_or_b32_e32 v86, 54, v0
	v_mov_b32_e32 v87, v1
	v_lshlrev_b64 v[86:87], 11, v[86:87]
	v_lshl_add_u64 v[86:87], v[42:43], 0, v[86:87]
	global_load_dword v86, v[86:87], off nt
	s_and_b64 vcc, exec, s[2:3]
	s_cbranch_vccnz .LBB0_159
	global_load_dword v87, v[44:45], off offset:216 nt
	s_waitcnt vmcnt(0)
	v_mul_f32_e32 v86, v86, v87
.LBB0_159:
	v_or_b32_e32 v88, 56, v0
	v_mov_b32_e32 v89, v1
	v_lshlrev_b64 v[88:89], 11, v[88:89]
	v_lshl_add_u64 v[88:89], v[42:43], 0, v[88:89]
	global_load_dword v87, v[88:89], off nt
	s_and_b64 vcc, exec, s[2:3]
	s_cbranch_vccnz .LBB0_161
	global_load_dword v88, v[44:45], off offset:224 nt
	s_waitcnt vmcnt(0)
	v_mul_f32_e32 v87, v87, v88
.LBB0_161:
	v_or_b32_e32 v88, 58, v0
	v_mov_b32_e32 v89, v1
	v_lshlrev_b64 v[88:89], 11, v[88:89]
	v_lshl_add_u64 v[88:89], v[42:43], 0, v[88:89]
	global_load_dword v88, v[88:89], off nt
	s_and_b64 vcc, exec, s[2:3]
	s_cbranch_vccnz .LBB0_163
	global_load_dword v89, v[44:45], off offset:232 nt
	s_waitcnt vmcnt(0)
	v_mul_f32_e32 v88, v88, v89
.LBB0_163:
	v_or_b32_e32 v90, 60, v0
	v_mov_b32_e32 v91, v1
	v_lshlrev_b64 v[90:91], 11, v[90:91]
	v_lshl_add_u64 v[90:91], v[42:43], 0, v[90:91]
	global_load_dword v89, v[90:91], off nt
	s_and_b64 vcc, exec, s[2:3]
	s_cbranch_vccnz .LBB0_165
	global_load_dword v90, v[44:45], off offset:240 nt
	s_waitcnt vmcnt(0)
	v_mul_f32_e32 v89, v89, v90
.LBB0_165:
	v_or_b32_e32 v0, 62, v0
	v_lshlrev_b64 v[90:91], 11, v[0:1]
	v_lshl_add_u64 v[42:43], v[42:43], 0, v[90:91]
	global_load_dword v0, v[42:43], off nt
	s_and_b64 vcc, exec, s[2:3]
	s_cbranch_vccnz .LBB0_167
	global_load_dword v42, v[44:45], off offset:248 nt
	s_waitcnt vmcnt(0)
	v_mul_f32_e32 v0, v0, v42

; DI void transpose_item(const float* W, int ldn, int sc, const float* gain, bf16* WT, int K, int drow, int k0, LAS float* scr, int lane) {
;     ...
; #pragma unroll
;     for (int i = 0; i < 32; ++i) { const int kk = 2 * i + (lane >> 5); tv[i] = 0.f;
;         if (sc >= 0) { tv[i] = W[(size_t)(k0 + kk) * ldn + sc + (lane & 31)]; if (gain) tv[i] *= gain[k0 + kk]; } }
; __global__ void __launch_bounds__(512, 2) fwd_megakernel(Params P) {
;     ...
;             if (r < I4) { const int g = r % 32, kb = r / 32; transpose_item(P.w_out, 1024, 32 * g, nullptr, Wt_out, 1024, 32 * g, 64 * kb, scr, lane); continue; } r -= I4;
.LBB0_169:
	s_andn2_b64 vcc, exec, s[2:3]
	s_cbranch_vccnz .LBB0_171
	s_add_i32 s1, s45, 0xfffff0e0
	s_add_i32 s0, s5, 0xffff0e00
	s_and_b32 s1, s1, 0x7fffffc0
	s_and_b32 s0, s0, 0x3e0
	v_or_b32_e32 v0, s1, v46
	s_lshl_b32 s76, s0, 2
	v_or_b32_e32 v60, 2, v0
	v_mov_b32_e32 v61, v1
	v_or_b32_e32 v62, 4, v0
	v_mov_b32_e32 v63, v1
	v_or_b32_e32 v64, 6, v0
	v_mov_b32_e32 v65, v1
	v_or_b32_e32 v66, 8, v0
	v_mov_b32_e32 v67, v1
	v_or_b32_e32 v68, 10, v0
	v_mov_b32_e32 v69, v1
	v_or_b32_e32 v70, 12, v0
	v_mov_b32_e32 v71, v1
	v_lshl_add_u64 v[42:43], v[22:23], 0, s[76:77]
	v_lshlrev_b64 v[44:45], 12, v[0:1]
	v_lshlrev_b64 v[60:61], 12, v[60:61]
	v_lshlrev_b64 v[62:63], 12, v[62:63]
	v_lshlrev_b64 v[64:65], 12, v[64:65]
	v_lshlrev_b64 v[66:67], 12, v[66:67]
	v_lshlrev_b64 v[68:69], 12, v[68:69]
	v_lshlrev_b64 v[70:71], 12, v[70:71]
	v_or_b32_e32 v72, 14, v0
	v_mov_b32_e32 v73, v1
	v_lshl_add_u64 v[44:45], v[42:43], 0, v[44:45]
	v_lshl_add_u64 v[60:61], v[42:43], 0, v[60:61]
	v_lshl_add_u64 v[62:63], v[42:43], 0, v[62:63]
	v_lshl_add_u64 v[64:65], v[42:43], 0, v[64:65]
	v_lshl_add_u64 v[66:67], v[42:43], 0, v[66:67]
	v_lshl_add_u64 v[68:69], v[42:43], 0, v[68:69]
	v_lshl_add_u64 v[70:71], v[42:43], 0, v[70:71]
	v_lshlrev_b64 v[72:73], 12, v[72:73]
	v_lshl_add_u64 v[72:73], v[42:43], 0, v[72:73]
	global_load_dword v41, v[44:45], off nt
	global_load_dword v74, v[60:61], off nt
	global_load_dword v75, v[62:63], off nt
	global_load_dword v76, v[64:65], off nt
	global_load_dword v77, v[66:67], off nt
	global_load_dword v78, v[68:69], off nt
	global_load_dword v79, v[70:71], off nt
	global_load_dword v80, v[72:73], off nt
	v_or_b32_e32 v44, 16, v0
	v_mov_b32_e32 v45, v1
	v_or_b32_e32 v60, 18, v0
	v_mov_b32_e32 v61, v1
	v_or_b32_e32 v62, 20, v0
	v_mov_b32_e32 v63, v1
	v_or_b32_e32 v64, 22, v0
	v_mov_b32_e32 v65, v1
	v_or_b32_e32 v66, 24, v0
	v_mov_b32_e32 v67, v1
	v_or_b32_e32 v68, 26, v0
	v_mov_b32_e32 v69, v1
	v_or_b32_e32 v70, 28, v0
	v_mov_b32_e32 v71, v1
	v_lshlrev_b64 v[44:45], 12, v[44:45]
	v_lshlrev_b64 v[60:61], 12, v[60:61]
	v_lshlrev_b64 v[62:63], 12, v[62:63]
	v_lshlrev_b64 v[64:65], 12, v[64:65]
	v_lshlrev_b64 v[66:67], 12, v[66:67]
	v_lshlrev_b64 v[68:69], 12, v[68:69]
	v_lshlrev_b64 v[70:71], 12, v[70:71]
	v_or_b32_e32 v72, 30, v0
	v_mov_b32_e32 v73, v1
	v_lshl_add_u64 v[44:45], v[42:43], 0, v[44:45]
	v_lshl_add_u64 v[60:61], v[42:43], 0, v[60:61]
	v_lshl_add_u64 v[62:63], v[42:43], 0, v[62:63]
	v_lshl_add_u64 v[64:65], v[42:43], 0, v[64:65]
	v_lshl_add_u64 v[66:67], v[42:43], 0, v[66:67]
	v_lshl_add_u64 v[68:69], v[42:43], 0, v[68:69]
	v_lshl_add_u64 v[70:71], v[42:43], 0, v[70:71]
	v_lshlrev_b64 v[72:73], 12, v[72:73]
	v_lshl_add_u64 v[72:73], v[42:43], 0, v[72:73]
	global_load_dword v81, v[44:45], off nt
	global_load_dword v82, v[60:61], off nt
	global_load_dword v83, v[62:63], off nt
	global_load_dword v84, v[64:65], off nt
	global_load_dword v85, v[66:67], off nt
	global_load_dword v86, v[68:69], off nt
	global_load_dword v87, v[70:71], off nt
	global_load_dword v88, v[72:73], off nt
	v_or_b32_e32 v44, 32, v0
	v_mov_b32_e32 v45, v1
	v_or_b32_e32 v60, 34, v0
	v_mov_b32_e32 v61, v1
	v_or_b32_e32 v62, 36, v0
	v_mov_b32_e32 v63, v1
	v_or_b32_e32 v64, 38, v0
	v_mov_b32_e32 v65, v1
	v_or_b32_e32 v66, 40, v0
	v_mov_b32_e32 v67, v1
	v_or_b32_e32 v68, 42, v0
	v_mov_b32_e32 v69, v1
	v_or_b32_e32 v70, 44, v0
	v_mov_b32_e32 v71, v1
	v_lshlrev_b64 v[44:45], 12, v[44:45]
	v_lshlrev_b64 v[60:61], 12, v[60:61]
	v_lshlrev_b64 v[62:63], 12, v[62:63]
	v_lshlrev_b64 v[64:65], 12, v[64:65]
	v_lshlrev_b64 v[66:67], 12, v[66:67]
	v_lshlrev_b64 v[68:69], 12, v[68:69]
	v_lshlrev_b64 v[70:71], 12, v[70:71]
	v_or_b32_e32 v72, 46, v0
	v_mov_b32_e32 v73, v1
	v_lshl_add_u64 v[44:45], v[42:43], 0, v[44:45]
	v_lshl_add_u64 v[60:61], v[42:43], 0, v[60:61]
	v_lshl_add_u64 v[62:63], v[42:43], 0, v[62:63]
	v_lshl_add_u64 v[64:65], v[42:43], 0, v[64:65]
	v_lshl_add_u64 v[66:67], v[42:43], 0, v[66:67]
	v_lshl_add_u64 v[68:69], v[42:43], 0, v[68:69]
	v_lshl_add_u64 v[70:71], v[42:43], 0, v[70:71]
	v_lshlrev_b64 v[72:73], 12, v[72:73]
	v_lshl_add_u64 v[72:73], v[42:43], 0, v[72:73]
	global_load_dword v89, v[44:45], off nt
	global_load_dword v90, v[60:61], off nt
	global_load_dword v91, v[62:63], off nt
	global_load_dword v92, v[64:65], off nt
	global_load_dword v93, v[66:67], off nt
	global_load_dword v94, v[68:69], off nt
	global_load_dword v95, v[70:71], off nt
	global_load_dword v96, v[72:73], off nt
	v_or_b32_e32 v44, 48, v0
	v_mov_b32_e32 v45, v1
	v_or_b32_e32 v60, 50, v0
	v_mov_b32_e32 v61, v1
	v_or_b32_e32 v62, 52, v0
	v_mov_b32_e32 v63, v1
	v_or_b32_e32 v64, 54, v0
	v_mov_b32_e32 v65, v1
	v_or_b32_e32 v66, 56, v0
	v_mov_b32_e32 v67, v1
	v_or_b32_e32 v68, 58, v0
	v_mov_b32_e32 v69, v1
	v_or_b32_e32 v70, 60, v0
	v_mov_b32_e32 v71, v1
	v_or_b32_e32 v0, 62, v0
	v_lshlrev_b64 v[44:45], 12, v[44:45]
	v_lshlrev_b64 v[60:61], 12, v[60:61]
	v_lshlrev_b64 v[62:63], 12, v[62:63]
	v_lshlrev_b64 v[64:65], 12, v[64:65]
	v_lshlrev_b64 v[66:67], 12, v[66:67]
	v_lshlrev_b64 v[68:69], 12, v[68:69]
	v_lshlrev_b64 v[70:71], 12, v[70:71]
	v_lshlrev_b64 v[72:73], 12, v[0:1]
	v_lshl_add_u64 v[44:45], v[42:43], 0, v[44:45]
	v_lshl_add_u64 v[60:61], v[42:43], 0, v[60:61]
	v_lshl_add_u64 v[62:63], v[42:43], 0, v[62:63]
	v_lshl_add_u64 v[64:65], v[42:43], 0, v[64:65]
	v_lshl_add_u64 v[66:67], v[42:43], 0, v[66:67]
	v_lshl_add_u64 v[68:69], v[42:43], 0, v[68:69]
	v_lshl_add_u64 v[70:71], v[42:43], 0, v[70:71]
	v_lshl_add_u64 v[42:43], v[42:43], 0, v[72:73]
	global_load_dword v0, v[44:45], off nt
	s_nop 0
	global_load_dword v44, v[60:61], off nt
	global_load_dword v45, v[62:63], off nt
	s_nop 0
	global_load_dword v60, v[64:65], off nt
	global_load_dword v61, v[66:67], off nt
	global_load_dword v62, v[68:69], off nt
	global_load_dword v63, v[70:71], off nt
	s_nop 0
	global_load_dword v42, v[42:43], off nt
	s_waitcnt vmcnt(30)
; #define LAS __attribute__((address_space(3)))
; DI unsigned pk2(float lo, float hi) { return pg8::cvt_pk_bf16(lo, hi); }
; DI void transpose_item(const float* W, int ldn, int sc, const float* gain, bf16* WT, int K, int drow, int k0, LAS float* scr, int lane) {
;     ...
;     for (int i = 0; i < 32; ++i) scr[(2 * i + (lane >> 5)) * 33 + (lane & 31)] = tv[i];
;     asm volatile("s_waitcnt lgkmcnt(0)" ::: "memory");
;     const int c = lane & 7;
; #pragma unroll
;     for (int j = 0; j < 4; ++j) { const int n = (lane >> 3) + 8 * j; const LAS float* s = scr + (8 * c) * 33 + n;
;         u32x4 o; o.x = pk2(s[0 * 33], s[1 * 33]); o.y = pk2(s[2 * 33], s[3 * 33]); o.z = pk2(s[4 * 33], s[5 * 33]); o.w = pk2(s[6 * 33], s[7 * 33]);
;         *(u32x4*)(WT + (size_t)(drow + n) * K + k0 + 8 * c) = o; }
	ds_write2_b32 v47, v41, v74 offset1:66
	s_waitcnt vmcnt(28)
	ds_write2_b32 v47, v75, v76 offset0:132 offset1:198
	s_waitcnt vmcnt(26)
	ds_write2_b32 v53, v77, v78 offset0:8 offset1:74
	s_waitcnt vmcnt(24)
	ds_write2_b32 v53, v79, v80 offset0:140 offset1:206
	s_waitcnt vmcnt(22)
	ds_write2_b32 v54, v81, v82 offset0:16 offset1:82
	s_waitcnt vmcnt(20)
	ds_write2_b32 v54, v83, v84 offset0:148 offset1:214
	s_waitcnt vmcnt(18)
	ds_write2_b32 v55, v85, v86 offset0:24 offset1:90
	s_waitcnt vmcnt(16)
	ds_write2_b32 v55, v87, v88 offset0:156 offset1:222
	s_waitcnt vmcnt(14)
	ds_write2_b32 v56, v89, v90 offset0:32 offset1:98
	s_waitcnt vmcnt(12)
	ds_write2_b32 v56, v91, v92 offset0:164 offset1:230
	s_waitcnt vmcnt(10)
	ds_write2_b32 v57, v93, v94 offset0:40 offset1:106
	s_waitcnt vmcnt(8)
	ds_write2_b32 v57, v95, v96 offset0:172 offset1:238
	s_waitcnt vmcnt(6)
	ds_write2_b32 v58, v0, v44 offset0:48 offset1:114
	s_waitcnt vmcnt(4)
	ds_write2_b32 v58, v45, v60 offset0:180 offset1:246
	s_waitcnt vmcnt(2)
	ds_write2_b32 v59, v61, v62 offset0:56 offset1:122
	s_waitcnt vmcnt(0)
	ds_write2_b32 v59, v63, v42 offset0:188 offset1:254
	s_waitcnt lgkmcnt(0)
	ds_read2_b32 v[60:61], v49 offset0:33 offset1:41
	ds_read2_b32 v[62:63], v49 offset1:8
	ds_read2_b32 v[64:65], v49 offset0:66 offset1:74
	ds_read2_b32 v[66:67], v49 offset0:99 offset1:107
	ds_read2_b32 v[68:69], v49 offset0:132 offset1:140
	ds_read2_b32 v[70:71], v49 offset0:165 offset1:173
	ds_read2_b32 v[72:73], v49 offset0:198 offset1:206
	ds_read2_b32 v[74:75], v49 offset0:231 offset1:239
	s_lshl_b32 s76, s1, 1
	v_or_b32_e32 v0, s0, v48
	v_lshl_add_u64 v[76:77], v[24:25], 0, s[76:77]
	v_lshlrev_b32_e32 v0, 11, v0
	v_lshl_add_u64 v[78:79], v[76:77], 0, v[0:1]
	s_waitcnt lgkmcnt(6)
	v_cvt_pk_bf16_f32 v42, v62, v60
	s_waitcnt lgkmcnt(4)
	v_cvt_pk_bf16_f32 v43, v64, v66
	s_waitcnt lgkmcnt(2)
	v_cvt_pk_bf16_f32 v44, v68, v70
	s_waitcnt lgkmcnt(0)
	v_cvt_pk_bf16_f32 v45, v72, v74
	global_store_dwordx4 v[78:79], v[42:45], off
	v_or_b32_e32 v0, s0, v50
	v_lshlrev_b32_e32 v0, 11, v0
	v_cvt_pk_bf16_f32 v42, v63, v61
	v_cvt_pk_bf16_f32 v43, v65, v67
	v_cvt_pk_bf16_f32 v44, v69, v71
	v_cvt_pk_bf16_f32 v45, v73, v75
	ds_read2_b32 v[62:63], v49 offset0:16 offset1:24
	ds_read2_b32 v[64:65], v49 offset0:49 offset1:57
	ds_read2_b32 v[66:67], v49 offset0:82 offset1:90
	ds_read2_b32 v[68:69], v49 offset0:115 offset1:123
	ds_read2_b32 v[70:71], v49 offset0:148 offset1:156
	ds_read2_b32 v[72:73], v49 offset0:181 offset1:189
	ds_read2_b32 v[74:75], v49 offset0:214 offset1:222
	ds_read2_b32 v[78:79], v49 offset0:247 offset1:255
	v_lshl_add_u64 v[60:61], v[76:77], 0, v[0:1]
	v_or_b32_e32 v0, s0, v51
	v_lshlrev_b32_e32 v0, 11, v0
	global_store_dwordx4 v[60:61], v[42:45], off
	v_lshl_add_u64 v[60:61], v[76:77], 0, v[0:1]
	v_or_b32_e32 v0, s0, v52
	v_lshlrev_b32_e32 v0, 11, v0
	s_waitcnt lgkmcnt(6)
	v_cvt_pk_bf16_f32 v42, v62, v64
	s_waitcnt lgkmcnt(4)
	v_cvt_pk_bf16_f32 v43, v66, v68
	s_waitcnt lgkmcnt(2)
	v_cvt_pk_bf16_f32 v44, v70, v72
	s_waitcnt lgkmcnt(0)
	v_cvt_pk_bf16_f32 v45, v74, v78
	global_store_dwordx4 v[60:61], v[42:45], off
	v_lshl_add_u64 v[60:61], v[76:77], 0, v[0:1]
	s_nop 0
	v_cvt_pk_bf16_f32 v42, v63, v65
	v_cvt_pk_bf16_f32 v43, v67, v69
	v_cvt_pk_bf16_f32 v44, v71, v73
	v_cvt_pk_bf16_f32 v45, v75, v79
	global_store_dwordx4 v[60:61], v[42:45], off
	s_waitcnt lgkmcnt(0)

; DI void transpose_item(const float* W, int ldn, int sc, const float* gain, bf16* WT, int K, int drow, int k0, LAS float* scr, int lane) {
;     ...
;     for (int i = 0; i < 32; ++i) { const int kk = 2 * i + (lane >> 5); tv[i] = 0.f;
;         if (sc >= 0) { tv[i] = W[(size_t)(k0 + kk) * ldn + sc + (lane & 31)]; if (gain) tv[i] *= gain[k0 + kk]; } }
; __global__ void __launch_bounds__(512, 2) fwd_megakernel(Params P) {
;     ...
;             if (r < I3) { const int g = r % 32, kb = r / 32; transpose_item(P.w_kv_up, 1024, 32 * g, P.kv_norm, Wt_kv, 256, 32 * g, 64 * kb, scr, lane); continue; } r -= I3;
.LBB0_172:
	s_andn2_b64 vcc, exec, s[2:3]
	s_cbranch_vccnz .LBB0_238
	s_add_i32 s0, s5, 0xffff1e00
	s_add_i32 s1, s45, 0xfffff1e0
	s_and_b32 s0, s0, 0x3e0
	s_and_b32 s1, s1, 0x7fffffc0
	v_or_b32_e32 v0, s1, v46
	s_lshl_b32 s76, s0, 2
	v_lshl_add_u64 v[42:43], v[26:27], 0, s[76:77]
	v_lshlrev_b64 v[44:45], 12, v[0:1]
	v_lshl_add_u64 v[44:45], v[42:43], 0, v[44:45]
	global_load_dword v41, v[44:45], off nt
	v_cndmask_b32_e64 v44, 0, 1, s[72:73]
	v_cmp_ne_u32_e64 s[2:3], 1, v44
	s_andn2_b64 vcc, exec, s[72:73]
	v_lshl_add_u64 v[44:45], v[0:1], 2, s[50:51]
	s_cbranch_vccnz .LBB0_175
	global_load_dword v60, v[44:45], off nt
	s_waitcnt vmcnt(0)
	v_mul_f32_e32 v41, v41, v60
.LBB0_175:
	v_or_b32_e32 v60, 2, v0
	v_mov_b32_e32 v61, v1
	v_lshlrev_b64 v[60:61], 12, v[60:61]
	v_lshl_add_u64 v[60:61], v[42:43], 0, v[60:61]
	global_load_dword v60, v[60:61], off nt
	s_and_b64 vcc, exec, s[2:3]
	s_cbranch_vccnz .LBB0_177
	global_load_dword v61, v[44:45], off offset:8 nt
	s_waitcnt vmcnt(0)
	v_mul_f32_e32 v60, v60, v61
.LBB0_177:
	v_or_b32_e32 v62, 4, v0
	v_mov_b32_e32 v63, v1
	v_lshlrev_b64 v[62:63], 12, v[62:63]
	v_lshl_add_u64 v[62:63], v[42:43], 0, v[62:63]
	global_load_dword v61, v[62:63], off nt
	s_and_b64 vcc, exec, s[2:3]
	s_cbranch_vccnz .LBB0_179
	global_load_dword v62, v[44:45], off offset:16 nt
	s_waitcnt vmcnt(0)
	v_mul_f32_e32 v61, v61, v62
.LBB0_179:
	v_or_b32_e32 v62, 6, v0
	v_mov_b32_e32 v63, v1
	v_lshlrev_b64 v[62:63], 12, v[62:63]
	v_lshl_add_u64 v[62:63], v[42:43], 0, v[62:63]
	global_load_dword v62, v[62:63], off nt
	s_and_b64 vcc, exec, s[2:3]
	s_cbranch_vccnz .LBB0_181
	global_load_dword v63, v[44:45], off offset:24 nt
	s_waitcnt vmcnt(0)
	v_mul_f32_e32 v62, v62, v63
.LBB0_181:
	v_or_b32_e32 v64, 8, v0
	v_mov_b32_e32 v65, v1
	v_lshlrev_b64 v[64:65], 12, v[64:65]
	v_lshl_add_u64 v[64:65], v[42:43], 0, v[64:65]
	global_load_dword v63, v[64:65], off nt
	s_and_b64 vcc, exec, s[2:3]
	s_cbranch_vccnz .LBB0_183
	global_load_dword v64, v[44:45], off offset:32 nt
	s_waitcnt vmcnt(0)
	v_mul_f32_e32 v63, v63, v64
.LBB0_183:
	v_or_b32_e32 v64, 10, v0
	v_mov_b32_e32 v65, v1
	v_lshlrev_b64 v[64:65], 12, v[64:65]
	v_lshl_add_u64 v[64:65], v[42:43], 0, v[64:65]
	global_load_dword v64, v[64:65], off nt
	s_and_b64 vcc, exec, s[2:3]
	s_cbranch_vccnz .LBB0_185
	global_load_dword v65, v[44:45], off offset:40 nt
	s_waitcnt vmcnt(0)
	v_mul_f32_e32 v64, v64, v65
.LBB0_185:
	v_or_b32_e32 v66, 12, v0
	v_mov_b32_e32 v67, v1
	v_lshlrev_b64 v[66:67], 12, v[66:67]
	v_lshl_add_u64 v[66:67], v[42:43], 0, v[66:67]
	global_load_dword v65, v[66:67], off nt
	s_and_b64 vcc, exec, s[2:3]
	s_cbranch_vccnz .LBB0_187
	global_load_dword v66, v[44:45], off offset:48 nt
	s_waitcnt vmcnt(0)
	v_mul_f32_e32 v65, v65, v66
.LBB0_187:
	v_or_b32_e32 v66, 14, v0
	v_mov_b32_e32 v67, v1
	v_lshlrev_b64 v[66:67], 12, v[66:67]
	v_lshl_add_u64 v[66:67], v[42:43], 0, v[66:67]
	global_load_dword v66, v[66:67], off nt
	s_and_b64 vcc, exec, s[2:3]
	s_cbranch_vccnz .LBB0_189
	global_load_dword v67, v[44:45], off offset:56 nt
	s_waitcnt vmcnt(0)
	v_mul_f32_e32 v66, v66, v67
.LBB0_189:
	v_or_b32_e32 v68, 16, v0
	v_mov_b32_e32 v69, v1
	v_lshlrev_b64 v[68:69], 12, v[68:69]
	v_lshl_add_u64 v[68:69], v[42:43], 0, v[68:69]
	global_load_dword v67, v[68:69], off nt
	s_and_b64 vcc, exec, s[2:3]
	s_cbranch_vccnz .LBB0_191
	global_load_dword v68, v[44:45], off offset:64 nt
	s_waitcnt vmcnt(0)
	v_mul_f32_e32 v67, v67, v68
.LBB0_191:
	v_or_b32_e32 v68, 18, v0
	v_mov_b32_e32 v69, v1
	v_lshlrev_b64 v[68:69], 12, v[68:69]
	v_lshl_add_u64 v[68:69], v[42:43], 0, v[68:69]
	global_load_dword v68, v[68:69], off nt
	s_and_b64 vcc, exec, s[2:3]
	s_cbranch_vccnz .LBB0_193
	global_load_dword v69, v[44:45], off offset:72 nt
	s_waitcnt vmcnt(0)
	v_mul_f32_e32 v68, v68, v69
.LBB0_193:
	v_or_b32_e32 v70, 20, v0
	v_mov_b32_e32 v71, v1
	v_lshlrev_b64 v[70:71], 12, v[70:71]
	v_lshl_add_u64 v[70:71], v[42:43], 0, v[70:71]
	global_load_dword v69, v[70:71], off nt
	s_and_b64 vcc, exec, s[2:3]
	s_cbranch_vccnz .LBB0_195
	global_load_dword v70, v[44:45], off offset:80 nt
	s_waitcnt vmcnt(0)
	v_mul_f32_e32 v69, v69, v70
.LBB0_195:
	v_or_b32_e32 v70, 22, v0
	v_mov_b32_e32 v71, v1
	v_lshlrev_b64 v[70:71], 12, v[70:71]
	v_lshl_add_u64 v[70:71], v[42:43], 0, v[70:71]
	global_load_dword v70, v[70:71], off nt
	s_and_b64 vcc, exec, s[2:3]
	s_cbranch_vccnz .LBB0_197
	global_load_dword v71, v[44:45], off offset:88 nt
	s_waitcnt vmcnt(0)
	v_mul_f32_e32 v70, v70, v71
.LBB0_197:
	v_or_b32_e32 v72, 24, v0
	v_mov_b32_e32 v73, v1
	v_lshlrev_b64 v[72:73], 12, v[72:73]
	v_lshl_add_u64 v[72:73], v[42:43], 0, v[72:73]
	global_load_dword v71, v[72:73], off nt
	s_and_b64 vcc, exec, s[2:3]
	s_cbranch_vccnz .LBB0_199
	global_load_dword v72, v[44:45], off offset:96 nt
	s_waitcnt vmcnt(0)
	v_mul_f32_e32 v71, v71, v72
.LBB0_199:
	v_or_b32_e32 v72, 26, v0
	v_mov_b32_e32 v73, v1
	v_lshlrev_b64 v[72:73], 12, v[72:73]
	v_lshl_add_u64 v[72:73], v[42:43], 0, v[72:73]
	global_load_dword v72, v[72:73], off nt
	s_and_b64 vcc, exec, s[2:3]
	s_cbranch_vccnz .LBB0_201
	global_load_dword v73, v[44:45], off offset:104 nt
	s_waitcnt vmcnt(0)
	v_mul_f32_e32 v72, v72, v73
.LBB0_201:
	v_or_b32_e32 v74, 28, v0
	v_mov_b32_e32 v75, v1
	v_lshlrev_b64 v[74:75], 12, v[74:75]
	v_lshl_add_u64 v[74:75], v[42:43], 0, v[74:75]
	global_load_dword v73, v[74:75], off nt
	s_and_b64 vcc, exec, s[2:3]
	s_cbranch_vccnz .LBB0_203
	global_load_dword v74, v[44:45], off offset:112 nt
	s_waitcnt vmcnt(0)
	v_mul_f32_e32 v73, v73, v74
; DI void transpose_item(const float* W, int ldn, int sc, const float* gain, bf16* WT, int K, int drow, int k0, LAS float* scr, int lane) {
;     ...
;     for (int i = 0; i < 32; ++i) { const int kk = 2 * i + (lane >> 5); tv[i] = 0.f;
;         if (sc >= 0) { tv[i] = W[(size_t)(k0 + kk) * ldn + sc + (lane & 31)]; if (gain) tv[i] *= gain[k0 + kk]; } }
; __global__ void __launch_bounds__(512, 2) fwd_megakernel(Params P) {
;     ...
;             if (r < I3) { const int g = r % 32, kb = r / 32; transpose_item(P.w_kv_up, 1024, 32 * g, P.kv_norm, Wt_kv, 256, 32 * g, 64 * kb, scr, lane); continue; } r -= I3;
.LBB0_203:
	v_or_b32_e32 v74, 30, v0
	v_mov_b32_e32 v75, v1
	v_lshlrev_b64 v[74:75], 12, v[74:75]
	v_lshl_add_u64 v[74:75], v[42:43], 0, v[74:75]
	global_load_dword v74, v[74:75], off nt
	s_and_b64 vcc, exec, s[2:3]
	s_cbranch_vccnz .LBB0_205
	global_load_dword v75, v[44:45], off offset:120 nt
	s_waitcnt vmcnt(0)
	v_mul_f32_e32 v74, v74, v75
.LBB0_205:
	v_or_b32_e32 v76, 32, v0
	v_mov_b32_e32 v77, v1
	v_lshlrev_b64 v[76:77], 12, v[76:77]
	v_lshl_add_u64 v[76:77], v[42:43], 0, v[76:77]
	global_load_dword v75, v[76:77], off nt
	s_and_b64 vcc, exec, s[2:3]
	s_cbranch_vccnz .LBB0_207
	global_load_dword v76, v[44:45], off offset:128 nt
	s_waitcnt vmcnt(0)
	v_mul_f32_e32 v75, v75, v76
.LBB0_207:
	v_or_b32_e32 v76, 34, v0
	v_mov_b32_e32 v77, v1
	v_lshlrev_b64 v[76:77], 12, v[76:77]
	v_lshl_add_u64 v[76:77], v[42:43], 0, v[76:77]
	global_load_dword v76, v[76:77], off nt
	s_and_b64 vcc, exec, s[2:3]
	s_cbranch_vccnz .LBB0_209
	global_load_dword v77, v[44:45], off offset:136 nt
	s_waitcnt vmcnt(0)
	v_mul_f32_e32 v76, v76, v77
.LBB0_209:
	v_or_b32_e32 v78, 36, v0
	v_mov_b32_e32 v79, v1
	v_lshlrev_b64 v[78:79], 12, v[78:79]
	v_lshl_add_u64 v[78:79], v[42:43], 0, v[78:79]
	global_load_dword v77, v[78:79], off nt
	s_and_b64 vcc, exec, s[2:3]
	s_cbranch_vccnz .LBB0_211
	global_load_dword v78, v[44:45], off offset:144 nt
	s_waitcnt vmcnt(0)
	v_mul_f32_e32 v77, v77, v78
.LBB0_211:
	v_or_b32_e32 v78, 38, v0
	v_mov_b32_e32 v79, v1
	v_lshlrev_b64 v[78:79], 12, v[78:79]
	v_lshl_add_u64 v[78:79], v[42:43], 0, v[78:79]
	global_load_dword v78, v[78:79], off nt
	s_and_b64 vcc, exec, s[2:3]
	s_cbranch_vccnz .LBB0_213
	global_load_dword v79, v[44:45], off offset:152 nt
	s_waitcnt vmcnt(0)
	v_mul_f32_e32 v78, v78, v79
.LBB0_213:
	v_or_b32_e32 v80, 40, v0
	v_mov_b32_e32 v81, v1
	v_lshlrev_b64 v[80:81], 12, v[80:81]
	v_lshl_add_u64 v[80:81], v[42:43], 0, v[80:81]
	global_load_dword v79, v[80:81], off nt
	s_and_b64 vcc, exec, s[2:3]
	s_cbranch_vccnz .LBB0_215
	global_load_dword v80, v[44:45], off offset:160 nt
	s_waitcnt vmcnt(0)
	v_mul_f32_e32 v79, v79, v80
.LBB0_215:
	v_or_b32_e32 v80, 42, v0
	v_mov_b32_e32 v81, v1
	v_lshlrev_b64 v[80:81], 12, v[80:81]
	v_lshl_add_u64 v[80:81], v[42:43], 0, v[80:81]
	global_load_dword v80, v[80:81], off nt
	s_and_b64 vcc, exec, s[2:3]
	s_cbranch_vccnz .LBB0_217
	global_load_dword v81, v[44:45], off offset:168 nt
	s_waitcnt vmcnt(0)
	v_mul_f32_e32 v80, v80, v81
.LBB0_217:
	v_or_b32_e32 v82, 44, v0
	v_mov_b32_e32 v83, v1
	v_lshlrev_b64 v[82:83], 12, v[82:83]
	v_lshl_add_u64 v[82:83], v[42:43], 0, v[82:83]
	global_load_dword v81, v[82:83], off nt
	s_and_b64 vcc, exec, s[2:3]
	s_cbranch_vccnz .LBB0_219
	global_load_dword v82, v[44:45], off offset:176 nt
	s_waitcnt vmcnt(0)
	v_mul_f32_e32 v81, v81, v82
.LBB0_219:
	v_or_b32_e32 v82, 46, v0
	v_mov_b32_e32 v83, v1
	v_lshlrev_b64 v[82:83], 12, v[82:83]
	v_lshl_add_u64 v[82:83], v[42:43], 0, v[82:83]
	global_load_dword v82, v[82:83], off nt
	s_and_b64 vcc, exec, s[2:3]
	s_cbranch_vccnz .LBB0_221
	global_load_dword v83, v[44:45], off offset:184 nt
	s_waitcnt vmcnt(0)
	v_mul_f32_e32 v82, v82, v83
.LBB0_221:
	v_or_b32_e32 v84, 48, v0
	v_mov_b32_e32 v85, v1
	v_lshlrev_b64 v[84:85], 12, v[84:85]
	v_lshl_add_u64 v[84:85], v[42:43], 0, v[84:85]
	global_load_dword v83, v[84:85], off nt
	s_and_b64 vcc, exec, s[2:3]
	s_cbranch_vccnz .LBB0_223
	global_load_dword v84, v[44:45], off offset:192 nt
	s_waitcnt vmcnt(0)
	v_mul_f32_e32 v83, v83, v84
.LBB0_223:
	v_or_b32_e32 v84, 50, v0
	v_mov_b32_e32 v85, v1
	v_lshlrev_b64 v[84:85], 12, v[84:85]
	v_lshl_add_u64 v[84:85], v[42:43], 0, v[84:85]
	global_load_dword v84, v[84:85], off nt
	s_and_b64 vcc, exec, s[2:3]
	s_cbranch_vccnz .LBB0_225
	global_load_dword v85, v[44:45], off offset:200 nt
	s_waitcnt vmcnt(0)
	v_mul_f32_e32 v84, v84, v85
.LBB0_225:
	v_or_b32_e32 v86, 52, v0
	v_mov_b32_e32 v87, v1
	v_lshlrev_b64 v[86:87], 12, v[86:87]
	v_lshl_add_u64 v[86:87], v[42:43], 0, v[86:87]
	global_load_dword v85, v[86:87], off nt
	s_and_b64 vcc, exec, s[2:3]
	s_cbranch_vccnz .LBB0_227
	global_load_dword v86, v[44:45], off offset:208 nt
	s_waitcnt vmcnt(0)
	v_mul_f32_e32 v85, v85, v86
.LBB0_227:
	v_or_b32_e32 v86, 54, v0
	v_mov_b32_e32 v87, v1
	v_lshlrev_b64 v[86:87], 12, v[86:87]
	v_lshl_add_u64 v[86:87], v[42:43], 0, v[86:87]
	global_load_dword v86, v[86:87], off nt
	s_and_b64 vcc, exec, s[2:3]
	s_cbranch_vccnz .LBB0_229
	global_load_dword v87, v[44:45], off offset:216 nt
	s_waitcnt vmcnt(0)
	v_mul_f32_e32 v86, v86, v87
.LBB0_229:
	v_or_b32_e32 v88, 56, v0
	v_mov_b32_e32 v89, v1
	v_lshlrev_b64 v[88:89], 12, v[88:89]
	v_lshl_add_u64 v[88:89], v[42:43], 0, v[88:89]
	global_load_dword v87, v[88:89], off nt
	s_and_b64 vcc, exec, s[2:3]
	s_cbranch_vccnz .LBB0_231
	global_load_dword v88, v[44:45], off offset:224 nt
	s_waitcnt vmcnt(0)
	v_mul_f32_e32 v87, v87, v88
.LBB0_231:
	v_or_b32_e32 v88, 58, v0
	v_mov_b32_e32 v89, v1
	v_lshlrev_b64 v[88:89], 12, v[88:89]
	v_lshl_add_u64 v[88:89], v[42:43], 0, v[88:89]
	global_load_dword v88, v[88:89], off nt
	s_and_b64 vcc, exec, s[2:3]
	s_cbranch_vccnz .LBB0_233
	global_load_dword v89, v[44:45], off offset:232 nt
	s_waitcnt vmcnt(0)
	v_mul_f32_e32 v88, v88, v89
.LBB0_233:
	v_or_b32_e32 v90, 60, v0
	v_mov_b32_e32 v91, v1
	v_lshlrev_b64 v[90:91], 12, v[90:91]
	v_lshl_add_u64 v[90:91], v[42:43], 0, v[90:91]
	global_load_dword v89, v[90:91], off nt
	s_and_b64 vcc, exec, s[2:3]
	s_cbranch_vccnz .LBB0_235
	global_load_dword v90, v[44:45], off offset:240 nt
	s_waitcnt vmcnt(0)
	v_mul_f32_e32 v89, v89, v90
.LBB0_235:
	v_or_b32_e32 v0, 62, v0
	v_lshlrev_b64 v[90:91], 12, v[0:1]
	v_lshl_add_u64 v[42:43], v[42:43], 0, v[90:91]
	global_load_dword v0, v[42:43], off nt
	s_and_b64 vcc, exec, s[2:3]
	s_cbranch_vccnz .LBB0_237
	global_load_dword v42, v[44:45], off offset:248 nt
	s_waitcnt vmcnt(0)
	v_mul_f32_e32 v0, v0, v42

; DI void transpose_item(const float* W, int ldn, int sc, const float* gain, bf16* WT, int K, int drow, int k0, LAS float* scr, int lane) {
;     ...
;     for (int i = 0; i < 32; ++i) { const int kk = 2 * i + (lane >> 5); tv[i] = 0.f;
;         if (sc >= 0) { tv[i] = W[(size_t)(k0 + kk) * ldn + sc + (lane & 31)]; if (gain) tv[i] *= gain[k0 + kk]; } }
; __global__ void __launch_bounds__(512, 2) fwd_megakernel(Params P) {
;     ...
;             if (r < I2) { const int g = r % 24, kb = r / 24; transpose_item(P.w_q_up, 768, 32 * g, P.q_norm, Wt_q, 384, 32 * g, 64 * kb, scr, lane); continue; } r -= I2;
.LBB0_239:
	s_andn2_b64 vcc, exec, s[2:3]
	s_cbranch_vccnz .LBB0_305
	s_xor_b32 s0, s64, 0xff80
	s_and_b32 s1, s0, 0xff
	s_mulk_i32 s1, 0xab
	s_bfe_u32 s2, s1, 0x4000c
	s_mul_i32 s1, s2, 24
	s_sub_i32 s0, s0, s1
	s_and_b32 s1, s0, 0xff
	s_lshl_b32 s0, s2, 6
	s_lshl_b32 s76, s1, 7
	v_or_b32_e32 v41, s0, v46
	v_lshl_add_u64 v[42:43], v[30:31], 0, s[76:77]
	v_mad_u64_u32 v[44:45], s[2:3], v41, s58, v[42:43]
	global_load_dword v0, v[44:45], off nt
	v_cndmask_b32_e64 v44, 0, 1, s[74:75]
	v_cmp_ne_u32_e64 s[2:3], 1, v44
	s_andn2_b64 vcc, exec, s[74:75]
	v_lshlrev_b32_e32 v44, 2, v41
	s_cbranch_vccnz .LBB0_242
	global_load_dword v45, v44, s[46:47] nt
	s_waitcnt vmcnt(0)
	v_mul_f32_e32 v0, v0, v45
.LBB0_242:
	v_or_b32_e32 v45, 2, v41
	v_mad_u64_u32 v[60:61], s[10:11], v45, s58, v[42:43]
	global_load_dword v45, v[60:61], off nt
	s_and_b64 vcc, exec, s[2:3]
	s_cbranch_vccnz .LBB0_244
	global_load_dword v60, v44, s[46:47] offset:8 nt
	s_waitcnt vmcnt(0)
	v_mul_f32_e32 v45, v45, v60
.LBB0_244:
	v_or_b32_e32 v60, 4, v41
	v_mad_u64_u32 v[60:61], s[10:11], v60, s58, v[42:43]
	global_load_dword v60, v[60:61], off nt
	s_and_b64 vcc, exec, s[2:3]
	s_cbranch_vccnz .LBB0_246
	global_load_dword v61, v44, s[46:47] offset:16 nt
	s_waitcnt vmcnt(0)
	v_mul_f32_e32 v60, v60, v61
.LBB0_246:
	v_or_b32_e32 v61, 6, v41
	v_mad_u64_u32 v[62:63], s[10:11], v61, s58, v[42:43]
	global_load_dword v61, v[62:63], off nt
	s_and_b64 vcc, exec, s[2:3]
	s_cbranch_vccnz .LBB0_248
	global_load_dword v62, v44, s[46:47] offset:24 nt
	s_waitcnt vmcnt(0)
	v_mul_f32_e32 v61, v61, v62
.LBB0_248:
	v_or_b32_e32 v62, 8, v41
	v_mad_u64_u32 v[62:63], s[10:11], v62, s58, v[42:43]
	global_load_dword v62, v[62:63], off nt
	s_and_b64 vcc, exec, s[2:3]
	s_cbranch_vccnz .LBB0_250
	global_load_dword v63, v44, s[46:47] offset:32 nt
	s_waitcnt vmcnt(0)
	v_mul_f32_e32 v62, v62, v63
.LBB0_250:
	v_or_b32_e32 v63, 10, v41
	v_mad_u64_u32 v[64:65], s[10:11], v63, s58, v[42:43]
	global_load_dword v63, v[64:65], off nt
	s_and_b64 vcc, exec, s[2:3]
	s_cbranch_vccnz .LBB0_252
	global_load_dword v64, v44, s[46:47] offset:40 nt
	s_waitcnt vmcnt(0)
	v_mul_f32_e32 v63, v63, v64
.LBB0_252:
	v_or_b32_e32 v64, 12, v41
	v_mad_u64_u32 v[64:65], s[10:11], v64, s58, v[42:43]
	global_load_dword v64, v[64:65], off nt
	s_and_b64 vcc, exec, s[2:3]
	s_cbranch_vccnz .LBB0_254
	global_load_dword v65, v44, s[46:47] offset:48 nt
	s_waitcnt vmcnt(0)
	v_mul_f32_e32 v64, v64, v65
.LBB0_254:
	v_or_b32_e32 v65, 14, v41
	v_mad_u64_u32 v[66:67], s[10:11], v65, s58, v[42:43]
	global_load_dword v65, v[66:67], off nt
	s_and_b64 vcc, exec, s[2:3]
	s_cbranch_vccnz .LBB0_256
	global_load_dword v66, v44, s[46:47] offset:56 nt
	s_waitcnt vmcnt(0)
	v_mul_f32_e32 v65, v65, v66
.LBB0_256:
	v_or_b32_e32 v66, 16, v41
	v_mad_u64_u32 v[66:67], s[10:11], v66, s58, v[42:43]
	global_load_dword v66, v[66:67], off nt
	s_and_b64 vcc, exec, s[2:3]
	s_cbranch_vccnz .LBB0_258
	global_load_dword v67, v44, s[46:47] offset:64 nt
	s_waitcnt vmcnt(0)
	v_mul_f32_e32 v66, v66, v67
.LBB0_258:
	v_or_b32_e32 v67, 18, v41
	v_mad_u64_u32 v[68:69], s[10:11], v67, s58, v[42:43]
	global_load_dword v67, v[68:69], off nt
	s_and_b64 vcc, exec, s[2:3]
	s_cbranch_vccnz .LBB0_260
	global_load_dword v68, v44, s[46:47] offset:72 nt
	s_waitcnt vmcnt(0)
	v_mul_f32_e32 v67, v67, v68
.LBB0_260:
	v_or_b32_e32 v68, 20, v41
	v_mad_u64_u32 v[68:69], s[10:11], v68, s58, v[42:43]
	global_load_dword v68, v[68:69], off nt
	s_and_b64 vcc, exec, s[2:3]
	s_cbranch_vccnz .LBB0_262
	global_load_dword v69, v44, s[46:47] offset:80 nt
	s_waitcnt vmcnt(0)
	v_mul_f32_e32 v68, v68, v69
.LBB0_262:
	v_or_b32_e32 v69, 22, v41
	v_mad_u64_u32 v[70:71], s[10:11], v69, s58, v[42:43]
	global_load_dword v69, v[70:71], off nt
	s_and_b64 vcc, exec, s[2:3]
	s_cbranch_vccnz .LBB0_264
	global_load_dword v70, v44, s[46:47] offset:88 nt
	s_waitcnt vmcnt(0)
	v_mul_f32_e32 v69, v69, v70
.LBB0_264:
	v_or_b32_e32 v70, 24, v41
	v_mad_u64_u32 v[70:71], s[10:11], v70, s58, v[42:43]
	global_load_dword v70, v[70:71], off nt
	s_and_b64 vcc, exec, s[2:3]
	s_cbranch_vccnz .LBB0_266
	global_load_dword v71, v44, s[46:47] offset:96 nt
	s_waitcnt vmcnt(0)
	v_mul_f32_e32 v70, v70, v71
.LBB0_266:
	v_or_b32_e32 v71, 26, v41
	v_mad_u64_u32 v[72:73], s[10:11], v71, s58, v[42:43]
	global_load_dword v71, v[72:73], off nt
	s_and_b64 vcc, exec, s[2:3]
	s_cbranch_vccnz .LBB0_268
	global_load_dword v72, v44, s[46:47] offset:104 nt
	s_waitcnt vmcnt(0)
	v_mul_f32_e32 v71, v71, v72
.LBB0_268:
	v_or_b32_e32 v72, 28, v41
	v_mad_u64_u32 v[72:73], s[10:11], v72, s58, v[42:43]
	global_load_dword v72, v[72:73], off nt
	s_and_b64 vcc, exec, s[2:3]
	s_cbranch_vccnz .LBB0_270
	global_load_dword v73, v44, s[46:47] offset:112 nt
	s_waitcnt vmcnt(0)
	v_mul_f32_e32 v72, v72, v73
; DI void transpose_item(const float* W, int ldn, int sc, const float* gain, bf16* WT, int K, int drow, int k0, LAS float* scr, int lane) {
;     ...
;     for (int i = 0; i < 32; ++i) { const int kk = 2 * i + (lane >> 5); tv[i] = 0.f;
;         if (sc >= 0) { tv[i] = W[(size_t)(k0 + kk) * ldn + sc + (lane & 31)]; if (gain) tv[i] *= gain[k0 + kk]; } }
; __global__ void __launch_bounds__(512, 2) fwd_megakernel(Params P) {
;     ...
;             if (r < I2) { const int g = r % 24, kb = r / 24; transpose_item(P.w_q_up, 768, 32 * g, P.q_norm, Wt_q, 384, 32 * g, 64 * kb, scr, lane); continue; } r -= I2;
.LBB0_270:
	v_or_b32_e32 v73, 30, v41
	v_mad_u64_u32 v[74:75], s[10:11], v73, s58, v[42:43]
	global_load_dword v73, v[74:75], off nt
	s_and_b64 vcc, exec, s[2:3]
	s_cbranch_vccnz .LBB0_272
	global_load_dword v74, v44, s[46:47] offset:120 nt
	s_waitcnt vmcnt(0)
	v_mul_f32_e32 v73, v73, v74
.LBB0_272:
	v_or_b32_e32 v74, 32, v41
	v_mad_u64_u32 v[74:75], s[10:11], v74, s58, v[42:43]
	global_load_dword v74, v[74:75], off nt
	s_and_b64 vcc, exec, s[2:3]
	s_cbranch_vccnz .LBB0_274
	global_load_dword v75, v44, s[46:47] offset:128 nt
	s_waitcnt vmcnt(0)
	v_mul_f32_e32 v74, v74, v75
.LBB0_274:
	v_or_b32_e32 v75, 34, v41
	v_mad_u64_u32 v[76:77], s[10:11], v75, s58, v[42:43]
	global_load_dword v75, v[76:77], off nt
	s_and_b64 vcc, exec, s[2:3]
	s_cbranch_vccnz .LBB0_276
	global_load_dword v76, v44, s[46:47] offset:136 nt
	s_waitcnt vmcnt(0)
	v_mul_f32_e32 v75, v75, v76
.LBB0_276:
	v_or_b32_e32 v76, 36, v41
	v_mad_u64_u32 v[76:77], s[10:11], v76, s58, v[42:43]
	global_load_dword v76, v[76:77], off nt
	s_and_b64 vcc, exec, s[2:3]
	s_cbranch_vccnz .LBB0_278
	global_load_dword v77, v44, s[46:47] offset:144 nt
	s_waitcnt vmcnt(0)
	v_mul_f32_e32 v76, v76, v77
.LBB0_278:
	v_or_b32_e32 v77, 38, v41
	v_mad_u64_u32 v[78:79], s[10:11], v77, s58, v[42:43]
	global_load_dword v77, v[78:79], off nt
	s_and_b64 vcc, exec, s[2:3]
	s_cbranch_vccnz .LBB0_280
	global_load_dword v78, v44, s[46:47] offset:152 nt
	s_waitcnt vmcnt(0)
	v_mul_f32_e32 v77, v77, v78
.LBB0_280:
	v_or_b32_e32 v78, 40, v41
	v_mad_u64_u32 v[78:79], s[10:11], v78, s58, v[42:43]
	global_load_dword v78, v[78:79], off nt
	s_and_b64 vcc, exec, s[2:3]
	s_cbranch_vccnz .LBB0_282
	global_load_dword v79, v44, s[46:47] offset:160 nt
	s_waitcnt vmcnt(0)
	v_mul_f32_e32 v78, v78, v79
.LBB0_282:
	v_or_b32_e32 v79, 42, v41
	v_mad_u64_u32 v[80:81], s[10:11], v79, s58, v[42:43]
	global_load_dword v79, v[80:81], off nt
	s_and_b64 vcc, exec, s[2:3]
	s_cbranch_vccnz .LBB0_284
	global_load_dword v80, v44, s[46:47] offset:168 nt
	s_waitcnt vmcnt(0)
	v_mul_f32_e32 v79, v79, v80
.LBB0_284:
	v_or_b32_e32 v80, 44, v41
	v_mad_u64_u32 v[80:81], s[10:11], v80, s58, v[42:43]
	global_load_dword v80, v[80:81], off nt
	s_and_b64 vcc, exec, s[2:3]
	s_cbranch_vccnz .LBB0_286
	global_load_dword v81, v44, s[46:47] offset:176 nt
	s_waitcnt vmcnt(0)
	v_mul_f32_e32 v80, v80, v81
.LBB0_286:
	v_or_b32_e32 v81, 46, v41
	v_mad_u64_u32 v[82:83], s[10:11], v81, s58, v[42:43]
	global_load_dword v81, v[82:83], off nt
	s_and_b64 vcc, exec, s[2:3]
	s_cbranch_vccnz .LBB0_288
	global_load_dword v82, v44, s[46:47] offset:184 nt
	s_waitcnt vmcnt(0)
	v_mul_f32_e32 v81, v81, v82
.LBB0_288:
	v_or_b32_e32 v82, 48, v41
	v_mad_u64_u32 v[82:83], s[10:11], v82, s58, v[42:43]
	global_load_dword v82, v[82:83], off nt
	s_and_b64 vcc, exec, s[2:3]
	s_cbranch_vccnz .LBB0_290
	global_load_dword v83, v44, s[46:47] offset:192 nt
	s_waitcnt vmcnt(0)
	v_mul_f32_e32 v82, v82, v83
.LBB0_290:
	v_or_b32_e32 v83, 50, v41
	v_mad_u64_u32 v[84:85], s[10:11], v83, s58, v[42:43]
	global_load_dword v83, v[84:85], off nt
	s_and_b64 vcc, exec, s[2:3]
	s_cbranch_vccnz .LBB0_292
	global_load_dword v84, v44, s[46:47] offset:200 nt
	s_waitcnt vmcnt(0)
	v_mul_f32_e32 v83, v83, v84
.LBB0_292:
	v_or_b32_e32 v84, 52, v41
	v_mad_u64_u32 v[84:85], s[10:11], v84, s58, v[42:43]
	global_load_dword v84, v[84:85], off nt
	s_and_b64 vcc, exec, s[2:3]
	s_cbranch_vccnz .LBB0_294
	global_load_dword v85, v44, s[46:47] offset:208 nt
	s_waitcnt vmcnt(0)
	v_mul_f32_e32 v84, v84, v85
.LBB0_294:
	v_or_b32_e32 v85, 54, v41
	v_mad_u64_u32 v[86:87], s[10:11], v85, s58, v[42:43]
	global_load_dword v85, v[86:87], off nt
	s_and_b64 vcc, exec, s[2:3]
	s_cbranch_vccnz .LBB0_296
	global_load_dword v86, v44, s[46:47] offset:216 nt
	s_waitcnt vmcnt(0)
	v_mul_f32_e32 v85, v85, v86
.LBB0_296:
	v_or_b32_e32 v86, 56, v41
	v_mad_u64_u32 v[86:87], s[10:11], v86, s58, v[42:43]
	global_load_dword v86, v[86:87], off nt
	s_and_b64 vcc, exec, s[2:3]
	s_cbranch_vccnz .LBB0_298
	global_load_dword v87, v44, s[46:47] offset:224 nt
	s_waitcnt vmcnt(0)
	v_mul_f32_e32 v86, v86, v87
.LBB0_298:
	v_or_b32_e32 v87, 58, v41
	v_mad_u64_u32 v[88:89], s[10:11], v87, s58, v[42:43]
	global_load_dword v87, v[88:89], off nt
	s_and_b64 vcc, exec, s[2:3]
	s_cbranch_vccnz .LBB0_300
	global_load_dword v88, v44, s[46:47] offset:232 nt
	s_waitcnt vmcnt(0)
	v_mul_f32_e32 v87, v87, v88
.LBB0_300:
	v_or_b32_e32 v88, 60, v41
	v_mad_u64_u32 v[88:89], s[10:11], v88, s58, v[42:43]
	global_load_dword v88, v[88:89], off nt
	s_and_b64 vcc, exec, s[2:3]
	s_cbranch_vccnz .LBB0_302
	global_load_dword v89, v44, s[46:47] offset:240 nt
	s_waitcnt vmcnt(0)
	v_mul_f32_e32 v88, v88, v89
.LBB0_302:
	v_or_b32_e32 v41, 62, v41
	v_mad_u64_u32 v[42:43], s[10:11], v41, s58, v[42:43]
	global_load_dword v41, v[42:43], off nt
	s_and_b64 vcc, exec, s[2:3]
	s_cbranch_vccnz .LBB0_304
	global_load_dword v42, v44, s[46:47] offset:248 nt
	s_waitcnt vmcnt(0)
	v_mul_f32_e32 v41, v41, v42

; DI void transpose_item(const float* W, int ldn, int sc, const float* gain, bf16* WT, int K, int drow, int k0, LAS float* scr, int lane) {
;     ...
;     for (int i = 0; i < 32; ++i) { const int kk = 2 * i + (lane >> 5); tv[i] = 0.f;
;         if (sc >= 0) { tv[i] = W[(size_t)(k0 + kk) * ldn + sc + (lane & 31)]; if (gain) tv[i] *= gain[k0 + kk]; } }
; __global__ void __launch_bounds__(512, 2) fwd_megakernel(Params P) {
;     ...
;             if (r < I1) { const int g = r % 32, kb = r / 32; transpose_item(P.w_mkv, 1024, 32 * g, nullptr, Wt_mkv, 1024, 32 * g, 64 * kb, scr, lane); continue; } r -= I1;
.LBB0_306:
	s_andn2_b64 vcc, exec, s[2:3]
	s_cbranch_vccnz .LBB0_308
	s_and_b32 s1, s45, 0xfc0
	s_add_i32 s2, s1, 0xfffff700
	s_and_b32 s0, s5, 0x3e0
	v_or_b32_e32 v0, s2, v46
	s_lshl_b32 s76, s0, 2
	v_or_b32_e32 v60, 2, v0
	v_mov_b32_e32 v61, v1
	v_or_b32_e32 v62, 4, v0
	v_mov_b32_e32 v63, v1
	v_or_b32_e32 v64, 6, v0
	v_mov_b32_e32 v65, v1
	v_or_b32_e32 v66, 8, v0
	v_mov_b32_e32 v67, v1
	v_or_b32_e32 v68, 10, v0
	v_mov_b32_e32 v69, v1
	v_or_b32_e32 v70, 12, v0
	v_mov_b32_e32 v71, v1
	v_lshl_add_u64 v[42:43], v[34:35], 0, s[76:77]
	v_lshlrev_b64 v[44:45], 12, v[0:1]
	v_lshlrev_b64 v[60:61], 12, v[60:61]
	v_lshlrev_b64 v[62:63], 12, v[62:63]
	v_lshlrev_b64 v[64:65], 12, v[64:65]
	v_lshlrev_b64 v[66:67], 12, v[66:67]
	v_lshlrev_b64 v[68:69], 12, v[68:69]
	v_lshlrev_b64 v[70:71], 12, v[70:71]
	v_or_b32_e32 v72, 14, v0
	v_mov_b32_e32 v73, v1
	v_lshl_add_u64 v[44:45], v[42:43], 0, v[44:45]
	v_lshl_add_u64 v[60:61], v[42:43], 0, v[60:61]
	v_lshl_add_u64 v[62:63], v[42:43], 0, v[62:63]
	v_lshl_add_u64 v[64:65], v[42:43], 0, v[64:65]
	v_lshl_add_u64 v[66:67], v[42:43], 0, v[66:67]
	v_lshl_add_u64 v[68:69], v[42:43], 0, v[68:69]
	v_lshl_add_u64 v[70:71], v[42:43], 0, v[70:71]
	v_lshlrev_b64 v[72:73], 12, v[72:73]
	v_lshl_add_u64 v[72:73], v[42:43], 0, v[72:73]
	global_load_dword v41, v[44:45], off nt
	global_load_dword v74, v[60:61], off nt
	global_load_dword v75, v[62:63], off nt
	global_load_dword v76, v[64:65], off nt
	global_load_dword v77, v[66:67], off nt
	global_load_dword v78, v[68:69], off nt
	global_load_dword v79, v[70:71], off nt
	global_load_dword v80, v[72:73], off nt
	v_or_b32_e32 v44, 16, v0
	v_mov_b32_e32 v45, v1
	v_or_b32_e32 v60, 18, v0
	v_mov_b32_e32 v61, v1
	v_or_b32_e32 v62, 20, v0
	v_mov_b32_e32 v63, v1
	v_or_b32_e32 v64, 22, v0
	v_mov_b32_e32 v65, v1
	v_or_b32_e32 v66, 24, v0
	v_mov_b32_e32 v67, v1
	v_or_b32_e32 v68, 26, v0
	v_mov_b32_e32 v69, v1
	v_or_b32_e32 v70, 28, v0
	v_mov_b32_e32 v71, v1
	v_lshlrev_b64 v[44:45], 12, v[44:45]
	v_lshlrev_b64 v[60:61], 12, v[60:61]
	v_lshlrev_b64 v[62:63], 12, v[62:63]
	v_lshlrev_b64 v[64:65], 12, v[64:65]
	v_lshlrev_b64 v[66:67], 12, v[66:67]
	v_lshlrev_b64 v[68:69], 12, v[68:69]
	v_lshlrev_b64 v[70:71], 12, v[70:71]
	v_or_b32_e32 v72, 30, v0
	v_mov_b32_e32 v73, v1
	v_lshl_add_u64 v[44:45], v[42:43], 0, v[44:45]
	v_lshl_add_u64 v[60:61], v[42:43], 0, v[60:61]
	v_lshl_add_u64 v[62:63], v[42:43], 0, v[62:63]
	v_lshl_add_u64 v[64:65], v[42:43], 0, v[64:65]
	v_lshl_add_u64 v[66:67], v[42:43], 0, v[66:67]
	v_lshl_add_u64 v[68:69], v[42:43], 0, v[68:69]
	v_lshl_add_u64 v[70:71], v[42:43], 0, v[70:71]
	v_lshlrev_b64 v[72:73], 12, v[72:73]
	v_lshl_add_u64 v[72:73], v[42:43], 0, v[72:73]
	global_load_dword v81, v[44:45], off nt
	global_load_dword v82, v[60:61], off nt
	global_load_dword v83, v[62:63], off nt
	global_load_dword v84, v[64:65], off nt
	global_load_dword v85, v[66:67], off nt
	global_load_dword v86, v[68:69], off nt
	global_load_dword v87, v[70:71], off nt
	global_load_dword v88, v[72:73], off nt
	v_or_b32_e32 v44, 32, v0
	v_mov_b32_e32 v45, v1
	v_or_b32_e32 v60, 34, v0
	v_mov_b32_e32 v61, v1
	v_or_b32_e32 v62, 36, v0
	v_mov_b32_e32 v63, v1
	v_or_b32_e32 v64, 38, v0
	v_mov_b32_e32 v65, v1
	v_or_b32_e32 v66, 40, v0
	v_mov_b32_e32 v67, v1
	v_or_b32_e32 v68, 42, v0
	v_mov_b32_e32 v69, v1
	v_or_b32_e32 v70, 44, v0
	v_mov_b32_e32 v71, v1
	v_lshlrev_b64 v[44:45], 12, v[44:45]
	v_lshlrev_b64 v[60:61], 12, v[60:61]
	v_lshlrev_b64 v[62:63], 12, v[62:63]
	v_lshlrev_b64 v[64:65], 12, v[64:65]
	v_lshlrev_b64 v[66:67], 12, v[66:67]
	v_lshlrev_b64 v[68:69], 12, v[68:69]
	v_lshlrev_b64 v[70:71], 12, v[70:71]
	v_or_b32_e32 v72, 46, v0
	v_mov_b32_e32 v73, v1
	v_lshl_add_u64 v[44:45], v[42:43], 0, v[44:45]
	v_lshl_add_u64 v[60:61], v[42:43], 0, v[60:61]
	v_lshl_add_u64 v[62:63], v[42:43], 0, v[62:63]
	v_lshl_add_u64 v[64:65], v[42:43], 0, v[64:65]
	v_lshl_add_u64 v[66:67], v[42:43], 0, v[66:67]
	v_lshl_add_u64 v[68:69], v[42:43], 0, v[68:69]
	v_lshl_add_u64 v[70:71], v[42:43], 0, v[70:71]
	v_lshlrev_b64 v[72:73], 12, v[72:73]
	v_lshl_add_u64 v[72:73], v[42:43], 0, v[72:73]
	global_load_dword v89, v[44:45], off nt
	global_load_dword v90, v[60:61], off nt
	global_load_dword v91, v[62:63], off nt
	global_load_dword v92, v[64:65], off nt
	global_load_dword v93, v[66:67], off nt
	global_load_dword v94, v[68:69], off nt
	global_load_dword v95, v[70:71], off nt
	global_load_dword v96, v[72:73], off nt
	v_or_b32_e32 v44, 48, v0
	v_mov_b32_e32 v45, v1
	v_or_b32_e32 v60, 50, v0
	v_mov_b32_e32 v61, v1
	v_or_b32_e32 v62, 52, v0
	v_mov_b32_e32 v63, v1
	v_or_b32_e32 v64, 54, v0
	v_mov_b32_e32 v65, v1
	v_or_b32_e32 v66, 56, v0
	v_mov_b32_e32 v67, v1
	v_or_b32_e32 v68, 58, v0
	v_mov_b32_e32 v69, v1
	v_or_b32_e32 v70, 60, v0
	v_mov_b32_e32 v71, v1
	v_or_b32_e32 v0, 62, v0
	v_lshlrev_b64 v[44:45], 12, v[44:45]
	v_lshlrev_b64 v[60:61], 12, v[60:61]
	v_lshlrev_b64 v[62:63], 12, v[62:63]
	v_lshlrev_b64 v[64:65], 12, v[64:65]
	v_lshlrev_b64 v[66:67], 12, v[66:67]
	v_lshlrev_b64 v[68:69], 12, v[68:69]
	v_lshlrev_b64 v[70:71], 12, v[70:71]
	v_lshlrev_b64 v[72:73], 12, v[0:1]
	v_lshl_add_u64 v[44:45], v[42:43], 0, v[44:45]
	v_lshl_add_u64 v[60:61], v[42:43], 0, v[60:61]
	v_lshl_add_u64 v[62:63], v[42:43], 0, v[62:63]
	v_lshl_add_u64 v[64:65], v[42:43], 0, v[64:65]
	v_lshl_add_u64 v[66:67], v[42:43], 0, v[66:67]
	v_lshl_add_u64 v[68:69], v[42:43], 0, v[68:69]
	v_lshl_add_u64 v[70:71], v[42:43], 0, v[70:71]
	v_lshl_add_u64 v[42:43], v[42:43], 0, v[72:73]
	global_load_dword v0, v[44:45], off nt
	s_nop 0
	global_load_dword v44, v[60:61], off nt
	global_load_dword v45, v[62:63], off nt
	s_nop 0
	global_load_dword v60, v[64:65], off nt
	global_load_dword v61, v[66:67], off nt
	global_load_dword v62, v[68:69], off nt
	global_load_dword v63, v[70:71], off nt
	s_nop 0
	global_load_dword v42, v[42:43], off nt
	s_waitcnt vmcnt(30)
; #define LAS __attribute__((address_space(3)))
; DI unsigned pk2(float lo, float hi) { return pg8::cvt_pk_bf16(lo, hi); }
; DI void transpose_item(const float* W, int ldn, int sc, const float* gain, bf16* WT, int K, int drow, int k0, LAS float* scr, int lane) {
;     ...
;     for (int i = 0; i < 32; ++i) scr[(2 * i + (lane >> 5)) * 33 + (lane & 31)] = tv[i];
;     asm volatile("s_waitcnt lgkmcnt(0)" ::: "memory");
;     const int c = lane & 7;
; #pragma unroll
;     for (int j = 0; j < 4; ++j) { const int n = (lane >> 3) + 8 * j; const LAS float* s = scr + (8 * c) * 33 + n;
;         u32x4 o; o.x = pk2(s[0 * 33], s[1 * 33]); o.y = pk2(s[2 * 33], s[3 * 33]); o.z = pk2(s[4 * 33], s[5 * 33]); o.w = pk2(s[6 * 33], s[7 * 33]);
;         *(u32x4*)(WT + (size_t)(drow + n) * K + k0 + 8 * c) = o; }
	ds_write2_b32 v47, v41, v74 offset1:66
	s_waitcnt vmcnt(28)
	ds_write2_b32 v47, v75, v76 offset0:132 offset1:198
	s_waitcnt vmcnt(26)
	ds_write2_b32 v53, v77, v78 offset0:8 offset1:74
	s_waitcnt vmcnt(24)
	ds_write2_b32 v53, v79, v80 offset0:140 offset1:206
	s_waitcnt vmcnt(22)
	ds_write2_b32 v54, v81, v82 offset0:16 offset1:82
	s_waitcnt vmcnt(20)
	ds_write2_b32 v54, v83, v84 offset0:148 offset1:214
	s_waitcnt vmcnt(18)
	ds_write2_b32 v55, v85, v86 offset0:24 offset1:90
	s_waitcnt vmcnt(16)
	ds_write2_b32 v55, v87, v88 offset0:156 offset1:222
	s_waitcnt vmcnt(14)
	ds_write2_b32 v56, v89, v90 offset0:32 offset1:98
	s_waitcnt vmcnt(12)
	ds_write2_b32 v56, v91, v92 offset0:164 offset1:230
	s_waitcnt vmcnt(10)
	ds_write2_b32 v57, v93, v94 offset0:40 offset1:106
	s_waitcnt vmcnt(8)
	ds_write2_b32 v57, v95, v96 offset0:172 offset1:238
	s_waitcnt vmcnt(6)
	ds_write2_b32 v58, v0, v44 offset0:48 offset1:114
	s_waitcnt vmcnt(4)
	ds_write2_b32 v58, v45, v60 offset0:180 offset1:246
	s_waitcnt vmcnt(2)
	ds_write2_b32 v59, v61, v62 offset0:56 offset1:122
	s_waitcnt vmcnt(0)
	ds_write2_b32 v59, v63, v42 offset0:188 offset1:254
	s_waitcnt lgkmcnt(0)
	ds_read2_b32 v[60:61], v49 offset0:33 offset1:41
	ds_read2_b32 v[62:63], v49 offset1:8
	ds_read2_b32 v[64:65], v49 offset0:66 offset1:74
	ds_read2_b32 v[66:67], v49 offset0:99 offset1:107
	ds_read2_b32 v[68:69], v49 offset0:132 offset1:140
	ds_read2_b32 v[70:71], v49 offset0:165 offset1:173
	ds_read2_b32 v[72:73], v49 offset0:198 offset1:206
	ds_read2_b32 v[74:75], v49 offset0:231 offset1:239
	s_mov_b32 s3, s77
	v_or_b32_e32 v0, s0, v48
	v_lshl_add_u64 v[76:77], s[2:3], 1, v[36:37]
	v_lshlrev_b32_e32 v0, 11, v0
	v_lshl_add_u64 v[78:79], v[76:77], 0, v[0:1]
	s_waitcnt lgkmcnt(6)
	v_cvt_pk_bf16_f32 v42, v62, v60
	s_waitcnt lgkmcnt(4)
	v_cvt_pk_bf16_f32 v43, v64, v66
	s_waitcnt lgkmcnt(2)
	v_cvt_pk_bf16_f32 v44, v68, v70
	s_waitcnt lgkmcnt(0)
	v_cvt_pk_bf16_f32 v45, v72, v74
	global_store_dwordx4 v[78:79], v[42:45], off
	v_or_b32_e32 v0, s0, v50
	v_lshlrev_b32_e32 v0, 11, v0
	v_cvt_pk_bf16_f32 v42, v63, v61
	v_cvt_pk_bf16_f32 v43, v65, v67
	v_cvt_pk_bf16_f32 v44, v69, v71
	v_cvt_pk_bf16_f32 v45, v73, v75
	ds_read2_b32 v[62:63], v49 offset0:16 offset1:24
	ds_read2_b32 v[64:65], v49 offset0:49 offset1:57
	ds_read2_b32 v[66:67], v49 offset0:82 offset1:90
	ds_read2_b32 v[68:69], v49 offset0:115 offset1:123
	ds_read2_b32 v[70:71], v49 offset0:148 offset1:156
	ds_read2_b32 v[72:73], v49 offset0:181 offset1:189
	ds_read2_b32 v[74:75], v49 offset0:214 offset1:222
	ds_read2_b32 v[78:79], v49 offset0:247 offset1:255
	v_lshl_add_u64 v[60:61], v[76:77], 0, v[0:1]
	v_or_b32_e32 v0, s0, v51
	v_lshlrev_b32_e32 v0, 11, v0
	global_store_dwordx4 v[60:61], v[42:45], off
	v_lshl_add_u64 v[60:61], v[76:77], 0, v[0:1]
	v_or_b32_e32 v0, s0, v52
	v_lshlrev_b32_e32 v0, 11, v0
	s_waitcnt lgkmcnt(6)
	v_cvt_pk_bf16_f32 v42, v62, v64
	s_waitcnt lgkmcnt(4)
	v_cvt_pk_bf16_f32 v43, v66, v68
	s_waitcnt lgkmcnt(2)
	v_cvt_pk_bf16_f32 v44, v70, v72
	s_waitcnt lgkmcnt(0)
	v_cvt_pk_bf16_f32 v45, v74, v78
	global_store_dwordx4 v[60:61], v[42:45], off
	v_lshl_add_u64 v[60:61], v[76:77], 0, v[0:1]
	s_nop 0
	v_cvt_pk_bf16_f32 v42, v63, v65
	v_cvt_pk_bf16_f32 v43, v67, v69
	v_cvt_pk_bf16_f32 v44, v71, v73
	v_cvt_pk_bf16_f32 v45, v75, v79
	global_store_dwordx4 v[60:61], v[42:45], off
	s_waitcnt lgkmcnt(0)

; DI void transpose_item(const float* W, int ldn, int sc, const float* gain, bf16* WT, int K, int drow, int k0, LAS float* scr, int lane) {
;     ...
;     for (int i = 0; i < 32; ++i) { const int kk = 2 * i + (lane >> 5); tv[i] = 0.f;
;         if (sc >= 0) { tv[i] = W[(size_t)(k0 + kk) * ldn + sc + (lane & 31)]; if (gain) tv[i] *= gain[k0 + kk]; } }
; __global__ void __launch_bounds__(512, 2) fwd_megakernel(Params P) {
;     ...
;             if (r < I0) { const int g = r % 72, kb = r / 72; int sc;
;                 if (g < 64) sc = 32 * g; else if (g == 64) sc = 2048; else if (g == 65) sc = 2080; else if (g == 66) sc = 2176; else if (g == 67) sc = -1;
;                 else if (g == 68) sc = 2112; else if (g == 69) sc = 2144; else if (g == 70) sc = 2208; else sc = -1;
;                 transpose_item(P.w_in, 2240, sc, nullptr, Wt_in, 1024, 32 * g, 64 * kb, scr, lane); continue; } r -= I0;
.LBB0_336:
	s_lshl_b32 s12, s1, 6
	s_cmp_gt_i32 s76, -1
	s_cselect_b64 s[20:21], -1, 0
	s_cmp_lt_i32 s76, 0
	v_or_b32_e32 v0, s12, v46
	v_lshl_add_u64 v[42:43], s[76:77], 2, v[38:39]
	s_cbranch_scc1 .LBB0_398
	v_mad_i64_i32 v[44:45], s[2:3], v0, s59, v[42:43]
	global_load_dword v41, v[44:45], off nt
	v_cndmask_b32_e64 v44, 0, 1, s[20:21]
	v_cmp_ne_u32_e64 s[2:3], 1, v44
	s_andn2_b64 vcc, exec, s[20:21]
	s_cbranch_vccnz .LBB0_399
.LBB0_338:
	v_or_b32_e32 v44, 2, v0
	v_mad_i64_i32 v[44:45], s[10:11], v44, s59, v[42:43]
	global_load_dword v44, v[44:45], off nt
	v_mov_b32_e32 v45, 0
	s_and_b64 vcc, exec, s[2:3]
	v_mov_b32_e32 v60, 0
	s_cbranch_vccnz .LBB0_340
.LBB0_339:
	v_or_b32_e32 v60, 4, v0
	v_mad_i64_i32 v[60:61], s[10:11], v60, s59, v[42:43]
	global_load_dword v60, v[60:61], off nt
.LBB0_340:
	s_and_b64 vcc, exec, s[2:3]
	s_cbranch_vccnz .LBB0_342
	v_or_b32_e32 v45, 6, v0
	v_mad_i64_i32 v[62:63], s[10:11], v45, s59, v[42:43]
	global_load_dword v45, v[62:63], off nt
.LBB0_342:
	v_mov_b32_e32 v61, 0
	s_and_b64 vcc, exec, s[2:3]
	v_mov_b32_e32 v62, 0
	s_cbranch_vccnz .LBB0_344
	v_or_b32_e32 v62, 8, v0
	v_mad_i64_i32 v[62:63], s[10:11], v62, s59, v[42:43]
	global_load_dword v62, v[62:63], off nt
.LBB0_344:
	s_and_b64 vcc, exec, s[2:3]
	s_cbranch_vccnz .LBB0_346
	v_or_b32_e32 v61, 10, v0
	v_mad_i64_i32 v[64:65], s[10:11], v61, s59, v[42:43]
	global_load_dword v61, v[64:65], off nt
.LBB0_346:
	v_mov_b32_e32 v63, 0
	s_and_b64 vcc, exec, s[2:3]
	v_mov_b32_e32 v64, 0
	s_cbranch_vccnz .LBB0_348
	v_or_b32_e32 v64, 12, v0
	v_mad_i64_i32 v[64:65], s[10:11], v64, s59, v[42:43]
	global_load_dword v64, v[64:65], off nt
.LBB0_348:
	s_and_b64 vcc, exec, s[2:3]
	s_cbranch_vccnz .LBB0_350
	v_or_b32_e32 v63, 14, v0
	v_mad_i64_i32 v[66:67], s[10:11], v63, s59, v[42:43]
	global_load_dword v63, v[66:67], off nt
.LBB0_350:
	v_mov_b32_e32 v65, 0
	s_and_b64 vcc, exec, s[2:3]
	v_mov_b32_e32 v66, 0
	s_cbranch_vccnz .LBB0_352
	v_or_b32_e32 v66, 16, v0
	v_mad_i64_i32 v[66:67], s[10:11], v66, s59, v[42:43]
	global_load_dword v66, v[66:67], off nt
.LBB0_352:
	s_and_b64 vcc, exec, s[2:3]
	s_cbranch_vccnz .LBB0_354
	v_or_b32_e32 v65, 18, v0
	v_mad_i64_i32 v[68:69], s[10:11], v65, s59, v[42:43]
	global_load_dword v65, v[68:69], off nt
.LBB0_354:
	v_mov_b32_e32 v67, 0
	s_and_b64 vcc, exec, s[2:3]
	v_mov_b32_e32 v68, 0
	s_cbranch_vccnz .LBB0_356
	v_or_b32_e32 v68, 20, v0
	v_mad_i64_i32 v[68:69], s[10:11], v68, s59, v[42:43]
	global_load_dword v68, v[68:69], off nt
.LBB0_356:
	s_and_b64 vcc, exec, s[2:3]
	s_cbranch_vccnz .LBB0_358
	v_or_b32_e32 v67, 22, v0
	v_mad_i64_i32 v[70:71], s[10:11], v67, s59, v[42:43]
	global_load_dword v67, v[70:71], off nt
.LBB0_358:
	v_mov_b32_e32 v69, 0
	s_and_b64 vcc, exec, s[2:3]
	v_mov_b32_e32 v70, 0
	s_cbranch_vccnz .LBB0_360
	v_or_b32_e32 v70, 24, v0
	v_mad_i64_i32 v[70:71], s[10:11], v70, s59, v[42:43]
	global_load_dword v70, v[70:71], off nt
.LBB0_360:
	s_and_b64 vcc, exec, s[2:3]
	s_cbranch_vccnz .LBB0_362
	v_or_b32_e32 v69, 26, v0
	v_mad_i64_i32 v[72:73], s[10:11], v69, s59, v[42:43]
	global_load_dword v69, v[72:73], off nt
.LBB0_362:
	v_mov_b32_e32 v71, 0
	s_and_b64 vcc, exec, s[2:3]
	v_mov_b32_e32 v72, 0
	s_cbranch_vccnz .LBB0_364
	v_or_b32_e32 v72, 28, v0
	v_mad_i64_i32 v[72:73], s[10:11], v72, s59, v[42:43]
	global_load_dword v72, v[72:73], off nt
.LBB0_364:
	s_and_b64 vcc, exec, s[2:3]
	s_cbranch_vccnz .LBB0_366
	v_or_b32_e32 v71, 30, v0
	v_mad_i64_i32 v[74:75], s[10:11], v71, s59, v[42:43]
	global_load_dword v71, v[74:75], off nt
.LBB0_366:
	v_mov_b32_e32 v73, 0
	s_and_b64 vcc, exec, s[2:3]
	v_mov_b32_e32 v74, 0
	s_cbranch_vccnz .LBB0_368
	v_or_b32_e32 v74, 32, v0
	v_mad_i64_i32 v[74:75], s[10:11], v74, s59, v[42:43]
	global_load_dword v74, v[74:75], off nt
.LBB0_368:
	s_and_b64 vcc, exec, s[2:3]
	s_cbranch_vccnz .LBB0_370
	v_or_b32_e32 v73, 34, v0
	v_mad_i64_i32 v[76:77], s[10:11], v73, s59, v[42:43]
	global_load_dword v73, v[76:77], off nt
.LBB0_370:
	v_mov_b32_e32 v75, 0
	s_and_b64 vcc, exec, s[2:3]
	v_mov_b32_e32 v76, 0
	s_cbranch_vccnz .LBB0_372
	v_or_b32_e32 v76, 36, v0
	v_mad_i64_i32 v[76:77], s[10:11], v76, s59, v[42:43]
	global_load_dword v76, v[76:77], off nt
.LBB0_372:
	s_and_b64 vcc, exec, s[2:3]
	s_cbranch_vccnz .LBB0_374
	v_or_b32_e32 v75, 38, v0
	v_mad_i64_i32 v[78:79], s[10:11], v75, s59, v[42:43]
	global_load_dword v75, v[78:79], off nt
.LBB0_374:
	v_mov_b32_e32 v77, 0
	s_and_b64 vcc, exec, s[2:3]
	v_mov_b32_e32 v78, 0
	s_cbranch_vccnz .LBB0_376
	v_or_b32_e32 v78, 40, v0
	v_mad_i64_i32 v[78:79], s[10:11], v78, s59, v[42:43]
	global_load_dword v78, v[78:79], off nt
.LBB0_376:
	s_and_b64 vcc, exec, s[2:3]
	s_cbranch_vccnz .LBB0_378
	v_or_b32_e32 v77, 42, v0
	v_mad_i64_i32 v[80:81], s[10:11], v77, s59, v[42:43]
	global_load_dword v77, v[80:81], off nt
.LBB0_378:
	v_mov_b32_e32 v79, 0
	s_and_b64 vcc, exec, s[2:3]
	v_mov_b32_e32 v80, 0
	s_cbranch_vccnz .LBB0_380
	v_or_b32_e32 v80, 44, v0
	v_mad_i64_i32 v[80:81], s[10:11], v80, s59, v[42:43]
	global_load_dword v80, v[80:81], off nt
.LBB0_380:
	s_and_b64 vcc, exec, s[2:3]
	s_cbranch_vccnz .LBB0_382
	v_or_b32_e32 v79, 46, v0
	v_mad_i64_i32 v[82:83], s[10:11], v79, s59, v[42:43]
	global_load_dword v79, v[82:83], off nt
.LBB0_382:
	v_mov_b32_e32 v81, 0
	s_and_b64 vcc, exec, s[2:3]
	v_mov_b32_e32 v82, 0
	s_cbranch_vccnz .LBB0_384
	v_or_b32_e32 v82, 48, v0
	v_mad_i64_i32 v[82:83], s[10:11], v82, s59, v[42:43]
	global_load_dword v82, v[82:83], off nt
.LBB0_384:
	s_and_b64 vcc, exec, s[2:3]
	s_cbranch_vccnz .LBB0_386
	v_or_b32_e32 v81, 50, v0
	v_mad_i64_i32 v[84:85], s[10:11], v81, s59, v[42:43]
	global_load_dword v81, v[84:85], off nt
.LBB0_386:
	v_mov_b32_e32 v83, 0
	s_and_b64 vcc, exec, s[2:3]
	v_mov_b32_e32 v84, 0
	s_cbranch_vccnz .LBB0_388
	v_or_b32_e32 v84, 52, v0
	v_mad_i64_i32 v[84:85], s[10:11], v84, s59, v[42:43]
	global_load_dword v84, v[84:85], off nt
.LBB0_388:
	s_and_b64 vcc, exec, s[2:3]
	s_cbranch_vccnz .LBB0_390
	v_or_b32_e32 v83, 54, v0
	v_mad_i64_i32 v[86:87], s[10:11], v83, s59, v[42:43]
	global_load_dword v83, v[86:87], off nt
.LBB0_390:
	v_mov_b32_e32 v85, 0
	s_and_b64 vcc, exec, s[2:3]
	v_mov_b32_e32 v86, 0
	s_cbranch_vccnz .LBB0_392
	v_or_b32_e32 v86, 56, v0
	v_mad_i64_i32 v[86:87], s[10:11], v86, s59, v[42:43]
	global_load_dword v86, v[86:87], off nt
.LBB0_392:
	s_and_b64 vcc, exec, s[2:3]
	s_cbranch_vccnz .LBB0_394
	v_or_b32_e32 v85, 58, v0
	v_mad_i64_i32 v[88:89], s[10:11], v85, s59, v[42:43]
	global_load_dword v85, v[88:89], off nt
.LBB0_394:
	v_mov_b32_e32 v87, 0
	s_and_b64 vcc, exec, s[2:3]
	v_mov_b32_e32 v88, 0
	s_cbranch_vccnz .LBB0_396
	v_or_b32_e32 v88, 60, v0
	v_mad_i64_i32 v[88:89], s[10:11], v88, s59, v[42:43]
	global_load_dword v88, v[88:89], off nt
.LBB0_396:
	s_and_b64 vcc, exec, s[2:3]
	s_cbranch_vccnz .LBB0_21
	v_or_b32_e32 v0, 62, v0
	v_mad_i64_i32 v[42:43], s[2:3], v0, s59, v[42:43]
	global_load_dword v87, v[42:43], off nt
	s_branch .LBB0_21

; DI unsigned pk2(float lo, float hi) { return pg8::cvt_pk_bf16(lo, hi); }
; DI void norm_row2_bf16(const float* xa, const float* xb, const float* g, bf16* oa, bf16* ob, int lane) {
;     f32x4 va[4], vb[4]; float sa = 0.f, sb = 0.f;
; #pragma unroll
;     for (int j = 0; j < 4; ++j) { va[j] = *(const f32x4*)(xa + 256 * j + 4 * lane); vb[j] = *(const f32x4*)(xb + 256 * j + 4 * lane); }
; #pragma unroll
;     for (int j = 0; j < 4; ++j) { sa += (va[j][0] * va[j][0] + va[j][1] * va[j][1]) + (va[j][2] * va[j][2] + va[j][3] * va[j][3]); sb += (vb[j][0] * vb[j][0] + vb[j][1] * vb[j][1]) + (vb[j][2] * vb[j][2] + vb[j][3] * vb[j][3]); }
;     const float ra = __builtin_amdgcn_rsqf(wave_sum(sa) * (1.f / 1024.f) + EPS), rb = __builtin_amdgcn_rsqf(wave_sum(sb) * (1.f / 1024.f) + EPS);
; #pragma unroll
;     for (int j = 0; j < 4; ++j) { const f32x4 gg = *(const f32x4*)(g + 256 * j + 4 * lane);
;         u32x2 o; o.x = pk2(va[j][0] * ra * gg[0], va[j][1] * ra * gg[1]); o.y = pk2(va[j][2] * ra * gg[2], va[j][3] * ra * gg[3]); *(u32x2*)(oa + 256 * j + 4 * lane) = o;
;         u32x2 p; p.x = pk2(vb[j][0] * rb * gg[0], vb[j][1] * rb * gg[1]); p.y = pk2(vb[j][2] * rb * gg[2], vb[j][3] * rb * gg[3]); *(u32x2*)(ob + 256 * j + 4 * lane) = p; }
; }
; __global__ void __launch_bounds__(512, 2) fwd_megakernel(Params P) {
;     ...
;           for (; m + NGW < T; m += 2 * NGW) norm_row2_bf16(P.x + (size_t)m * 1024, P.x + (size_t)(m + NGW) * 1024, P.norm_mix, HB + (size_t)m * 1024, HB + (size_t)(m + NGW) * 1024, lane);
.LBB0_404:
	global_load_dwordx4 v[30:33], v[22:23], off offset:-3072 nt
	global_load_dwordx4 v[34:37], v[22:23], off offset:-2048 nt
	global_load_dwordx4 v[4:7], v[22:23], off offset:-1024 nt
	global_load_dwordx4 v[0:3], v[22:23], off nt
	s_ashr_i32 s15, s14, 31
	s_lshl_b64 s[10:11], s[14:15], 12
	v_lshl_add_u64 v[58:59], v[14:15], 0, s[10:11]
	global_load_dwordx4 v[38:41], v[16:17], off
	global_load_dwordx4 v[42:45], v[58:59], off nt
	global_load_dwordx4 v[46:49], v[58:59], off offset:1024 nt
	global_load_dwordx4 v[50:53], v[58:59], off offset:2048 nt
	global_load_dwordx4 v[54:57], v[58:59], off offset:3072 nt
	s_lshl_b64 s[14:15], s[14:15], 11
	v_lshl_add_u64 v[60:61], v[18:19], 0, s[14:15]
	s_add_i32 s1, s1, s12
	s_add_i32 s29, s29, s12
	s_add_i32 s14, s1, s28
	s_add_i32 s5, s0, s29
	v_lshl_add_u64 v[22:23], v[22:23], 0, s[6:7]
	s_cmpk_gt_i32 s5, 0x7fff
	s_waitcnt vmcnt(8)
	v_mul_f32_e32 v13, v31, v31
	v_mul_f32_e32 v58, v33, v33
	s_waitcnt vmcnt(7)
	v_mul_f32_e32 v59, v35, v35
	v_mul_f32_e32 v62, v37, v37
	s_waitcnt vmcnt(6)
	v_mul_f32_e32 v63, v5, v5
	v_mul_f32_e32 v64, v7, v7
	s_waitcnt vmcnt(5)
	v_mul_f32_e32 v65, v1, v1
	v_mul_f32_e32 v66, v3, v3
	v_fmac_f32_e32 v13, v30, v30
	v_fmac_f32_e32 v58, v32, v32
	v_fmac_f32_e32 v59, v34, v34
	v_fmac_f32_e32 v62, v36, v36
	v_fmac_f32_e32 v63, v4, v4
	v_fmac_f32_e32 v64, v6, v6
	v_fmac_f32_e32 v65, v0, v0
	v_fmac_f32_e32 v66, v2, v2
	v_add_f32_e32 v13, v13, v58
	v_add_f32_e32 v58, v59, v62
	v_add_f32_e32 v59, v63, v64
	v_add_f32_e32 v62, v65, v66
	s_waitcnt vmcnt(3)
	v_mul_f32_e32 v63, v43, v43
	v_mul_f32_e32 v64, v45, v45
	v_add_f32_e32 v13, v13, v58
	s_waitcnt vmcnt(2)
	v_mul_f32_e32 v58, v47, v47
	v_mul_f32_e32 v65, v49, v49
	s_waitcnt vmcnt(1)
	v_mul_f32_e32 v66, v51, v51
	v_mul_f32_e32 v67, v53, v53
	v_fmac_f32_e32 v63, v42, v42
	v_fmac_f32_e32 v64, v44, v44
	v_fmac_f32_e32 v58, v46, v46
	v_fmac_f32_e32 v65, v48, v48
	v_add_f32_e32 v13, v13, v59
	s_waitcnt vmcnt(0)
	v_mul_f32_e32 v68, v55, v55
	v_mul_f32_e32 v69, v57, v57
	v_fmac_f32_e32 v66, v50, v50
	v_fmac_f32_e32 v67, v52, v52
	v_add_f32_e32 v59, v63, v64
	v_add_f32_e32 v58, v58, v65
	v_add_f32_e32 v13, v13, v62
	v_fmac_f32_e32 v68, v54, v54
	v_fmac_f32_e32 v69, v56, v56
	v_add_f32_e32 v63, v66, v67
	v_add_f32_e32 v58, v59, v58
	ds_bpermute_b32 v59, v24, v13
	v_add_f32_e32 v62, v68, v69
	v_add_f32_e32 v58, v58, v63
	v_add_f32_e32 v58, v58, v62
	ds_bpermute_b32 v62, v24, v58
	s_waitcnt lgkmcnt(1)
	v_add_f32_e32 v13, v13, v59
	ds_bpermute_b32 v59, v25, v13
	s_waitcnt lgkmcnt(1)
	v_add_f32_e32 v58, v58, v62
	ds_bpermute_b32 v62, v25, v58
	s_waitcnt lgkmcnt(1)
	v_add_f32_e32 v13, v13, v59
	ds_bpermute_b32 v59, v26, v13
	s_waitcnt lgkmcnt(1)
	v_add_f32_e32 v58, v58, v62
	ds_bpermute_b32 v62, v26, v58
	s_waitcnt lgkmcnt(1)
	v_add_f32_e32 v13, v13, v59
	ds_bpermute_b32 v59, v27, v13
	s_waitcnt lgkmcnt(1)
	v_add_f32_e32 v58, v58, v62
	ds_bpermute_b32 v62, v27, v58
	s_waitcnt lgkmcnt(1)
	v_add_f32_e32 v13, v13, v59
	ds_bpermute_b32 v59, v28, v13
	s_waitcnt lgkmcnt(1)
	v_add_f32_e32 v58, v58, v62
	ds_bpermute_b32 v62, v28, v58
	s_waitcnt lgkmcnt(1)
	v_add_f32_e32 v13, v13, v59
	ds_bpermute_b32 v59, v29, v13
	s_waitcnt lgkmcnt(1)
	v_add_f32_e32 v58, v58, v62
	ds_bpermute_b32 v62, v29, v58
	s_waitcnt lgkmcnt(1)
	v_add_f32_e32 v13, v13, v59
	v_fmamk_f32 v13, v13, 0x3a800000, v11
	v_rsq_f32_e32 v13, v13
	s_waitcnt lgkmcnt(0)
	v_add_f32_e32 v58, v58, v62
	v_fmamk_f32 v58, v58, 0x3a800000, v11
	v_rsq_f32_e32 v58, v58
	v_mul_f32_e32 v30, v30, v13
	v_mul_f32_e32 v31, v31, v13
	v_mul_f32_e32 v32, v32, v13
	v_mul_f32_e32 v33, v33, v13
	v_mul_f32_e32 v30, v30, v38
	v_mul_f32_e32 v31, v31, v39
	v_mul_f32_e32 v32, v32, v40
	v_mul_f32_e32 v33, v33, v41
	v_cvt_pk_bf16_f32 v30, v30, v31
	v_cvt_pk_bf16_f32 v31, v32, v33
	global_store_dwordx2 v[20:21], v[30:31], off offset:-1024
	v_mul_f32_e32 v30, v42, v58
	v_mul_f32_e32 v31, v43, v58
	v_mul_f32_e32 v32, v44, v58
	v_mul_f32_e32 v33, v45, v58
	v_mul_f32_e32 v30, v38, v30
	v_mul_f32_e32 v31, v39, v31
	v_mul_f32_e32 v32, v40, v32
	v_mul_f32_e32 v33, v41, v33
	v_cvt_pk_bf16_f32 v30, v30, v31
	v_cvt_pk_bf16_f32 v31, v32, v33
	global_store_dwordx2 v[60:61], v[30:31], off
	global_load_dwordx4 v[30:33], v[16:17], off offset:1024
	v_mul_f32_e32 v34, v34, v13
	v_mul_f32_e32 v35, v35, v13
	v_mul_f32_e32 v36, v36, v13
	v_mul_f32_e32 v37, v37, v13
	v_mul_f32_e32 v38, v46, v58
	v_mul_f32_e32 v39, v47, v58
	v_mul_f32_e32 v41, v49, v58
	v_mul_f32_e32 v40, v48, v58
	v_mul_f32_e32 v4, v4, v13
	v_mul_f32_e32 v5, v5, v13
	v_mul_f32_e32 v6, v6, v13
	v_mul_f32_e32 v7, v7, v13
	v_mul_f32_e32 v0, v0, v13
	v_mul_f32_e32 v1, v1, v13
	v_mul_f32_e32 v2, v2, v13
	v_mul_f32_e32 v3, v3, v13
	v_mul_f32_e32 v13, v54, v58
	s_waitcnt vmcnt(0)
	v_mul_f32_e32 v34, v34, v30
	v_mul_f32_e32 v35, v35, v31
	v_mul_f32_e32 v36, v36, v32
	v_mul_f32_e32 v37, v37, v33
	v_mul_f32_e32 v38, v38, v30
	v_mul_f32_e32 v39, v39, v31
	v_mul_f32_e32 v33, v41, v33
	v_cvt_pk_bf16_f32 v30, v34, v35
	v_cvt_pk_bf16_f32 v31, v36, v37
	v_mul_f32_e32 v40, v40, v32
	v_cvt_pk_bf16_f32 v32, v38, v39
	v_cvt_pk_bf16_f32 v33, v40, v33
	global_store_dwordx2 v[20:21], v[30:31], off offset:-512
	global_store_dwordx2 v[60:61], v[32:33], off offset:512
	global_load_dwordx4 v[30:33], v[16:17], off offset:2048
	v_mul_f32_e32 v34, v50, v58
	v_mul_f32_e32 v35, v51, v58
	v_mul_f32_e32 v36, v52, v58
	v_mul_f32_e32 v37, v53, v58
	s_waitcnt vmcnt(0)
	v_mul_f32_e32 v4, v4, v30
	v_mul_f32_e32 v5, v5, v31
	v_mul_f32_e32 v6, v6, v32
	v_mul_f32_e32 v7, v7, v33
	v_cvt_pk_bf16_f32 v4, v4, v5
	v_cvt_pk_bf16_f32 v5, v6, v7
	v_mul_f32_e32 v30, v34, v30
	v_mul_f32_e32 v31, v35, v31
	v_mul_f32_e32 v32, v36, v32
	v_mul_f32_e32 v33, v37, v33
	v_cvt_pk_bf16_f32 v6, v30, v31
	v_cvt_pk_bf16_f32 v7, v32, v33
	global_store_dwordx2 v[20:21], v[4:5], off
	global_store_dwordx2 v[60:61], v[6:7], off offset:1024
	global_load_dwordx4 v[4:7], v[16:17], off offset:3072
	v_mul_f32_e32 v30, v55, v58
	v_mul_f32_e32 v31, v56, v58
	v_mul_f32_e32 v32, v57, v58
	s_waitcnt vmcnt(0)
	v_mul_f32_e32 v0, v0, v4
	v_mul_f32_e32 v1, v1, v5
	v_mul_f32_e32 v2, v2, v6
	v_mul_f32_e32 v3, v3, v7
	v_cvt_pk_bf16_f32 v0, v0, v1
	v_cvt_pk_bf16_f32 v1, v2, v3
	v_mul_f32_e32 v4, v13, v4
	v_mul_f32_e32 v5, v30, v5
	v_mul_f32_e32 v6, v31, v6
	v_mul_f32_e32 v7, v32, v7
	v_cvt_pk_bf16_f32 v2, v4, v5
	v_cvt_pk_bf16_f32 v3, v6, v7
	global_store_dwordx2 v[20:21], v[0:1], off offset:512
	global_store_dwordx2 v[60:61], v[2:3], off offset:1536
	v_lshl_add_u64 v[20:21], v[20:21], 0, s[2:3]
	s_cbranch_scc0 .LBB0_404
	s_add_i32 s2, s96, s29

; __global__ void __launch_bounds__(512, 2) fwd_megakernel(Params P) {
;     ...
;         for (int j = 0; j < 2; ++j) { const int mj = (m + j * NGW < T) ? m + j * NGW : m;
;             l[j][0] = LSE[(size_t)mj * 8 + h]; l[j][1] = LSE[(size_t)(T + mj) * 8 + h]; l[j][2] = LSE[(size_t)(2 * T + mj) * 8 + h];
;             r0[j] = *(const u32x4*)(OA + (size_t)mj * 512 + 8 * lane); r1[j] = *(const u32x4*)(OA + (size_t)(T + mj) * 512 + 8 * lane); r2[j] = *(const u32x4*)(OA + (size_t)(2 * T + mj) * 512 + 8 * lane);
;             rb_[j] = *(const u32x4*)(OB + (size_t)mj * 512 + 8 * lane); }
; #pragma unroll
;         for (int j = 0; j < 2; ++j) { const int mj = m + j * NGW;
;             const float mx = fmaxf(l[j][0], fmaxf(l[j][1], l[j][2])); float w0 = __expf(l[j][0] - mx), w1 = __expf(l[j][1] - mx), w2 = __expf(l[j][2] - mx); const float inv = 1.f / (w0 + w1 + w2); w0 *= inv; w1 *= inv; w2 *= inv;
;             float a0[8], a1[8], a2[8], ob[8], oa[8];
;             unpack8(r0[j], a0); unpack8(r1[j], a1); unpack8(r2[j], a2); unpack8(rb_[j], ob);
;             float sa = 0.f, sb = 0.f;
; #pragma unroll
;             for (int i = 0; i < 8; ++i) { oa[i] = w0 * a0[i] + w1 * a1[i] + w2 * a2[i]; sa += oa[i] * oa[i]; sb += ob[i] * ob[i]; }
;             const float ra = __builtin_amdgcn_rsqf(wave_sum(sa) * (1.f / 512.f) + EPS), rb = __builtin_amdgcn_rsqf(wave_sum(sb) * (1.f / 512.f) + EPS);
.LBB0_993:
	s_ashr_i32 s3, s2, 31
	s_lshl_b64 s[0:1], s[2:3], 5
	v_lshl_add_u64 v[20:21], v[24:25], 0, s[0:1]
	s_add_i32 s0, s2, 0x8000
	s_ashr_i32 s1, s0, 31
	s_lshl_b64 s[4:5], s[0:1], 5
	v_lshl_add_u64 v[22:23], v[24:25], 0, s[4:5]
	s_add_i32 s4, s2, 0x10000
	s_lshl_b64 s[6:7], s[2:3], 10
	s_ashr_i32 s5, s4, 31
	v_lshl_add_u64 v[16:17], v[28:29], 0, s[6:7]
	s_lshl_b64 s[10:11], s[4:5], 5
	s_lshl_b64 s[0:1], s[0:1], 10
	global_load_dwordx4 v[16:19], v[16:17], off nt
	v_lshl_add_u64 v[40:41], v[24:25], 0, s[10:11]
	global_load_dword v39, v[20:21], off nt
	global_load_dword v54, v[22:23], off nt
	global_load_dword v55, v[40:41], off nt
	v_lshl_add_u64 v[20:21], v[26:27], 0, s[0:1]
	s_lshl_b64 s[0:1], s[4:5], 10
	global_load_dwordx4 v[20:23], v[20:21], off nt
	v_lshl_add_u64 v[50:51], v[26:27], 0, s[0:1]
	v_lshl_add_u64 v[48:49], v[26:27], 0, s[6:7]
	global_load_dwordx4 v[40:43], v[50:51], off nt
	global_load_dwordx4 v[44:47], v[48:49], off nt
	s_add_i32 s4, s28, s2
	s_cmp_lt_i32 s4, 0x8000
	s_cselect_b32 s0, s4, s2
	s_ashr_i32 s1, s0, 31
	s_add_i32 s6, s0, 0x8000
	s_add_i32 s16, s0, 0x10000
	s_lshl_b64 s[10:11], s[0:1], 5
	s_ashr_i32 s7, s6, 31
	s_ashr_i32 s17, s16, 31
	s_lshl_b64 s[14:15], s[0:1], 10
	s_lshl_b64 s[0:1], s[6:7], 5
	s_lshl_b64 s[18:19], s[16:17], 5
	v_lshl_add_u64 v[48:49], v[24:25], 0, s[10:11]
	v_lshl_add_u64 v[50:51], v[24:25], 0, s[0:1]
	v_lshl_add_u64 v[52:53], v[24:25], 0, s[18:19]
	global_load_dword v56, v[48:49], off nt
	global_load_dword v57, v[50:51], off nt
	global_load_dword v58, v[52:53], off nt
	s_lshl_b64 s[10:11], s[16:17], 10
	s_waitcnt vmcnt(9)
	v_lshlrev_b32_e32 v61, 16, v18
	v_and_b32_e32 v62, 0xffff0000, v18
	s_waitcnt vmcnt(6)
	v_max3_f32 v48, v39, v54, v55
	v_sub_f32_e32 v39, v39, v48
	v_lshlrev_b32_e32 v63, 16, v19
	s_waitcnt vmcnt(5)
	v_lshlrev_b32_e32 v50, 16, v20
	v_and_b32_e32 v51, 0xffff0000, v20
	s_waitcnt vmcnt(4)
	v_lshlrev_b32_e32 v18, 16, v40
	v_and_b32_e32 v20, 0xffff0000, v40
	v_sub_f32_e32 v40, v54, v48
	v_and_b32_e32 v64, 0xffff0000, v19
	v_lshlrev_b32_e32 v65, 16, v21
	v_and_b32_e32 v66, 0xffff0000, v21
	s_waitcnt vmcnt(3)
	v_lshlrev_b32_e32 v19, 16, v44
	v_and_b32_e32 v21, 0xffff0000, v44
	v_sub_f32_e32 v44, v55, v48
	v_mul_f32_e32 v39, 0x3fb8aa3b, v39
	v_mul_f32_e32 v40, 0x3fb8aa3b, v40
	v_mul_f32_e32 v44, 0x3fb8aa3b, v44
	v_exp_f32_e32 v49, v39
	v_exp_f32_e32 v39, v40
	v_exp_f32_e32 v48, v44
	v_lshlrev_b32_e32 v67, 16, v22
	v_and_b32_e32 v68, 0xffff0000, v22
	v_add_f32_e32 v40, v49, v39
	v_add_f32_e32 v40, v48, v40
	v_div_scale_f32 v44, s[0:1], v40, v40, 1.0
	v_rcp_f32_e32 v54, v44
	v_div_scale_f32 v55, vcc, 1.0, v40, 1.0
	v_lshlrev_b32_e32 v69, 16, v23
	v_fma_f32 v72, -v44, v54, 1.0
	v_fmac_f32_e32 v54, v72, v54
	v_mul_f32_e32 v72, v55, v54
	v_fma_f32 v73, -v44, v72, v55
	v_fmac_f32_e32 v72, v73, v54
	v_fma_f32 v44, -v44, v72, v55
	v_div_fmas_f32 v44, v44, v54, v72
	v_div_fixup_f32 v40, v44, v40, 1.0
	v_pk_mul_f32 v[48:49], v[48:49], v[40:41] op_sel_hi:[1,0]
	v_mul_f32_e32 v39, v39, v40
	v_pk_mul_f32 v[18:19], v[48:49], v[18:19]
	v_pk_mul_f32 v[20:21], v[48:49], v[20:21]
	v_fma_f32 v19, v39, v50, v19
	v_add_f32_e32 v54, v18, v19
	v_and_b32_e32 v19, 0xffff0000, v45
	v_and_b32_e32 v18, 0xffff0000, v41
	v_pk_mul_f32 v[18:19], v[48:49], v[18:19]
	v_and_b32_e32 v70, 0xffff0000, v23
	v_fma_f32 v19, v39, v66, v19
	v_lshlrev_b32_e32 v22, 16, v41
	v_lshlrev_b32_e32 v23, 16, v45
	v_fma_f32 v21, v39, v51, v21
	v_add_f32_e32 v66, v18, v19
	v_lshlrev_b32_e32 v18, 16, v42
	v_lshlrev_b32_e32 v19, 16, v46
	v_and_b32_e32 v53, 0xffff0000, v16
	v_pk_mul_f32 v[22:23], v[48:49], v[22:23]
	v_add_f32_e32 v55, v20, v21
	v_pk_mul_f32 v[18:19], v[48:49], v[18:19]
	v_lshlrev_b32_e32 v52, 16, v16
	v_lshlrev_b32_e32 v59, 16, v17
	v_and_b32_e32 v60, 0xffff0000, v17
	v_mul_f32_e32 v71, v53, v53
	v_lshlrev_b32_e32 v16, 16, v43
	v_lshlrev_b32_e32 v17, 16, v47
	v_fma_f32 v23, v39, v65, v23
	v_mul_f32_e32 v20, v55, v55
	v_fma_f32 v19, v39, v67, v19
	v_fmac_f32_e32 v71, v52, v52
	v_add_f32_e32 v65, v22, v23
	v_fmac_f32_e32 v20, v54, v54
	v_add_f32_e32 v67, v18, v19
	v_and_b32_e32 v19, 0xffff0000, v46
	v_and_b32_e32 v18, 0xffff0000, v42
	v_pk_mul_f32 v[16:17], v[48:49], v[16:17]
	v_fmac_f32_e32 v71, v59, v59
	v_fmac_f32_e32 v20, v65, v65
	v_pk_mul_f32 v[18:19], v[48:49], v[18:19]
	v_fma_f32 v17, v39, v69, v17
	v_fmac_f32_e32 v71, v60, v60
	v_fmac_f32_e32 v20, v66, v66
	v_fma_f32 v19, v39, v68, v19
	v_add_f32_e32 v69, v16, v17
	v_and_b32_e32 v17, 0xffff0000, v47
	v_and_b32_e32 v16, 0xffff0000, v43
	v_fmac_f32_e32 v71, v61, v61
	v_fmac_f32_e32 v20, v67, v67
	v_add_f32_e32 v68, v18, v19
	v_pk_mul_f32 v[16:17], v[48:49], v[16:17]
	v_fmac_f32_e32 v71, v62, v62
	v_fmac_f32_e32 v20, v68, v68
	v_fma_f32 v17, v39, v70, v17
	v_fmac_f32_e32 v20, v69, v69
	v_fmac_f32_e32 v71, v63, v63
	v_add_f32_e32 v39, v16, v17
	v_fmac_f32_e32 v20, v39, v39
	v_fmac_f32_e32 v71, v64, v64
	s_lshl_b64 s[0:1], s[6:7], 10
	v_lshl_add_u64 v[40:41], v[26:27], 0, s[14:15]
	v_lshl_add_u64 v[42:43], v[26:27], 0, s[0:1]
	s_nop 1
	v_add_f32_dpp v16, v20, v20 quad_perm:[1,0,3,2] row_mask:0xf bank_mask:0xf
	s_nop 1
	v_add_f32_dpp v17, v71, v71 quad_perm:[1,0,3,2] row_mask:0xf bank_mask:0xf
	v_lshl_add_u64 v[48:49], v[26:27], 0, s[10:11]
	v_lshl_add_u64 v[50:51], v[28:29], 0, s[14:15]
	s_lshl_b64 s[6:7], s[2:3], 11
	s_nop 1
	v_add_f32_dpp v16, v16, v16 quad_perm:[2,3,0,1] row_mask:0xf bank_mask:0xf
	s_nop 1
	v_add_f32_dpp v17, v17, v17 quad_perm:[2,3,0,1] row_mask:0xf bank_mask:0xf
	s_cmpk_gt_i32 s4, 0x7fff
	s_nop 1
	v_add_f32_dpp v44, v16, v16 row_half_mirror row_mask:0xf bank_mask:0xf
	s_nop 1
	v_add_f32_dpp v46, v17, v17 row_half_mirror row_mask:0xf bank_mask:0xf
; DI unsigned pk2(float lo, float hi) { return pg8::cvt_pk_bf16(lo, hi); }
; __global__ void __launch_bounds__(512, 2) fwd_megakernel(Params P) {
;     ...
;         for (int j = 0; j < 2; ++j) { const int mj = (m + j * NGW < T) ? m + j * NGW : m;
;             l[j][0] = LSE[(size_t)mj * 8 + h]; l[j][1] = LSE[(size_t)(T + mj) * 8 + h]; l[j][2] = LSE[(size_t)(2 * T + mj) * 8 + h];
;             r0[j] = *(const u32x4*)(OA + (size_t)mj * 512 + 8 * lane); r1[j] = *(const u32x4*)(OA + (size_t)(T + mj) * 512 + 8 * lane); r2[j] = *(const u32x4*)(OA + (size_t)(2 * T + mj) * 512 + 8 * lane);
;             rb_[j] = *(const u32x4*)(OB + (size_t)mj * 512 + 8 * lane); }
; #pragma unroll
;         for (int j = 0; j < 2; ++j) { const int mj = m + j * NGW;
;             const float mx = fmaxf(l[j][0], fmaxf(l[j][1], l[j][2])); float w0 = __expf(l[j][0] - mx), w1 = __expf(l[j][1] - mx), w2 = __expf(l[j][2] - mx); const float inv = 1.f / (w0 + w1 + w2); w0 *= inv; w1 *= inv; w2 *= inv;
;             float a0[8], a1[8], a2[8], ob[8], oa[8];
;             unpack8(r0[j], a0); unpack8(r1[j], a1); unpack8(r2[j], a2); unpack8(rb_[j], ob);
;             float sa = 0.f, sb = 0.f;
; #pragma unroll
;             for (int i = 0; i < 8; ++i) { oa[i] = w0 * a0[i] + w1 * a1[i] + w2 * a2[i]; sa += oa[i] * oa[i]; sb += ob[i] * ob[i]; }
;             const float ra = __builtin_amdgcn_rsqf(wave_sum(sa) * (1.f / 512.f) + EPS), rb = __builtin_amdgcn_rsqf(wave_sum(sb) * (1.f / 512.f) + EPS);
;             u32x4 wa, wb;
;             wa.x = pk2(oa[0] * ra * ga0[0], oa[1] * ra * ga0[1]); wa.y = pk2(oa[2] * ra * ga0[2], oa[3] * ra * ga0[3]); wa.z = pk2(oa[4] * ra * ga1[0], oa[5] * ra * ga1[1]); wa.w = pk2(oa[6] * ra * ga1[2], oa[7] * ra * ga1[3]);
;             wb.x = pk2(ob[0] * rb * gb0[0], ob[1] * rb * gb0[1]); wb.y = pk2(ob[2] * rb * gb0[2], ob[3] * rb * gb0[3]); wb.z = pk2(ob[4] * rb * gb1[0], ob[5] * rb * gb1[1]); wb.w = pk2(ob[6] * rb * gb1[2], ob[7] * rb * gb1[3]);
	global_load_dwordx4 v[16:19], v[40:41], off nt
	global_load_dwordx4 v[20:23], v[42:43], off nt
	s_nop 1
	v_add_f32_dpp v40, v44, v44 row_mirror row_mask:0xf bank_mask:0xf
	s_nop 1
	v_add_f32_dpp v42, v46, v46 row_mirror row_mask:0xf bank_mask:0xf
	v_mov_b32_e32 v41, v40
	v_mov_b32_e32 v43, v42
	s_nop 1
	v_permlane16_swap_b32_e32 v41, v40
	v_add_f32_e32 v70, v40, v41
	s_nop 1
	v_permlane16_swap_b32_e32 v43, v42
	v_add_f32_e32 v72, v42, v43
	global_load_dwordx4 v[40:43], v[48:49], off nt
	global_load_dwordx4 v[44:47], v[50:51], off nt
	v_mov_b32_e32 v71, v70
	v_mov_b32_e32 v73, v72
	s_nop 1
	v_permlane32_swap_b32_e32 v71, v70
	v_add_f32_e32 v48, v70, v71
	v_fmamk_f32 v48, v48, 0x3b000000, v38
	v_rsq_f32_e32 v51, v48
	s_nop 1
	v_permlane32_swap_b32_e32 v73, v72
	v_add_f32_e32 v48, v72, v73
	v_fmamk_f32 v48, v48, 0x3b000000, v38
	v_rsq_f32_e32 v70, v48
	v_mul_f32_e32 v48, v54, v51
	v_mul_f32_e32 v49, v55, v51
	v_mul_f32_e32 v48, v4, v48
	v_mul_f32_e32 v49, v5, v49
	v_cvt_pk_bf16_f32 v48, v48, v49
	v_mul_f32_e32 v49, v65, v51
	v_mul_f32_e32 v50, v66, v51
	v_mul_f32_e32 v49, v6, v49
	v_mul_f32_e32 v50, v7, v50
	v_cvt_pk_bf16_f32 v49, v49, v50
	v_mul_f32_e32 v50, v67, v51
	v_mul_f32_e32 v54, v68, v51
	v_mul_f32_e32 v50, v12, v50
	v_mul_f32_e32 v54, v13, v54
	v_mul_f32_e32 v39, v39, v51
	v_cvt_pk_bf16_f32 v50, v50, v54
	v_mul_f32_e32 v54, v69, v51
	v_mul_f32_e32 v39, v15, v39
	v_mul_f32_e32 v54, v14, v54
	v_cvt_pk_bf16_f32 v51, v54, v39
	v_mul_f32_e32 v39, v70, v52
	v_mul_f32_e32 v52, v70, v53
	s_waitcnt vmcnt(4)
	v_max3_f32 v53, v56, v57, v58
	v_sub_f32_e32 v54, v56, v53
	v_sub_f32_e32 v55, v57, v53
	v_mul_f32_e32 v54, 0x3fb8aa3b, v54
	v_mul_f32_e32 v55, 0x3fb8aa3b, v55
	v_sub_f32_e32 v53, v58, v53
	v_exp_f32_e32 v54, v54
	v_exp_f32_e32 v55, v55
	v_mul_f32_e32 v53, 0x3fb8aa3b, v53
	v_exp_f32_e32 v56, v53
	v_mul_f32_e32 v39, v0, v39
	v_add_f32_e32 v57, v54, v55
	v_mul_f32_e32 v52, v1, v52
	v_add_f32_e32 v57, v56, v57
	v_div_scale_f32 v58, s[0:1], v57, v57, 1.0
	v_cvt_pk_bf16_f32 v52, v39, v52
	v_mul_f32_e32 v39, v70, v59
	v_rcp_f32_e32 v59, v58
	v_mul_f32_e32 v53, v70, v60
	v_mul_f32_e32 v39, v2, v39
	v_mul_f32_e32 v53, v3, v53
	v_fma_f32 v60, -v58, v59, 1.0
	v_fmac_f32_e32 v59, v60, v59
	v_div_scale_f32 v60, vcc, 1.0, v57, 1.0
	v_cvt_pk_bf16_f32 v53, v39, v53
	v_mul_f32_e32 v39, v70, v61
	v_mul_f32_e32 v61, v60, v59
	v_fma_f32 v65, -v58, v61, v60
	v_fmac_f32_e32 v61, v65, v59
	v_fma_f32 v58, -v58, v61, v60
	v_div_fmas_f32 v58, v58, v59, v61
	v_div_fixup_f32 v57, v58, v57, 1.0
	v_mul_f32_e32 v55, v55, v57
	s_waitcnt vmcnt(2)
	v_lshlrev_b32_e32 v61, 16, v20
	v_and_b32_e32 v20, 0xffff0000, v20
	v_mul_f32_e32 v54, v54, v57
	v_mul_f32_e32 v56, v56, v57
	v_lshlrev_b32_e32 v57, 16, v16
	v_and_b32_e32 v16, 0xffff0000, v16
	v_mul_f32_e32 v20, v55, v20
	v_lshlrev_b32_e32 v65, 16, v21
	v_and_b32_e32 v21, 0xffff0000, v21
	v_mul_f32_e32 v61, v55, v61
	s_waitcnt vmcnt(1)
	v_lshlrev_b32_e32 v68, 16, v40
	v_and_b32_e32 v40, 0xffff0000, v40
	v_fmac_f32_e32 v20, v54, v16
	v_lshlrev_b32_e32 v58, 16, v17
	v_and_b32_e32 v17, 0xffff0000, v17
	v_fmac_f32_e32 v61, v54, v57
	v_fmac_f32_e32 v20, v56, v40
	v_mul_f32_e32 v57, v55, v65
	v_mul_f32_e32 v21, v55, v21
	v_lshlrev_b32_e32 v66, 16, v22
	v_and_b32_e32 v22, 0xffff0000, v22
	v_lshlrev_b32_e32 v69, 16, v41
	v_and_b32_e32 v41, 0xffff0000, v41
	v_fmac_f32_e32 v61, v56, v68
	v_mul_f32_e32 v16, v20, v20
	v_fmac_f32_e32 v57, v54, v58
	v_fmac_f32_e32 v21, v54, v17
	v_lshlrev_b32_e32 v59, 16, v18
	v_and_b32_e32 v18, 0xffff0000, v18
	v_fmac_f32_e32 v16, v61, v61
	v_fmac_f32_e32 v57, v56, v69
	v_fmac_f32_e32 v21, v56, v41
	v_mul_f32_e32 v41, v55, v66
	v_mul_f32_e32 v22, v55, v22
	v_lshlrev_b32_e32 v67, 16, v23
	v_lshlrev_b32_e32 v71, 16, v42
	v_and_b32_e32 v42, 0xffff0000, v42
	v_fmac_f32_e32 v16, v57, v57
	v_fmac_f32_e32 v41, v54, v59
	v_fmac_f32_e32 v22, v54, v18
	v_lshlrev_b32_e32 v60, 16, v19
	v_and_b32_e32 v23, 0xffff0000, v23
	s_waitcnt vmcnt(0)
; DI unsigned pk2(float lo, float hi) { return pg8::cvt_pk_bf16(lo, hi); }
; __global__ void __launch_bounds__(512, 2) fwd_megakernel(Params P) {
;     ...
;             for (int i = 0; i < 8; ++i) { oa[i] = w0 * a0[i] + w1 * a1[i] + w2 * a2[i]; sa += oa[i] * oa[i]; sb += ob[i] * ob[i]; }
;             const float ra = __builtin_amdgcn_rsqf(wave_sum(sa) * (1.f / 512.f) + EPS), rb = __builtin_amdgcn_rsqf(wave_sum(sb) * (1.f / 512.f) + EPS);
;             u32x4 wa, wb;
;             wa.x = pk2(oa[0] * ra * ga0[0], oa[1] * ra * ga0[1]); wa.y = pk2(oa[2] * ra * ga0[2], oa[3] * ra * ga0[3]); wa.z = pk2(oa[4] * ra * ga1[0], oa[5] * ra * ga1[1]); wa.w = pk2(oa[6] * ra * ga1[2], oa[7] * ra * ga1[3]);
;             wb.x = pk2(ob[0] * rb * gb0[0], ob[1] * rb * gb0[1]); wb.y = pk2(ob[2] * rb * gb0[2], ob[3] * rb * gb0[3]); wb.z = pk2(ob[4] * rb * gb1[0], ob[5] * rb * gb1[1]); wb.w = pk2(ob[6] * rb * gb1[2], ob[7] * rb * gb1[3]);
;             if (mj < T) { *(u32x4*)(HB + (size_t)mj * 1024 + 8 * lane) = wa; *(u32x4*)(HB + (size_t)mj * 1024 + 512 + 8 * lane) = wb; } }
	v_lshlrev_b32_e32 v73, 16, v44
	v_and_b32_e32 v44, 0xffff0000, v44
	v_fmac_f32_e32 v16, v21, v21
	v_fmac_f32_e32 v41, v56, v71
	v_fmac_f32_e32 v22, v56, v42
	v_mul_f32_e32 v42, v55, v67
	v_and_b32_e32 v19, 0xffff0000, v19
	v_lshlrev_b32_e32 v72, 16, v43
	v_mul_f32_e32 v40, v44, v44
	v_fmac_f32_e32 v16, v41, v41
	v_fmac_f32_e32 v42, v54, v60
	v_mul_f32_e32 v23, v55, v23
	v_and_b32_e32 v43, 0xffff0000, v43
	v_lshlrev_b32_e32 v74, 16, v45
	v_fmac_f32_e32 v40, v73, v73
	v_fmac_f32_e32 v16, v22, v22
	v_fmac_f32_e32 v42, v56, v72
	v_fmac_f32_e32 v23, v54, v19
	v_and_b32_e32 v45, 0xffff0000, v45
	v_fmac_f32_e32 v40, v74, v74
	v_fmac_f32_e32 v16, v42, v42
	v_fmac_f32_e32 v23, v56, v43
	v_lshlrev_b32_e32 v75, 16, v46
	v_fmac_f32_e32 v40, v45, v45
	v_fmac_f32_e32 v16, v23, v23
	v_and_b32_e32 v46, 0xffff0000, v46
	v_fmac_f32_e32 v40, v75, v75
	v_lshlrev_b32_e32 v76, 16, v47
	v_fmac_f32_e32 v40, v46, v46
	v_and_b32_e32 v47, 0xffff0000, v47
	v_fmac_f32_e32 v40, v76, v76
	v_fmac_f32_e32 v40, v47, v47
	s_nop 1
	v_add_f32_dpp v16, v16, v16 quad_perm:[1,0,3,2] row_mask:0xf bank_mask:0xf
	v_mul_f32_e32 v39, v8, v39
	v_mul_f32_e32 v19, v70, v62
	s_nop 1
	v_add_f32_dpp v18, v40, v40 quad_perm:[1,0,3,2] row_mask:0xf bank_mask:0xf
	s_nop 1
	v_add_f32_dpp v16, v16, v16 quad_perm:[2,3,0,1] row_mask:0xf bank_mask:0xf
	v_mul_f32_e32 v19, v9, v19
	v_cvt_pk_bf16_f32 v54, v39, v19
	s_nop 1
	v_add_f32_dpp v18, v18, v18 quad_perm:[2,3,0,1] row_mask:0xf bank_mask:0xf
	s_nop 1
	v_add_f32_dpp v16, v16, v16 row_half_mirror row_mask:0xf bank_mask:0xf
	v_mul_f32_e32 v19, v70, v63
	v_mul_f32_e32 v19, v10, v19
	s_nop 1
	v_add_f32_dpp v18, v18, v18 row_half_mirror row_mask:0xf bank_mask:0xf
	s_nop 1
	v_add_f32_dpp v43, v16, v16 row_mirror row_mask:0xf bank_mask:0xf
	v_mov_b32_e32 v56, v43
	v_mul_f32_e32 v40, v70, v64
	v_mul_f32_e32 v40, v11, v40
	s_nop 1
	v_add_f32_dpp v18, v18, v18 row_mirror row_mask:0xf bank_mask:0xf
	v_cvt_pk_bf16_f32 v55, v19, v40
	v_mov_b32_e32 v19, v18
	s_nop 1
	v_permlane16_swap_b32_e32 v56, v43
	v_add_f32_e32 v39, v43, v56
	v_mov_b32_e32 v40, v39
	v_lshl_add_u64 v[16:17], v[30:31], 0, s[6:7]
	global_store_dwordx4 v[16:17], v[48:51], off
	s_nop 1
	v_permlane16_swap_b32_e32 v19, v18
	v_add_f32_e32 v18, v18, v19
	v_mov_b32_e32 v19, v18
	global_store_dwordx4 v[16:17], v[52:55], off offset:1024
	s_nop 1
	v_permlane32_swap_b32_e32 v40, v39
	v_add_f32_e32 v16, v39, v40
	v_fmamk_f32 v16, v16, 0x3b000000, v38
	v_rsq_f32_e32 v39, v16
	s_nop 1
	v_permlane32_swap_b32_e32 v19, v18
	v_add_f32_e32 v16, v18, v19
	v_fmamk_f32 v16, v16, 0x3b000000, v38
	v_rsq_f32_e32 v40, v16
	v_mul_f32_e32 v16, v61, v39
	v_mul_f32_e32 v17, v20, v39
	v_mul_f32_e32 v16, v4, v16
	v_mul_f32_e32 v17, v5, v17
	v_cvt_pk_bf16_f32 v16, v16, v17
	v_mul_f32_e32 v17, v57, v39
	v_mul_f32_e32 v18, v21, v39
	v_mul_f32_e32 v17, v6, v17
	v_mul_f32_e32 v18, v7, v18
	v_cvt_pk_bf16_f32 v17, v17, v18
	v_mul_f32_e32 v18, v41, v39
	v_mul_f32_e32 v19, v22, v39
	v_mul_f32_e32 v18, v12, v18
	v_mul_f32_e32 v19, v13, v19
	v_cvt_pk_bf16_f32 v18, v18, v19
	v_mul_f32_e32 v19, v42, v39
	v_mul_f32_e32 v20, v23, v39
	v_mul_f32_e32 v19, v14, v19
	v_mul_f32_e32 v20, v15, v20
	v_cvt_pk_bf16_f32 v19, v19, v20
	v_mul_f32_e32 v20, v40, v73
	v_mul_f32_e32 v21, v40, v44
	v_mul_f32_e32 v20, v0, v20
	v_mul_f32_e32 v21, v1, v21
	v_cvt_pk_bf16_f32 v20, v20, v21
	v_mul_f32_e32 v21, v40, v74
	v_mul_f32_e32 v22, v40, v45
	v_mul_f32_e32 v21, v2, v21
	v_mul_f32_e32 v22, v3, v22
	v_cvt_pk_bf16_f32 v21, v21, v22
	v_mul_f32_e32 v22, v40, v75
	v_mul_f32_e32 v23, v40, v46
	v_mul_f32_e32 v22, v8, v22
	v_mul_f32_e32 v23, v9, v23
	v_cvt_pk_bf16_f32 v22, v22, v23
	v_mul_f32_e32 v23, v40, v76
	v_mul_f32_e32 v23, v10, v23
	v_mul_f32_e32 v39, v40, v47
	v_mul_f32_e32 v39, v11, v39
	v_cvt_pk_bf16_f32 v23, v23, v39
	s_cbranch_scc1 .LBB0_992
	s_ashr_i32 s5, s4, 31
	s_lshl_b64 s[0:1], s[4:5], 11
	v_lshl_add_u64 v[40:41], v[30:31], 0, s[0:1]
	global_store_dwordx4 v[40:41], v[16:19], off
	global_store_dwordx4 v[40:41], v[20:23], off offset:1024
	s_branch .LBB0_992
